# M1 + s_setprio 0 moved after the closing barrier of each MFMA block (compute wave arrives one issue slot earlier)
# baseline (speedup 1.0000x reference)
; #define PG8_SB(B) __builtin_amdgcn_rcpf(1.f + expneg(B))
; #define PG8_SB(B) __builtin_amdgcn_rcpf(1.f + expneg(B))
; #define PG8_STAGE(bufoff, gbase, voff) do { _Pragma("unroll") for (int _i = 0; _i < 2; ++_i) \
;         __builtin_amdgcn_global_load_lds((const unsigned*)((const char*)(gbase) + (size_t)_i * qstep + (voff)[0]), (PG8_LAS unsigned*)(lds + (bufoff) + ldsw + _i * 8192), 16, 0, 0); } while (0)
; #define PG8_LDA(dst, b, h) do { _Pragma("unroll") for (int m = 0; m < 4; ++m) _Pragma("unroll") for (int k = 0; k < 2; ++k) dst[m][k] = *(const PG8_LAS bf16x8*)(lds + PG8_SA(b, h) + aoff + m * 2048 + k * 1024); } while (0)
; #define PG8_LDB(dst, b, h) do { _Pragma("unroll") for (int n = 0; n < 2; ++n) _Pragma("unroll") for (int k = 0; k < 2; ++k) dst[n][k] = *(const PG8_LAS bf16x8*)(lds + PG8_SB(b, h) + boff + n * 2048 + k * 1024); } while (0)
; #define PG8_MMA(ai, bj, At, Bt) do { __builtin_amdgcn_s_setprio(1); _Pragma("unroll") for (int m = 0; m < 4; ++m) _Pragma("unroll") for (int n = 0; n < 2; ++n) _Pragma("unroll") for (int k = 0; k < 2; ++k) \
;         acc[ai][bj][m][n] = __builtin_amdgcn_mfma_f32_16x16x32_bf16(Bt[n][k], At[m][k], acc[ai][bj][m][n], 0, 0, 0); __builtin_amdgcn_s_setprio(0); } while (0)
; #define PG8_WAIT_V89() do { if constexpr (SLIVER) PG8_WAIT_V(9); else PG8_WAIT_V(8); } while (0)
; #define PG8_STAGE_S(b, gbase) do { if constexpr (SLIVER) __builtin_amdgcn_global_load_lds((const unsigned*)((const char*)(gbase) + voffS), (PG8_LAS unsigned*)(lds + STAGE_BYTES + (b) * 2048 + wid * 256), 4, 0, 0); } while (0)
; #define PG8_BAR __builtin_amdgcn_s_barrier()
; template <class Epi, class Sched, bool ALIGN_EPI = false, bool SP2 = false, bool SLIVER = false>
; __device__ __forceinline__ void gemm_phase(PG8_LAS unsigned char* lds, const Gemm g, const Sched& S, const Epi& E) {
;     ...
;             PG8_LDB(B0, 0, 0); PG8_LDB(B1, 0, 1); PG8_SCHED; PG8_LDA(At, 0, 0); PG8_STAGE(PG8_SA(1, 1), a1 + hstep, voffA); PG8_STAGE_S(1, s1);
;             PG8_WAIT_V89(); PG8_WAIT_L(0); PG8_BAR; PG8_MMA(0, 0, At, B0); PG8_MMA(0, 1, At, B1); PG8_BAR; PG8_SCHED;
;             PG8_LDA(At, 0, 1); PG8_LDS_S(0); PG8_STAGE(PG8_SB(0, 0), b2, voffB); PG8_STAGE(PG8_SB(0, 1), b2 + hstep, voffB); PG8_STAGE(PG8_SA(0, 0), a2, voffA);
;             PG8_WAIT_V89(); PG8_WAIT_L(0); PG8_BAR; PG8_MMA(1, 0, At, B0); PG8_MMA(1, 1, At, B1); PG8_MMA_S(); PG8_BAR; PG8_SCHED;
.Lgin_skipw0:
	s_waitcnt lgkmcnt(0)
	s_setprio 1
	s_barrier
	v_mfma_f32_16x16x32_bf16 v[126:129], v[136:139], v[174:177], v[126:129]
	v_mfma_f32_16x16x32_bf16 v[122:125], v[150:153], v[174:177], v[122:125]
	v_mfma_f32_16x16x32_bf16 v[114:117], v[136:139], v[184:187], v[114:117]
	v_mfma_f32_16x16x32_bf16 v[106:109], v[150:153], v[184:187], v[106:109]
	v_mfma_f32_16x16x32_bf16 v[98:101], v[136:139], v[192:195], v[98:101]
	v_mfma_f32_16x16x32_bf16 v[90:93], v[150:153], v[192:195], v[90:93]
	v_mfma_f32_16x16x32_bf16 v[82:85], v[136:139], v[200:203], v[82:85]
	v_mfma_f32_16x16x32_bf16 v[74:77], v[150:153], v[200:203], v[74:77]
	v_mfma_f32_16x16x32_bf16 v[126:129], v[140:143], v[180:183], v[126:129]
	v_mfma_f32_16x16x32_bf16 v[122:125], v[154:157], v[180:183], v[122:125]
	v_mfma_f32_16x16x32_bf16 v[114:117], v[140:143], v[188:191], v[114:117]
	v_mfma_f32_16x16x32_bf16 v[106:109], v[154:157], v[188:191], v[106:109]
	v_mfma_f32_16x16x32_bf16 v[98:101], v[140:143], v[196:199], v[98:101]
	v_mfma_f32_16x16x32_bf16 v[90:93], v[154:157], v[196:199], v[90:93]
	v_mfma_f32_16x16x32_bf16 v[82:85], v[140:143], v[210:213], v[82:85]
	v_mfma_f32_16x16x32_bf16 v[74:77], v[154:157], v[210:213], v[74:77]
	s_setprio 0
	s_setprio 1
	v_mfma_f32_16x16x32_bf16 v[118:121], v[158:161], v[174:177], v[118:121]
	v_mfma_f32_16x16x32_bf16 v[110:113], v[166:169], v[174:177], v[110:113]
	v_mfma_f32_16x16x32_bf16 v[102:105], v[158:161], v[184:187], v[102:105]
	v_mfma_f32_16x16x32_bf16 v[94:97], v[166:169], v[184:187], v[94:97]
	v_mfma_f32_16x16x32_bf16 v[86:89], v[158:161], v[192:195], v[86:89]
	v_mfma_f32_16x16x32_bf16 v[78:81], v[166:169], v[192:195], v[78:81]
	v_mfma_f32_16x16x32_bf16 v[70:73], v[158:161], v[200:203], v[70:73]
	v_mfma_f32_16x16x32_bf16 v[66:69], v[166:169], v[200:203], v[66:69]
	v_mfma_f32_16x16x32_bf16 v[118:121], v[162:165], v[180:183], v[118:121]
	v_mfma_f32_16x16x32_bf16 v[110:113], v[170:173], v[180:183], v[110:113]
	v_mfma_f32_16x16x32_bf16 v[102:105], v[162:165], v[188:191], v[102:105]
	v_mfma_f32_16x16x32_bf16 v[94:97], v[170:173], v[188:191], v[94:97]
	v_mfma_f32_16x16x32_bf16 v[86:89], v[162:165], v[196:199], v[86:89]
	v_mfma_f32_16x16x32_bf16 v[78:81], v[170:173], v[196:199], v[78:81]
	v_mfma_f32_16x16x32_bf16 v[70:73], v[162:165], v[210:213], v[70:73]
	v_mfma_f32_16x16x32_bf16 v[66:69], v[170:173], v[210:213], v[66:69]
	s_barrier
	s_setprio 0
	s_add_i32 s77, s77, s53
	v_lshl_add_u64 v[146:147], s[78:79], 0, v[132:133]
	s_mov_b32 m0, s77
	ds_read_b128 v[174:177], v149 offset:16384
	ds_read_b128 v[180:183], v149 offset:17408
	ds_read_b128 v[184:187], v149 offset:18432
	ds_read_b128 v[188:191], v149 offset:19456
	ds_read_b128 v[192:195], v149 offset:20480
	ds_read_b128 v[196:199], v149 offset:21504
	ds_read_b128 v[200:203], v149 offset:22528
	ds_read_b128 v[210:213], v149 offset:23552
	global_load_lds_dwordx4 v[146:147], off
	v_lshl_add_u64 v[214:215], v[146:147], 0, s[20:21]
	s_add_i32 m0, s77, 0x2000
	s_add_i32 s77, s80, s53
	global_load_lds_dwordx4 v[214:215], off
	v_lshl_add_u64 v[214:215], v[146:147], 0, s[22:23]
	s_mov_b32 m0, s77
	s_nop 0
	global_load_lds_dwordx4 v[214:215], off
	v_lshl_add_u64 v[214:215], v[146:147], 0, s[24:25]
	s_add_i32 m0, s77, 0x2000
	s_nop 0
	global_load_lds_dwordx4 v[214:215], off
	v_lshl_add_u64 v[214:215], s[62:63], 0, v[130:131]
	s_mov_b32 m0, s91
	v_lshl_add_u64 v[216:217], v[214:215], 0, s[20:21]
	global_load_lds_dwordx4 v[214:215], off
	s_mov_b32 m0, s50
	s_nop 0
	global_load_lds_dwordx4 v[216:217], off
	s_cmp_eq_u32 s76, s101
	s_cbranch_scc1 .Lgin_skipw1
	s_waitcnt vmcnt(8)
.Lgin_skipw1:
	s_waitcnt lgkmcnt(0)
	s_setprio 1
	s_barrier
	v_mfma_f32_16x16x32_bf16 v[62:65], v[136:139], v[174:177], v[62:65]
	v_mfma_f32_16x16x32_bf16 v[58:61], v[150:153], v[174:177], v[58:61]
	v_mfma_f32_16x16x32_bf16 v[50:53], v[136:139], v[184:187], v[50:53]
	v_mfma_f32_16x16x32_bf16 v[42:45], v[150:153], v[184:187], v[42:45]
	v_mfma_f32_16x16x32_bf16 v[34:37], v[136:139], v[192:195], v[34:37]
	v_mfma_f32_16x16x32_bf16 v[26:29], v[150:153], v[192:195], v[26:29]
	v_mfma_f32_16x16x32_bf16 v[18:21], v[136:139], v[200:203], v[18:21]
	v_mfma_f32_16x16x32_bf16 v[10:13], v[150:153], v[200:203], v[10:13]
	v_mfma_f32_16x16x32_bf16 v[62:65], v[140:143], v[180:183], v[62:65]
	v_mfma_f32_16x16x32_bf16 v[58:61], v[154:157], v[180:183], v[58:61]
	v_mfma_f32_16x16x32_bf16 v[50:53], v[140:143], v[188:191], v[50:53]
	v_mfma_f32_16x16x32_bf16 v[42:45], v[154:157], v[188:191], v[42:45]
	v_mfma_f32_16x16x32_bf16 v[34:37], v[140:143], v[196:199], v[34:37]
	v_mfma_f32_16x16x32_bf16 v[26:29], v[154:157], v[196:199], v[26:29]
	v_mfma_f32_16x16x32_bf16 v[18:21], v[140:143], v[210:213], v[18:21]
	v_mfma_f32_16x16x32_bf16 v[10:13], v[154:157], v[210:213], v[10:13]
	s_setprio 0
	s_setprio 1
	v_mfma_f32_16x16x32_bf16 v[54:57], v[158:161], v[174:177], v[54:57]
	v_mfma_f32_16x16x32_bf16 v[46:49], v[166:169], v[174:177], v[46:49]
	v_mfma_f32_16x16x32_bf16 v[38:41], v[158:161], v[184:187], v[38:41]
	v_mfma_f32_16x16x32_bf16 v[30:33], v[166:169], v[184:187], v[30:33]
	v_mfma_f32_16x16x32_bf16 v[22:25], v[158:161], v[192:195], v[22:25]
	v_mfma_f32_16x16x32_bf16 v[14:17], v[166:169], v[192:195], v[14:17]
	v_mfma_f32_16x16x32_bf16 v[6:9], v[158:161], v[200:203], v[6:9]
	v_mfma_f32_16x16x32_bf16 v[2:5], v[166:169], v[200:203], v[2:5]
	v_mfma_f32_16x16x32_bf16 v[54:57], v[162:165], v[180:183], v[54:57]
	v_mfma_f32_16x16x32_bf16 v[46:49], v[170:173], v[180:183], v[46:49]
	v_mfma_f32_16x16x32_bf16 v[38:41], v[162:165], v[188:191], v[38:41]
	v_mfma_f32_16x16x32_bf16 v[30:33], v[170:173], v[188:191], v[30:33]
	v_mfma_f32_16x16x32_bf16 v[22:25], v[162:165], v[196:199], v[22:25]
	v_mfma_f32_16x16x32_bf16 v[14:17], v[170:173], v[196:199], v[14:17]
	v_mfma_f32_16x16x32_bf16 v[6:9], v[162:165], v[210:213], v[6:9]
	v_mfma_f32_16x16x32_bf16 v[2:5], v[170:173], v[210:213], v[2:5]
	s_barrier
; #define PG8_STAGE(bufoff, gbase, voff) do { _Pragma("unroll") for (int _i = 0; _i < 2; ++_i) \
;         __builtin_amdgcn_global_load_lds((const unsigned*)((const char*)(gbase) + (size_t)_i * qstep + (voff)[0]), (PG8_LAS unsigned*)(lds + (bufoff) + ldsw + _i * 8192), 16, 0, 0); } while (0)
; #define PG8_LDA(dst, b, h) do { _Pragma("unroll") for (int m = 0; m < 4; ++m) _Pragma("unroll") for (int k = 0; k < 2; ++k) dst[m][k] = *(const PG8_LAS bf16x8*)(lds + PG8_SA(b, h) + aoff + m * 2048 + k * 1024); } while (0)
; #define PG8_LDB(dst, b, h) do { _Pragma("unroll") for (int n = 0; n < 2; ++n) _Pragma("unroll") for (int k = 0; k < 2; ++k) dst[n][k] = *(const PG8_LAS bf16x8*)(lds + PG8_SB(b, h) + boff + n * 2048 + k * 1024); } while (0)
; #define PG8_MMA(ai, bj, At, Bt) do { __builtin_amdgcn_s_setprio(1); _Pragma("unroll") for (int m = 0; m < 4; ++m) _Pragma("unroll") for (int n = 0; n < 2; ++n) _Pragma("unroll") for (int k = 0; k < 2; ++k) \
;         acc[ai][bj][m][n] = __builtin_amdgcn_mfma_f32_16x16x32_bf16(Bt[n][k], At[m][k], acc[ai][bj][m][n], 0, 0, 0); __builtin_amdgcn_s_setprio(0); } while (0)
; #define PG8_WAIT_V89() do { if constexpr (SLIVER) PG8_WAIT_V(9); else PG8_WAIT_V(8); } while (0)
; #define PG8_STAGE_S(b, gbase) do { if constexpr (SLIVER) __builtin_amdgcn_global_load_lds((const unsigned*)((const char*)(gbase) + voffS), (PG8_LAS unsigned*)(lds + STAGE_BYTES + (b) * 2048 + wid * 256), 4, 0, 0); } while (0)
; #define PG8_WAIT_L(n) asm volatile("s_waitcnt lgkmcnt(" #n ")" ::: "memory")
; #define PG8_BAR __builtin_amdgcn_s_barrier()
; #define PG8_SCHED __builtin_amdgcn_sched_barrier(0)
; template <class Epi, class Sched, bool ALIGN_EPI = false, bool SP2 = false, bool SLIVER = false>
; __device__ __forceinline__ void gemm_phase(PG8_LAS unsigned char* lds, const Gemm g, const Sched& S, const Epi& E) {
;     ...
;             PG8_LDB(B0, 1, 0); PG8_LDB(B1, 1, 1); PG8_SCHED; PG8_LDA(At, 1, 0); PG8_STAGE(PG8_SA(0, 1), a2 + hstep, voffA); PG8_STAGE_S(0, s2);
;             PG8_WAIT_V89(); PG8_WAIT_L(0); PG8_BAR; PG8_MMA(0, 0, At, B0); PG8_MMA(0, 1, At, B1); PG8_BAR; PG8_SCHED;
	s_setprio 0
	s_add_i32 s62, 0, 0x18000
	v_add_u32_e32 v144, s62, v145
	s_add_i32 s63, 0, 0x1c000
	ds_read_b128 v[136:139], v144
	ds_read_b128 v[140:143], v144 offset:1024
	ds_read_b128 v[150:153], v144 offset:2048
	ds_read_b128 v[154:157], v144 offset:3072
	v_add_u32_e32 v144, s63, v145
	ds_read_b128 v[158:161], v144
	ds_read_b128 v[162:165], v144 offset:1024
	ds_read_b128 v[166:169], v144 offset:2048
	ds_read_b128 v[170:173], v144 offset:3072
	s_mov_b32 m0, s51
	v_lshl_add_u64 v[216:217], v[214:215], 0, s[22:23]
	ds_read_b128 v[174:177], v149 offset:32768
	ds_read_b128 v[180:183], v149 offset:33792
	ds_read_b128 v[184:187], v149 offset:34816
	ds_read_b128 v[188:191], v149 offset:35840
	ds_read_b128 v[192:195], v149 offset:36864
	ds_read_b128 v[196:199], v149 offset:37888
	ds_read_b128 v[200:203], v149 offset:38912
	ds_read_b128 v[210:213], v149 offset:39936
	global_load_lds_dwordx4 v[216:217], off
	v_lshl_add_u64 v[216:217], v[214:215], 0, s[24:25]
	s_mov_b32 m0, s54
	s_nop 0
	global_load_lds_dwordx4 v[216:217], off
	s_waitcnt vmcnt(8)
	s_waitcnt lgkmcnt(0)
	s_setprio 1
	s_barrier
	v_mfma_f32_16x16x32_bf16 v[126:129], v[136:139], v[174:177], v[126:129]
	v_mfma_f32_16x16x32_bf16 v[122:125], v[150:153], v[174:177], v[122:125]
	v_mfma_f32_16x16x32_bf16 v[114:117], v[136:139], v[184:187], v[114:117]
	v_mfma_f32_16x16x32_bf16 v[106:109], v[150:153], v[184:187], v[106:109]
	v_mfma_f32_16x16x32_bf16 v[98:101], v[136:139], v[192:195], v[98:101]
	v_mfma_f32_16x16x32_bf16 v[90:93], v[150:153], v[192:195], v[90:93]
	v_mfma_f32_16x16x32_bf16 v[82:85], v[136:139], v[200:203], v[82:85]
	v_mfma_f32_16x16x32_bf16 v[74:77], v[150:153], v[200:203], v[74:77]
	v_mfma_f32_16x16x32_bf16 v[126:129], v[140:143], v[180:183], v[126:129]
	v_mfma_f32_16x16x32_bf16 v[122:125], v[154:157], v[180:183], v[122:125]
	v_mfma_f32_16x16x32_bf16 v[114:117], v[140:143], v[188:191], v[114:117]
	v_mfma_f32_16x16x32_bf16 v[106:109], v[154:157], v[188:191], v[106:109]
	v_mfma_f32_16x16x32_bf16 v[98:101], v[140:143], v[196:199], v[98:101]
	v_mfma_f32_16x16x32_bf16 v[90:93], v[154:157], v[196:199], v[90:93]
	v_mfma_f32_16x16x32_bf16 v[82:85], v[140:143], v[210:213], v[82:85]
	v_mfma_f32_16x16x32_bf16 v[74:77], v[154:157], v[210:213], v[74:77]
	s_setprio 0
	s_setprio 1
	v_mfma_f32_16x16x32_bf16 v[118:121], v[158:161], v[174:177], v[118:121]
	v_mfma_f32_16x16x32_bf16 v[110:113], v[166:169], v[174:177], v[110:113]
	v_mfma_f32_16x16x32_bf16 v[102:105], v[158:161], v[184:187], v[102:105]
	v_mfma_f32_16x16x32_bf16 v[94:97], v[166:169], v[184:187], v[94:97]
	v_mfma_f32_16x16x32_bf16 v[86:89], v[158:161], v[192:195], v[86:89]
	v_mfma_f32_16x16x32_bf16 v[78:81], v[166:169], v[192:195], v[78:81]
	v_mfma_f32_16x16x32_bf16 v[70:73], v[158:161], v[200:203], v[70:73]
	v_mfma_f32_16x16x32_bf16 v[66:69], v[166:169], v[200:203], v[66:69]
	v_mfma_f32_16x16x32_bf16 v[118:121], v[162:165], v[180:183], v[118:121]
	v_mfma_f32_16x16x32_bf16 v[110:113], v[170:173], v[180:183], v[110:113]
	v_mfma_f32_16x16x32_bf16 v[102:105], v[162:165], v[188:191], v[102:105]
	v_mfma_f32_16x16x32_bf16 v[94:97], v[170:173], v[188:191], v[94:97]
	v_mfma_f32_16x16x32_bf16 v[86:89], v[162:165], v[196:199], v[86:89]
	v_mfma_f32_16x16x32_bf16 v[78:81], v[170:173], v[196:199], v[78:81]
	v_mfma_f32_16x16x32_bf16 v[70:73], v[162:165], v[210:213], v[70:73]
	v_mfma_f32_16x16x32_bf16 v[66:69], v[170:173], v[210:213], v[66:69]
	s_barrier
; #define PG8_SB(B) __builtin_amdgcn_rcpf(1.f + expneg(B))
; #define PG8_SB(B) __builtin_amdgcn_rcpf(1.f + expneg(B))
; #define PG8_STAGE(bufoff, gbase, voff) do { _Pragma("unroll") for (int _i = 0; _i < 2; ++_i) \
;         __builtin_amdgcn_global_load_lds((const unsigned*)((const char*)(gbase) + (size_t)_i * qstep + (voff)[0]), (PG8_LAS unsigned*)(lds + (bufoff) + ldsw + _i * 8192), 16, 0, 0); } while (0)
; #define PG8_LDA(dst, b, h) do { _Pragma("unroll") for (int m = 0; m < 4; ++m) _Pragma("unroll") for (int k = 0; k < 2; ++k) dst[m][k] = *(const PG8_LAS bf16x8*)(lds + PG8_SA(b, h) + aoff + m * 2048 + k * 1024); } while (0)
; #define PG8_MMA(ai, bj, At, Bt) do { __builtin_amdgcn_s_setprio(1); _Pragma("unroll") for (int m = 0; m < 4; ++m) _Pragma("unroll") for (int n = 0; n < 2; ++n) _Pragma("unroll") for (int k = 0; k < 2; ++k) \
;         acc[ai][bj][m][n] = __builtin_amdgcn_mfma_f32_16x16x32_bf16(Bt[n][k], At[m][k], acc[ai][bj][m][n], 0, 0, 0); __builtin_amdgcn_s_setprio(0); } while (0)
; #define PG8_WAIT_V89() do { if constexpr (SLIVER) PG8_WAIT_V(9); else PG8_WAIT_V(8); } while (0)
; #define PG8_LDS_S(b) do { if constexpr (SLIVER) { Sf[0] = *(const PG8_LAS bf16x8*)(lds + STAGE_BYTES + (b) * 2048 + soff0); Sf[1] = *(const PG8_LAS bf16x8*)(lds + STAGE_BYTES + (b) * 2048 + (soff0 ^ 64)); } } while (0)
; #define PG8_WAIT_L(n) asm volatile("s_waitcnt lgkmcnt(" #n ")" ::: "memory")
; #define PG8_BAR __builtin_amdgcn_s_barrier()
; #define PG8_SCHED __builtin_amdgcn_sched_barrier(0)
; template <class Epi, class Sched, bool ALIGN_EPI = false, bool SP2 = false, bool SLIVER = false>
; __device__ __forceinline__ void gemm_phase(PG8_LAS unsigned char* lds, const Gemm g, const Sched& S, const Epi& E) {
;     ...
;         for (int t = 0; t < nt; t += 2) {
;     ...
;             PG8_LDA(At, 1, 1); PG8_LDS_S(1); PG8_STAGE(PG8_SB(1, 0), b3, voffB); PG8_STAGE(PG8_SB(1, 1), b3 + hstep, voffB); PG8_STAGE(PG8_SA(1, 0), a3, voffA);
;             PG8_WAIT_V89(); PG8_WAIT_L(0); PG8_BAR; PG8_MMA(1, 0, At, B0); PG8_MMA(1, 1, At, B1); PG8_MMA_S(); PG8_BAR; PG8_SCHED;
;     ...
;         if constexpr (ALIGN_EPI) { if (wr == 0) PG8_BAR; }
	s_setprio 0
	s_add_i32 s62, s62, s53
	v_lshl_add_u64 v[216:217], v[146:147], 0, s[26:27]
	s_mov_b32 m0, s62
	ds_read_b128 v[174:177], v149 offset:49152
	ds_read_b128 v[180:183], v149 offset:50176
	ds_read_b128 v[184:187], v149 offset:51200
	ds_read_b128 v[188:191], v149 offset:52224
	ds_read_b128 v[192:195], v149 offset:53248
	ds_read_b128 v[196:199], v149 offset:54272
	ds_read_b128 v[200:203], v149 offset:55296
	ds_read_b128 v[210:213], v149 offset:56320
	global_load_lds_dwordx4 v[216:217], off
	v_lshl_add_u64 v[216:217], v[146:147], 0, s[28:29]
	s_add_i32 m0, s62, 0x2000
	s_add_i32 s62, s63, s53
	global_load_lds_dwordx4 v[216:217], off
	v_lshl_add_u64 v[216:217], v[146:147], 0, s[30:31]
	s_mov_b32 m0, s62
	v_lshl_add_u64 v[146:147], v[146:147], 0, s[34:35]
	global_load_lds_dwordx4 v[216:217], off
	s_add_i32 m0, s62, 0x2000
	s_nop 0
	global_load_lds_dwordx4 v[146:147], off
	v_lshl_add_u64 v[146:147], v[214:215], 0, s[26:27]
	s_mov_b32 m0, s10
	s_nop 0
	global_load_lds_dwordx4 v[146:147], off
	v_lshl_add_u64 v[146:147], v[214:215], 0, s[28:29]
	s_mov_b32 m0, s55
	s_nop 0
	global_load_lds_dwordx4 v[146:147], off
	s_waitcnt vmcnt(8)
	s_waitcnt lgkmcnt(0)
	s_setprio 1
	s_barrier
	v_mfma_f32_16x16x32_bf16 v[62:65], v[136:139], v[174:177], v[62:65]
	v_mfma_f32_16x16x32_bf16 v[58:61], v[150:153], v[174:177], v[58:61]
	v_mfma_f32_16x16x32_bf16 v[50:53], v[136:139], v[184:187], v[50:53]
	v_mfma_f32_16x16x32_bf16 v[42:45], v[150:153], v[184:187], v[42:45]
	v_mfma_f32_16x16x32_bf16 v[34:37], v[136:139], v[192:195], v[34:37]
	v_mfma_f32_16x16x32_bf16 v[26:29], v[150:153], v[192:195], v[26:29]
	v_mfma_f32_16x16x32_bf16 v[18:21], v[136:139], v[200:203], v[18:21]
	v_mfma_f32_16x16x32_bf16 v[10:13], v[150:153], v[200:203], v[10:13]
	v_mfma_f32_16x16x32_bf16 v[62:65], v[140:143], v[180:183], v[62:65]
	v_mfma_f32_16x16x32_bf16 v[58:61], v[154:157], v[180:183], v[58:61]
	v_mfma_f32_16x16x32_bf16 v[50:53], v[140:143], v[188:191], v[50:53]
	v_mfma_f32_16x16x32_bf16 v[42:45], v[154:157], v[188:191], v[42:45]
	v_mfma_f32_16x16x32_bf16 v[34:37], v[140:143], v[196:199], v[34:37]
	v_mfma_f32_16x16x32_bf16 v[26:29], v[154:157], v[196:199], v[26:29]
	v_mfma_f32_16x16x32_bf16 v[18:21], v[140:143], v[210:213], v[18:21]
	v_mfma_f32_16x16x32_bf16 v[10:13], v[154:157], v[210:213], v[10:13]
	s_setprio 0
	s_setprio 1
	v_mfma_f32_16x16x32_bf16 v[54:57], v[158:161], v[174:177], v[54:57]
	v_mfma_f32_16x16x32_bf16 v[46:49], v[166:169], v[174:177], v[46:49]
	v_mfma_f32_16x16x32_bf16 v[38:41], v[158:161], v[184:187], v[38:41]
	v_mfma_f32_16x16x32_bf16 v[30:33], v[166:169], v[184:187], v[30:33]
	v_mfma_f32_16x16x32_bf16 v[22:25], v[158:161], v[192:195], v[22:25]
	v_mfma_f32_16x16x32_bf16 v[14:17], v[166:169], v[192:195], v[14:17]
	v_mfma_f32_16x16x32_bf16 v[6:9], v[158:161], v[200:203], v[6:9]
	v_mfma_f32_16x16x32_bf16 v[2:5], v[166:169], v[200:203], v[2:5]
	v_mfma_f32_16x16x32_bf16 v[54:57], v[162:165], v[180:183], v[54:57]
	v_mfma_f32_16x16x32_bf16 v[46:49], v[170:173], v[180:183], v[46:49]
	v_mfma_f32_16x16x32_bf16 v[38:41], v[162:165], v[188:191], v[38:41]
	v_mfma_f32_16x16x32_bf16 v[30:33], v[170:173], v[188:191], v[30:33]
	v_mfma_f32_16x16x32_bf16 v[22:25], v[162:165], v[196:199], v[22:25]
	v_mfma_f32_16x16x32_bf16 v[14:17], v[170:173], v[196:199], v[14:17]
	v_mfma_f32_16x16x32_bf16 v[6:9], v[162:165], v[210:213], v[6:9]
	v_mfma_f32_16x16x32_bf16 v[2:5], v[170:173], v[210:213], v[2:5]
	s_barrier
	s_setprio 0
	s_add_i32 s76, s76, 2
	s_add_u32 s40, s40, 0x100
	s_addc_u32 s41, s41, 0
	s_add_u32 s68, s68, 0x100
	s_addc_u32 s69, s69, 0
	s_cmp_gt_u32 s76, 29
	s_cbranch_scc0 .LBB0_153
	s_and_b64 vcc, exec, s[48:49]
	s_cbranch_vccz .LBB0_156
	s_barrier

; #define PG8_STAGE(bufoff, gbase, voff) do { _Pragma("unroll") for (int _i = 0; _i < 2; ++_i) \
;         __builtin_amdgcn_global_load_lds((const unsigned*)((const char*)(gbase) + (size_t)_i * qstep + (voff)[0]), (PG8_LAS unsigned*)(lds + (bufoff) + ldsw + _i * 8192), 16, 0, 0); } while (0)
; #define PG8_LDA(dst, b, h) do { _Pragma("unroll") for (int m = 0; m < 4; ++m) _Pragma("unroll") for (int k = 0; k < 2; ++k) dst[m][k] = *(const PG8_LAS bf16x8*)(lds + PG8_SA(b, h) + aoff + m * 2048 + k * 1024); } while (0)
; #define PG8_LDB(dst, b, h) do { _Pragma("unroll") for (int n = 0; n < 2; ++n) _Pragma("unroll") for (int k = 0; k < 2; ++k) dst[n][k] = *(const PG8_LAS bf16x8*)(lds + PG8_SB(b, h) + boff + n * 2048 + k * 1024); } while (0)
; #define PG8_MMA(ai, bj, At, Bt) do { __builtin_amdgcn_s_setprio(1); _Pragma("unroll") for (int m = 0; m < 4; ++m) _Pragma("unroll") for (int n = 0; n < 2; ++n) _Pragma("unroll") for (int k = 0; k < 2; ++k) \
;         acc[ai][bj][m][n] = __builtin_amdgcn_mfma_f32_16x16x32_bf16(Bt[n][k], At[m][k], acc[ai][bj][m][n], 0, 0, 0); __builtin_amdgcn_s_setprio(0); } while (0)
; #define PG8_WAIT_V89() do { if constexpr (SLIVER) PG8_WAIT_V(9); else PG8_WAIT_V(8); } while (0)
; #define PG8_STAGE_S(b, gbase) do { if constexpr (SLIVER) __builtin_amdgcn_global_load_lds((const unsigned*)((const char*)(gbase) + voffS), (PG8_LAS unsigned*)(lds + STAGE_BYTES + (b) * 2048 + wid * 256), 4, 0, 0); } while (0)
; #define PG8_WAIT_L(n) asm volatile("s_waitcnt lgkmcnt(" #n ")" ::: "memory")
; #define PG8_BAR __builtin_amdgcn_s_barrier()
; #define PG8_SCHED __builtin_amdgcn_sched_barrier(0)
; template <class Epi, class Sched, bool ALIGN_EPI = false, bool SP2 = false, bool SLIVER = false>
; __device__ __forceinline__ void gemm_phase(PG8_LAS unsigned char* lds, const Gemm g, const Sched& S, const Epi& E) {
;     ...
;         for (int t = 0; t < nt; t += 2) {
;     ...
;             PG8_LDB(B0, 0, 0); PG8_LDB(B1, 0, 1); PG8_SCHED; PG8_LDA(At, 0, 0); PG8_STAGE(PG8_SA(1, 1), a1 + hstep, voffA); PG8_STAGE_S(1, s1);
;             PG8_WAIT_V89(); PG8_WAIT_L(0); PG8_BAR; PG8_MMA(0, 0, At, B0); PG8_MMA(0, 1, At, B1); PG8_BAR; PG8_SCHED;
;     ...
;         if constexpr (ALIGN_EPI) { if (wr == 0) PG8_BAR; }
.LBB0_497:
	s_add_i32 s67, s67, 2
	s_barrier
	s_setprio 0
	s_add_u32 s80, s80, 0x100
	s_addc_u32 s81, s81, 0
	s_cmp_ge_u32 s67, s3
	s_cbranch_scc1 .LBB0_508
.LBB0_498:
	s_cmp_eq_u32 s66, s80
	s_cselect_b64 s[86:87], -1, 0
	s_add_u32 s40, s16, s80
	s_addc_u32 s41, s17, s81
	s_add_u32 s68, s40, 0x100
	s_addc_u32 s69, s41, 0
	s_and_b64 s[40:41], s[86:87], exec
	s_cselect_b32 s41, s55, s69
	s_cselect_b32 s40, s54, s68
	s_add_u32 s76, s12, s80
	s_addc_u32 s77, s13, s81
	s_add_i32 s78, 0, 0x10000
	s_and_b64 s[68:69], s[86:87], exec
	v_add_u32_e32 v138, s78, v239
	s_cselect_b32 s69, s83, s77
	s_cselect_b32 s68, s82, s76
	s_add_i32 s76, 0, 0x14000
	ds_read_b128 v[146:149], v138
	ds_read_b128 v[150:153], v138 offset:1024
	ds_read_b128 v[154:157], v138 offset:2048
	ds_read_b128 v[158:161], v138 offset:3072
	v_add_u32_e32 v138, s76, v239
	ds_read_b128 v[166:169], v138
	ds_read_b128 v[170:173], v138 offset:1024
	ds_read_b128 v[174:177], v138 offset:2048
	ds_read_b128 v[162:165], v138 offset:3072
	v_lshl_add_u64 v[208:209], v[188:189], 0, s[80:81]
	v_lshl_add_u64 v[224:225], v[208:209], 0, s[34:35]
	s_add_i32 m0, s96, 0xc000
	s_mov_b64 s[88:89], 0x120080
	ds_read_b128 v[138:141], v242
	ds_read_b128 v[142:145], v242 offset:1024
	ds_read_b128 v[180:183], v242 offset:2048
	ds_read_b128 v[184:187], v242 offset:3072
	ds_read_b128 v[192:195], v242 offset:4096
	ds_read_b128 v[196:199], v242 offset:5120
	ds_read_b128 v[200:203], v242 offset:6144
	ds_read_b128 v[220:223], v242 offset:7168
	global_load_lds_dwordx4 v[224:225], off
	v_lshl_add_u64 v[208:209], v[208:209], 0, s[88:89]
	s_add_i32 m0, s96, 0xe000
	s_nop 0
	global_load_lds_dwordx4 v[208:209], off
	v_lshl_add_u64 v[208:209], v[190:191], 0, s[80:81]
	s_add_i32 m0, s94, 0x20800
	s_nop 0
	global_load_lds_dword v[208:209], off
	s_waitcnt vmcnt(9)
	s_waitcnt lgkmcnt(0)
	s_setprio 1
	s_barrier
	v_mfma_f32_16x16x32_bf16 v[134:137], v[146:149], v[138:141], v[134:137]
	v_mfma_f32_16x16x32_bf16 v[130:133], v[154:157], v[138:141], v[130:133]
	v_mfma_f32_16x16x32_bf16 v[126:129], v[146:149], v[180:183], v[126:129]
	v_mfma_f32_16x16x32_bf16 v[122:125], v[154:157], v[180:183], v[122:125]
	v_mfma_f32_16x16x32_bf16 v[118:121], v[146:149], v[192:195], v[118:121]
	v_mfma_f32_16x16x32_bf16 v[114:117], v[154:157], v[192:195], v[114:117]
	v_mfma_f32_16x16x32_bf16 v[110:113], v[146:149], v[200:203], v[110:113]
	v_mfma_f32_16x16x32_bf16 v[106:109], v[154:157], v[200:203], v[106:109]
	v_mfma_f32_16x16x32_bf16 v[134:137], v[150:153], v[142:145], v[134:137]
	v_mfma_f32_16x16x32_bf16 v[130:133], v[158:161], v[142:145], v[130:133]
	v_mfma_f32_16x16x32_bf16 v[126:129], v[150:153], v[184:187], v[126:129]
	v_mfma_f32_16x16x32_bf16 v[122:125], v[158:161], v[184:187], v[122:125]
	v_mfma_f32_16x16x32_bf16 v[118:121], v[150:153], v[196:199], v[118:121]
	v_mfma_f32_16x16x32_bf16 v[114:117], v[158:161], v[196:199], v[114:117]
	v_mfma_f32_16x16x32_bf16 v[110:113], v[150:153], v[220:223], v[110:113]
	v_mfma_f32_16x16x32_bf16 v[106:109], v[158:161], v[220:223], v[106:109]
	s_setprio 0
	s_setprio 1
	v_mfma_f32_16x16x32_bf16 v[102:105], v[166:169], v[138:141], v[102:105]
	v_mfma_f32_16x16x32_bf16 v[98:101], v[174:177], v[138:141], v[98:101]
	v_mfma_f32_16x16x32_bf16 v[90:93], v[166:169], v[180:183], v[90:93]
	v_mfma_f32_16x16x32_bf16 v[86:89], v[174:177], v[180:183], v[86:89]
	v_mfma_f32_16x16x32_bf16 v[78:81], v[166:169], v[192:195], v[78:81]
	v_mfma_f32_16x16x32_bf16 v[74:77], v[174:177], v[192:195], v[74:77]
	v_mfma_f32_16x16x32_bf16 v[70:73], v[166:169], v[200:203], v[70:73]
	v_mfma_f32_16x16x32_bf16 v[66:69], v[174:177], v[200:203], v[66:69]
	v_mfma_f32_16x16x32_bf16 v[102:105], v[170:173], v[142:145], v[102:105]
	v_mfma_f32_16x16x32_bf16 v[98:101], v[162:165], v[142:145], v[98:101]
	v_mfma_f32_16x16x32_bf16 v[90:93], v[170:173], v[184:187], v[90:93]
	v_mfma_f32_16x16x32_bf16 v[86:89], v[162:165], v[184:187], v[86:89]
	v_mfma_f32_16x16x32_bf16 v[78:81], v[170:173], v[196:199], v[78:81]
	v_mfma_f32_16x16x32_bf16 v[74:77], v[162:165], v[196:199], v[74:77]
	v_mfma_f32_16x16x32_bf16 v[70:73], v[170:173], v[220:223], v[70:73]
	v_mfma_f32_16x16x32_bf16 v[66:69], v[162:165], v[220:223], v[66:69]
	s_barrier
; #define PG8_SB(B) __builtin_amdgcn_rcpf(1.f + expneg(B))
; #define PG8_SB(B) __builtin_amdgcn_rcpf(1.f + expneg(B))
; #define PG8_STAGE(bufoff, gbase, voff) do { _Pragma("unroll") for (int _i = 0; _i < 2; ++_i) \
;         __builtin_amdgcn_global_load_lds((const unsigned*)((const char*)(gbase) + (size_t)_i * qstep + (voff)[0]), (PG8_LAS unsigned*)(lds + (bufoff) + ldsw + _i * 8192), 16, 0, 0); } while (0)
; #define PG8_LDA(dst, b, h) do { _Pragma("unroll") for (int m = 0; m < 4; ++m) _Pragma("unroll") for (int k = 0; k < 2; ++k) dst[m][k] = *(const PG8_LAS bf16x8*)(lds + PG8_SA(b, h) + aoff + m * 2048 + k * 1024); } while (0)
; #define PG8_MMA(ai, bj, At, Bt) do { __builtin_amdgcn_s_setprio(1); _Pragma("unroll") for (int m = 0; m < 4; ++m) _Pragma("unroll") for (int n = 0; n < 2; ++n) _Pragma("unroll") for (int k = 0; k < 2; ++k) \
;         acc[ai][bj][m][n] = __builtin_amdgcn_mfma_f32_16x16x32_bf16(Bt[n][k], At[m][k], acc[ai][bj][m][n], 0, 0, 0); __builtin_amdgcn_s_setprio(0); } while (0)
; #define PG8_WAIT_V89() do { if constexpr (SLIVER) PG8_WAIT_V(9); else PG8_WAIT_V(8); } while (0)
; #define PG8_LDS_S(b) do { if constexpr (SLIVER) { Sf[0] = *(const PG8_LAS bf16x8*)(lds + STAGE_BYTES + (b) * 2048 + soff0); Sf[1] = *(const PG8_LAS bf16x8*)(lds + STAGE_BYTES + (b) * 2048 + (soff0 ^ 64)); } } while (0)
; #define PG8_WAIT_L(n) asm volatile("s_waitcnt lgkmcnt(" #n ")" ::: "memory")
; #define PG8_BAR __builtin_amdgcn_s_barrier()
; #define PG8_SCHED __builtin_amdgcn_sched_barrier(0)
; template <class Epi, class Sched, bool ALIGN_EPI = false, bool SP2 = false, bool SLIVER = false>
; __device__ __forceinline__ void gemm_phase(PG8_LAS unsigned char* lds, const Gemm g, const Sched& S, const Epi& E) {
;     ...
;             PG8_LDA(At, 0, 1); PG8_LDS_S(0); PG8_STAGE(PG8_SB(0, 0), b2, voffB); PG8_STAGE(PG8_SB(0, 1), b2 + hstep, voffB); PG8_STAGE(PG8_SA(0, 0), a2, voffA);
;             PG8_WAIT_V89(); PG8_WAIT_L(0); PG8_BAR; PG8_MMA(1, 0, At, B0); PG8_MMA(1, 1, At, B1); PG8_MMA_S(); PG8_BAR; PG8_SCHED;
	s_setprio 0
	s_add_i32 s77, 0, 0x20000
	v_lshl_add_u64 v[192:193], s[68:69], 0, v[212:213]
	s_add_i32 s68, s78, s95
	v_add_u32_e32 v178, s77, v240
	v_add_u32_e32 v184, s77, v241
	s_mov_b32 m0, s68
	s_mov_b64 s[88:89], 0x60000
	ds_read_b128 v[138:141], v242 offset:16384
	ds_read_b128 v[142:145], v242 offset:17408
	ds_read_b128 v[196:199], v242 offset:18432
	ds_read_b128 v[200:203], v242 offset:19456
	ds_read_b128 v[220:223], v242 offset:20480
	ds_read_b128 v[224:227], v242 offset:21504
	ds_read_b128 v[228:231], v242 offset:22528
	ds_read_b128 v[232:235], v242 offset:23552
	ds_read_b128 v[180:183], v178
	ds_read_b128 v[184:187], v184
	global_load_lds_dwordx4 v[192:193], off
	v_lshl_add_u64 v[194:195], v[192:193], 0, s[88:89]
	s_add_i32 m0, s68, 0x2000
	s_add_i32 s68, s76, s95
	global_load_lds_dwordx4 v[194:195], off
	v_lshl_add_u64 v[194:195], v[192:193], 0, s[24:25]
	s_mov_b32 m0, s68
	s_nop 0
	global_load_lds_dwordx4 v[194:195], off
	v_lshl_add_u64 v[194:195], v[192:193], 0, s[14:15]
	s_add_i32 m0, s68, 0x2000
	s_nop 0
	global_load_lds_dwordx4 v[194:195], off
	v_lshl_add_u64 v[194:195], s[40:41], 0, v[210:211]
	s_mov_b32 m0, s96
	v_lshl_add_u64 v[208:209], v[194:195], 0, s[88:89]
	global_load_lds_dwordx4 v[194:195], off
	s_mov_b32 m0, s19
	s_nop 0
	global_load_lds_dwordx4 v[208:209], off
	s_waitcnt vmcnt(9)
	s_waitcnt lgkmcnt(0)
	s_setprio 1
	s_barrier
	v_mfma_f32_16x16x32_bf16 v[62:65], v[146:149], v[138:141], v[62:65]
	v_mfma_f32_16x16x32_bf16 v[58:61], v[154:157], v[138:141], v[58:61]
	v_mfma_f32_16x16x32_bf16 v[54:57], v[146:149], v[196:199], v[54:57]
	v_mfma_f32_16x16x32_bf16 v[50:53], v[154:157], v[196:199], v[50:53]
	v_mfma_f32_16x16x32_bf16 v[46:49], v[146:149], v[220:223], v[46:49]
	v_mfma_f32_16x16x32_bf16 v[42:45], v[154:157], v[220:223], v[42:45]
	v_mfma_f32_16x16x32_bf16 v[38:41], v[146:149], v[228:231], v[38:41]
	v_mfma_f32_16x16x32_bf16 v[34:37], v[154:157], v[228:231], v[34:37]
	v_mfma_f32_16x16x32_bf16 v[62:65], v[150:153], v[142:145], v[62:65]
	v_mfma_f32_16x16x32_bf16 v[58:61], v[158:161], v[142:145], v[58:61]
	v_mfma_f32_16x16x32_bf16 v[54:57], v[150:153], v[200:203], v[54:57]
	v_mfma_f32_16x16x32_bf16 v[50:53], v[158:161], v[200:203], v[50:53]
	v_mfma_f32_16x16x32_bf16 v[46:49], v[150:153], v[224:227], v[46:49]
	v_mfma_f32_16x16x32_bf16 v[42:45], v[158:161], v[224:227], v[42:45]
	v_mfma_f32_16x16x32_bf16 v[38:41], v[150:153], v[232:235], v[38:41]
	v_mfma_f32_16x16x32_bf16 v[34:37], v[158:161], v[232:235], v[34:37]
	s_setprio 0
	s_setprio 1
	v_mfma_f32_16x16x32_bf16 v[30:33], v[166:169], v[138:141], v[30:33]
	v_mfma_f32_16x16x32_bf16 v[26:29], v[174:177], v[138:141], v[26:29]
	v_mfma_f32_16x16x32_bf16 v[22:25], v[166:169], v[196:199], v[22:25]
	v_mfma_f32_16x16x32_bf16 v[18:21], v[174:177], v[196:199], v[18:21]
	v_mfma_f32_16x16x32_bf16 v[14:17], v[166:169], v[220:223], v[14:17]
	v_mfma_f32_16x16x32_bf16 v[10:13], v[174:177], v[220:223], v[10:13]
	v_mfma_f32_16x16x32_bf16 v[6:9], v[166:169], v[228:231], v[6:9]
	v_mfma_f32_16x16x32_bf16 v[2:5], v[174:177], v[228:231], v[2:5]
	v_mfma_f32_16x16x32_bf16 v[30:33], v[170:173], v[142:145], v[30:33]
	v_mfma_f32_16x16x32_bf16 v[26:29], v[162:165], v[142:145], v[26:29]
	v_mfma_f32_16x16x32_bf16 v[22:25], v[170:173], v[200:203], v[22:25]
	v_mfma_f32_16x16x32_bf16 v[18:21], v[162:165], v[200:203], v[18:21]
	v_mfma_f32_16x16x32_bf16 v[14:17], v[170:173], v[224:227], v[14:17]
	v_mfma_f32_16x16x32_bf16 v[10:13], v[162:165], v[224:227], v[10:13]
	v_mfma_f32_16x16x32_bf16 v[6:9], v[170:173], v[232:235], v[6:9]
	v_mfma_f32_16x16x32_bf16 v[2:5], v[162:165], v[232:235], v[2:5]
	s_setprio 0
	s_setprio 1
	v_cndmask_b32_e64 v138, 0, 1, s[52:53]
	v_cmp_ne_u32_e64 s[40:41], 1, v138
	s_andn2_b64 vcc, exec, s[52:53]
	s_mov_b64 s[88:89], -1
	s_cbranch_vccnz .LBB0_500
	v_mfma_f32_16x16x32_bf16 v[138:141], v[166:169], v[180:183], v[82:85]
	s_mov_b64 s[88:89], 0
	v_mfma_f32_16x16x32_bf16 v[142:145], v[174:177], v[180:183], v[94:97]
	v_mfma_f32_16x16x32_bf16 v[138:141], v[170:173], v[184:187], v[138:141]
	v_mfma_f32_16x16x32_bf16 v[142:145], v[162:165], v[184:187], v[142:145]

; #define PG8_STAGE(bufoff, gbase, voff) do { _Pragma("unroll") for (int _i = 0; _i < 2; ++_i) \
;         __builtin_amdgcn_global_load_lds((const unsigned*)((const char*)(gbase) + (size_t)_i * qstep + (voff)[0]), (PG8_LAS unsigned*)(lds + (bufoff) + ldsw + _i * 8192), 16, 0, 0); } while (0)
; #define PG8_LDA(dst, b, h) do { _Pragma("unroll") for (int m = 0; m < 4; ++m) _Pragma("unroll") for (int k = 0; k < 2; ++k) dst[m][k] = *(const PG8_LAS bf16x8*)(lds + PG8_SA(b, h) + aoff + m * 2048 + k * 1024); } while (0)
; #define PG8_LDB(dst, b, h) do { _Pragma("unroll") for (int n = 0; n < 2; ++n) _Pragma("unroll") for (int k = 0; k < 2; ++k) dst[n][k] = *(const PG8_LAS bf16x8*)(lds + PG8_SB(b, h) + boff + n * 2048 + k * 1024); } while (0)
; #define PG8_MMA(ai, bj, At, Bt) do { __builtin_amdgcn_s_setprio(1); _Pragma("unroll") for (int m = 0; m < 4; ++m) _Pragma("unroll") for (int n = 0; n < 2; ++n) _Pragma("unroll") for (int k = 0; k < 2; ++k) \
;         acc[ai][bj][m][n] = __builtin_amdgcn_mfma_f32_16x16x32_bf16(Bt[n][k], At[m][k], acc[ai][bj][m][n], 0, 0, 0); __builtin_amdgcn_s_setprio(0); } while (0)
; #define PG8_WAIT_V89() do { if constexpr (SLIVER) PG8_WAIT_V(9); else PG8_WAIT_V(8); } while (0)
; #define PG8_STAGE_S(b, gbase) do { if constexpr (SLIVER) __builtin_amdgcn_global_load_lds((const unsigned*)((const char*)(gbase) + voffS), (PG8_LAS unsigned*)(lds + STAGE_BYTES + (b) * 2048 + wid * 256), 4, 0, 0); } while (0)
; #define PG8_WAIT_L(n) asm volatile("s_waitcnt lgkmcnt(" #n ")" ::: "memory")
; #define PG8_BAR __builtin_amdgcn_s_barrier()
; #define PG8_SCHED __builtin_amdgcn_sched_barrier(0)
; template <class Epi, class Sched, bool ALIGN_EPI = false, bool SP2 = false, bool SLIVER = false>
; __device__ __forceinline__ void gemm_phase(PG8_LAS unsigned char* lds, const Gemm g, const Sched& S, const Epi& E) {
;     ...
;             PG8_LDB(B0, 1, 0); PG8_LDB(B1, 1, 1); PG8_SCHED; PG8_LDA(At, 1, 0); PG8_STAGE(PG8_SA(0, 1), a2 + hstep, voffA); PG8_STAGE_S(0, s2);
;             PG8_WAIT_V89(); PG8_WAIT_L(0); PG8_BAR; PG8_MMA(0, 0, At, B0); PG8_MMA(0, 1, At, B1); PG8_BAR; PG8_SCHED;
.LBB0_502:
	s_add_u32 s68, s62, s80
	s_addc_u32 s69, s63, s81
	s_add_u32 s76, s68, 0x100
	s_addc_u32 s77, s69, 0
	s_and_b64 s[68:69], s[86:87], exec
	s_cselect_b32 s69, s85, s77
	s_cselect_b32 s68, s84, s76
	s_barrier
	s_setprio 0
	s_add_i32 s76, 0, 0x18000
	v_add_u32_e32 v82, s76, v239
	s_add_i32 s77, 0, 0x1c000
	ds_read_b128 v[146:149], v82
	ds_read_b128 v[150:153], v82 offset:1024
	ds_read_b128 v[154:157], v82 offset:2048
	ds_read_b128 v[158:161], v82 offset:3072
	v_add_u32_e32 v82, s77, v239
	ds_read_b128 v[166:169], v82
	ds_read_b128 v[170:173], v82 offset:1024
	ds_read_b128 v[174:177], v82 offset:2048
	ds_read_b128 v[162:165], v82 offset:3072
	s_mov_b32 m0, s91
	v_lshl_add_u64 v[208:209], v[194:195], 0, s[24:25]
	ds_read_b128 v[82:85], v242 offset:32768
	ds_read_b128 v[94:97], v242 offset:33792
	ds_read_b128 v[180:183], v242 offset:34816
	ds_read_b128 v[184:187], v242 offset:35840
	ds_read_b128 v[196:199], v242 offset:36864
	ds_read_b128 v[200:203], v242 offset:37888
	ds_read_b128 v[220:223], v242 offset:38912
	ds_read_b128 v[224:227], v242 offset:39936
	global_load_lds_dwordx4 v[208:209], off
	v_lshl_add_u64 v[208:209], v[194:195], 0, s[14:15]
	s_mov_b32 m0, s92
	s_nop 0
	global_load_lds_dwordx4 v[208:209], off
	v_lshl_add_u64 v[208:209], s[68:69], 0, v[214:215]
	s_mov_b32 m0, s93
	s_nop 0
	global_load_lds_dword v[208:209], off
	s_waitcnt vmcnt(9)
	s_waitcnt lgkmcnt(0)
	s_setprio 1
	s_barrier
	v_mfma_f32_16x16x32_bf16 v[134:137], v[146:149], v[82:85], v[134:137]
	v_mfma_f32_16x16x32_bf16 v[130:133], v[154:157], v[82:85], v[130:133]
	v_mfma_f32_16x16x32_bf16 v[126:129], v[146:149], v[180:183], v[126:129]
	v_mfma_f32_16x16x32_bf16 v[122:125], v[154:157], v[180:183], v[122:125]
	v_mfma_f32_16x16x32_bf16 v[118:121], v[146:149], v[196:199], v[118:121]
	v_mfma_f32_16x16x32_bf16 v[114:117], v[154:157], v[196:199], v[114:117]
	v_mfma_f32_16x16x32_bf16 v[110:113], v[146:149], v[220:223], v[110:113]
	v_mfma_f32_16x16x32_bf16 v[106:109], v[154:157], v[220:223], v[106:109]
	v_mfma_f32_16x16x32_bf16 v[134:137], v[150:153], v[94:97], v[134:137]
	v_mfma_f32_16x16x32_bf16 v[130:133], v[158:161], v[94:97], v[130:133]
	v_mfma_f32_16x16x32_bf16 v[126:129], v[150:153], v[184:187], v[126:129]
	v_mfma_f32_16x16x32_bf16 v[122:125], v[158:161], v[184:187], v[122:125]
	v_mfma_f32_16x16x32_bf16 v[118:121], v[150:153], v[200:203], v[118:121]
	v_mfma_f32_16x16x32_bf16 v[114:117], v[158:161], v[200:203], v[114:117]
	v_mfma_f32_16x16x32_bf16 v[110:113], v[150:153], v[224:227], v[110:113]
	v_mfma_f32_16x16x32_bf16 v[106:109], v[158:161], v[224:227], v[106:109]
	s_setprio 0
	s_setprio 1
	v_mfma_f32_16x16x32_bf16 v[102:105], v[166:169], v[82:85], v[102:105]
	v_mfma_f32_16x16x32_bf16 v[82:85], v[174:177], v[82:85], v[98:101]
	v_mfma_f32_16x16x32_bf16 v[98:101], v[162:165], v[94:97], v[82:85]
	v_mfma_f32_16x16x32_bf16 v[82:85], v[166:169], v[180:183], v[90:93]
	v_mfma_f32_16x16x32_bf16 v[90:93], v[170:173], v[184:187], v[82:85]
	v_mfma_f32_16x16x32_bf16 v[82:85], v[174:177], v[180:183], v[86:89]
	v_mfma_f32_16x16x32_bf16 v[78:81], v[166:169], v[196:199], v[78:81]
	v_mfma_f32_16x16x32_bf16 v[74:77], v[174:177], v[196:199], v[74:77]
	v_mfma_f32_16x16x32_bf16 v[70:73], v[166:169], v[220:223], v[70:73]
	v_mfma_f32_16x16x32_bf16 v[66:69], v[174:177], v[220:223], v[66:69]
	v_mfma_f32_16x16x32_bf16 v[102:105], v[170:173], v[94:97], v[102:105]
	v_mfma_f32_16x16x32_bf16 v[86:89], v[162:165], v[184:187], v[82:85]
	v_mfma_f32_16x16x32_bf16 v[78:81], v[170:173], v[200:203], v[78:81]
	v_mfma_f32_16x16x32_bf16 v[74:77], v[162:165], v[200:203], v[74:77]
	v_mfma_f32_16x16x32_bf16 v[70:73], v[170:173], v[224:227], v[70:73]
	v_mfma_f32_16x16x32_bf16 v[66:69], v[162:165], v[224:227], v[66:69]
	s_barrier
; #define PG8_SB(B) __builtin_amdgcn_rcpf(1.f + expneg(B))
; #define PG8_SB(B) __builtin_amdgcn_rcpf(1.f + expneg(B))
; #define PG8_STAGE(bufoff, gbase, voff) do { _Pragma("unroll") for (int _i = 0; _i < 2; ++_i) \
;         __builtin_amdgcn_global_load_lds((const unsigned*)((const char*)(gbase) + (size_t)_i * qstep + (voff)[0]), (PG8_LAS unsigned*)(lds + (bufoff) + ldsw + _i * 8192), 16, 0, 0); } while (0)
; #define PG8_LDA(dst, b, h) do { _Pragma("unroll") for (int m = 0; m < 4; ++m) _Pragma("unroll") for (int k = 0; k < 2; ++k) dst[m][k] = *(const PG8_LAS bf16x8*)(lds + PG8_SA(b, h) + aoff + m * 2048 + k * 1024); } while (0)
; #define PG8_MMA(ai, bj, At, Bt) do { __builtin_amdgcn_s_setprio(1); _Pragma("unroll") for (int m = 0; m < 4; ++m) _Pragma("unroll") for (int n = 0; n < 2; ++n) _Pragma("unroll") for (int k = 0; k < 2; ++k) \
;         acc[ai][bj][m][n] = __builtin_amdgcn_mfma_f32_16x16x32_bf16(Bt[n][k], At[m][k], acc[ai][bj][m][n], 0, 0, 0); __builtin_amdgcn_s_setprio(0); } while (0)
; #define PG8_WAIT_V89() do { if constexpr (SLIVER) PG8_WAIT_V(9); else PG8_WAIT_V(8); } while (0)
; #define PG8_LDS_S(b) do { if constexpr (SLIVER) { Sf[0] = *(const PG8_LAS bf16x8*)(lds + STAGE_BYTES + (b) * 2048 + soff0); Sf[1] = *(const PG8_LAS bf16x8*)(lds + STAGE_BYTES + (b) * 2048 + (soff0 ^ 64)); } } while (0)
; #define PG8_WAIT_L(n) asm volatile("s_waitcnt lgkmcnt(" #n ")" ::: "memory")
; #define PG8_BAR __builtin_amdgcn_s_barrier()
; #define PG8_SCHED __builtin_amdgcn_sched_barrier(0)
; template <class Epi, class Sched, bool ALIGN_EPI = false, bool SP2 = false, bool SLIVER = false>
; __device__ __forceinline__ void gemm_phase(PG8_LAS unsigned char* lds, const Gemm g, const Sched& S, const Epi& E) {
;     ...
;             PG8_LDA(At, 1, 1); PG8_LDS_S(1); PG8_STAGE(PG8_SB(1, 0), b3, voffB); PG8_STAGE(PG8_SB(1, 1), b3 + hstep, voffB); PG8_STAGE(PG8_SA(1, 0), a3, voffA);
;             PG8_WAIT_V89(); PG8_WAIT_L(0); PG8_BAR; PG8_MMA(1, 0, At, B0); PG8_MMA(1, 1, At, B1); PG8_MMA_S(); PG8_BAR; PG8_SCHED;
	s_setprio 0
	s_add_i32 s68, 0, 0x20800
	v_add_u32_e32 v178, s68, v240
	v_add_u32_e32 v184, s68, v241
	s_add_i32 s68, s76, s95
	v_lshl_add_u64 v[208:209], v[192:193], 0, s[26:27]
	s_mov_b32 m0, s68
	ds_read_b128 v[82:85], v242 offset:49152
	ds_read_b128 v[94:97], v242 offset:50176
	ds_read_b128 v[196:199], v242 offset:51200
	ds_read_b128 v[200:203], v242 offset:52224
	ds_read_b128 v[220:223], v242 offset:53248
	ds_read_b128 v[224:227], v242 offset:54272
	ds_read_b128 v[228:231], v242 offset:55296
	ds_read_b128 v[232:235], v242 offset:56320
	ds_read_b128 v[180:183], v178
	ds_read_b128 v[184:187], v184
	global_load_lds_dwordx4 v[208:209], off
	v_lshl_add_u64 v[208:209], v[192:193], 0, s[72:73]
	s_add_i32 m0, s68, 0x2000
	s_add_i32 s68, s77, s95
	global_load_lds_dwordx4 v[208:209], off
	v_lshl_add_u64 v[208:209], v[192:193], 0, s[34:35]
	s_mov_b32 m0, s68
	s_mov_b64 s[76:77], 0x120080
	global_load_lds_dwordx4 v[208:209], off
	v_lshl_add_u64 v[192:193], v[192:193], 0, s[76:77]
	s_add_i32 m0, s68, 0x2000
	s_nop 0
	global_load_lds_dwordx4 v[192:193], off
	v_lshl_add_u64 v[192:193], v[194:195], 0, s[26:27]
	s_mov_b32 m0, s97
	s_nop 0
	global_load_lds_dwordx4 v[192:193], off
	v_lshl_add_u64 v[192:193], v[194:195], 0, s[72:73]
	s_mov_b32 m0, s18
	s_nop 0
	global_load_lds_dwordx4 v[192:193], off
	s_waitcnt vmcnt(9)
	s_waitcnt lgkmcnt(0)
	s_setprio 1
	s_barrier
	v_mfma_f32_16x16x32_bf16 v[62:65], v[146:149], v[82:85], v[62:65]
	v_mfma_f32_16x16x32_bf16 v[58:61], v[154:157], v[82:85], v[58:61]
	v_mfma_f32_16x16x32_bf16 v[54:57], v[146:149], v[196:199], v[54:57]
	v_mfma_f32_16x16x32_bf16 v[50:53], v[154:157], v[196:199], v[50:53]
	v_mfma_f32_16x16x32_bf16 v[46:49], v[146:149], v[220:223], v[46:49]
	v_mfma_f32_16x16x32_bf16 v[42:45], v[154:157], v[220:223], v[42:45]
	v_mfma_f32_16x16x32_bf16 v[38:41], v[146:149], v[228:231], v[38:41]
	v_mfma_f32_16x16x32_bf16 v[34:37], v[154:157], v[228:231], v[34:37]
	v_mfma_f32_16x16x32_bf16 v[62:65], v[150:153], v[94:97], v[62:65]
	v_mfma_f32_16x16x32_bf16 v[58:61], v[158:161], v[94:97], v[58:61]
	v_mfma_f32_16x16x32_bf16 v[54:57], v[150:153], v[200:203], v[54:57]
	v_mfma_f32_16x16x32_bf16 v[50:53], v[158:161], v[200:203], v[50:53]
	v_mfma_f32_16x16x32_bf16 v[46:49], v[150:153], v[224:227], v[46:49]
	v_mfma_f32_16x16x32_bf16 v[42:45], v[158:161], v[224:227], v[42:45]
	v_mfma_f32_16x16x32_bf16 v[38:41], v[150:153], v[232:235], v[38:41]
	v_mfma_f32_16x16x32_bf16 v[34:37], v[158:161], v[232:235], v[34:37]
	s_setprio 0
	s_setprio 1
	v_mfma_f32_16x16x32_bf16 v[30:33], v[166:169], v[82:85], v[30:33]
	v_mfma_f32_16x16x32_bf16 v[26:29], v[174:177], v[82:85], v[26:29]
	v_mfma_f32_16x16x32_bf16 v[22:25], v[166:169], v[196:199], v[22:25]
	v_mfma_f32_16x16x32_bf16 v[18:21], v[174:177], v[196:199], v[18:21]
	v_mfma_f32_16x16x32_bf16 v[14:17], v[166:169], v[220:223], v[14:17]
	v_mfma_f32_16x16x32_bf16 v[10:13], v[174:177], v[220:223], v[10:13]
	v_mfma_f32_16x16x32_bf16 v[6:9], v[166:169], v[228:231], v[6:9]
	v_mfma_f32_16x16x32_bf16 v[2:5], v[174:177], v[228:231], v[2:5]
	v_mfma_f32_16x16x32_bf16 v[30:33], v[170:173], v[94:97], v[30:33]
	v_mfma_f32_16x16x32_bf16 v[26:29], v[162:165], v[94:97], v[26:29]
	v_mfma_f32_16x16x32_bf16 v[22:25], v[170:173], v[200:203], v[22:25]
	v_mfma_f32_16x16x32_bf16 v[18:21], v[162:165], v[200:203], v[18:21]
	v_mfma_f32_16x16x32_bf16 v[14:17], v[170:173], v[224:227], v[14:17]
	v_mfma_f32_16x16x32_bf16 v[10:13], v[162:165], v[224:227], v[10:13]
	v_mfma_f32_16x16x32_bf16 v[6:9], v[170:173], v[232:235], v[6:9]
	v_mfma_f32_16x16x32_bf16 v[2:5], v[162:165], v[232:235], v[2:5]
	s_setprio 0
	s_setprio 1
	s_and_b64 vcc, exec, s[40:41]
	s_mov_b64 s[40:41], -1
	s_mov_b64 s[86:87], 0x4000400
	s_mov_b64 s[88:89], 0x4000800
	s_cbranch_vccnz .LBB0_504
	v_mfma_f32_16x16x32_bf16 v[82:85], v[166:169], v[180:183], v[138:141]
	s_mov_b64 s[40:41], 0
	v_mfma_f32_16x16x32_bf16 v[94:97], v[174:177], v[180:183], v[142:145]
	v_mfma_f32_16x16x32_bf16 v[82:85], v[170:173], v[184:187], v[82:85]
	v_mfma_f32_16x16x32_bf16 v[94:97], v[162:165], v[184:187], v[94:97]

; #define PG8_STAGE(bufoff, gbase, voff) do { _Pragma("unroll") for (int _i = 0; _i < 2; ++_i) \
;         __builtin_amdgcn_global_load_lds((const unsigned*)((const char*)(gbase) + (size_t)_i * qstep + (voff)[0]), (PG8_LAS unsigned*)(lds + (bufoff) + ldsw + _i * 8192), 16, 0, 0); } while (0)
; #define PG8_LDA(dst, b, h) do { _Pragma("unroll") for (int m = 0; m < 4; ++m) _Pragma("unroll") for (int k = 0; k < 2; ++k) dst[m][k] = *(const PG8_LAS bf16x8*)(lds + PG8_SA(b, h) + aoff + m * 2048 + k * 1024); } while (0)
; #define PG8_LDB(dst, b, h) do { _Pragma("unroll") for (int n = 0; n < 2; ++n) _Pragma("unroll") for (int k = 0; k < 2; ++k) dst[n][k] = *(const PG8_LAS bf16x8*)(lds + PG8_SB(b, h) + boff + n * 2048 + k * 1024); } while (0)
; #define PG8_MMA(ai, bj, At, Bt) do { __builtin_amdgcn_s_setprio(1); _Pragma("unroll") for (int m = 0; m < 4; ++m) _Pragma("unroll") for (int n = 0; n < 2; ++n) _Pragma("unroll") for (int k = 0; k < 2; ++k) \
;         acc[ai][bj][m][n] = __builtin_amdgcn_mfma_f32_16x16x32_bf16(Bt[n][k], At[m][k], acc[ai][bj][m][n], 0, 0, 0); __builtin_amdgcn_s_setprio(0); } while (0)
; #define PG8_WAIT_V89() do { if constexpr (SLIVER) PG8_WAIT_V(9); else PG8_WAIT_V(8); } while (0)
; #define PG8_WAIT_L(n) asm volatile("s_waitcnt lgkmcnt(" #n ")" ::: "memory")
; #define PG8_BAR __builtin_amdgcn_s_barrier()
; template <class Epi, class Sched, bool ALIGN_EPI = false, bool SP2 = false, bool SLIVER = false>
; __device__ __forceinline__ void gemm_phase(PG8_LAS unsigned char* lds, const Gemm g, const Sched& S, const Epi& E) {
;     ...
;         for (int t = 0; t < nt; t += 2) {
;             const bool last = (t == nt - 2);
;             const char* a1 = cA + (size_t)(t + 1) * kstep;
;             const char* a2 = last ? nA : cA + (size_t)(t + 2) * kstep; const char* b2 = last ? nB : cB + (size_t)(t + 2) * kstep;
;             const char* a3 = a2 + kstep; const char* b3 = b2 + kstep;
;             const char* s1 = cS + (size_t)(t + 1) * kstep; const char* s2 = last ? nS : cS + (size_t)(t + 2) * kstep;
;             if (last && has_next) S.a_ready(nxt);
;             if constexpr (SP2) {
;             PG8_LDB(B0, 0, 0); PG8_LDB(B1, 0, 1); PG8_SCHED; PG8_LDA(At, 0, 0); PG8_STAGE(PG8_SA(1, 1), a1 + hstep, voffA); PG8_STAGE_S(1, s1);
;             PG8_WAIT_V89(); PG8_WAIT_L(0); PG8_BAR; PG8_MMA(0, 0, At, B0); PG8_MMA(0, 1, At, B1); PG8_BAR; PG8_SCHED;
.LBB0_597:
	s_barrier
	s_setprio 0
	s_add_i32 s76, s76, 2
	s_add_u32 s62, s62, 0x100
	s_addc_u32 s63, s63, 0
	s_cmp_gt_u32 s76, 29
	s_cbranch_scc1 .LBB0_606
.LBB0_598:
	s_add_u32 s40, s92, s62
	s_addc_u32 s41, s93, s63
	s_add_u32 s77, s40, 0x100
	s_addc_u32 s78, s41, 0
	s_add_u32 s83, s68, s62
	s_addc_u32 s79, s69, s63
	s_add_i32 s96, 0, 0x10000
	s_cmpk_eq_i32 s62, 0xf00
	s_cselect_b64 s[80:81], -1, 0
	s_and_b64 s[40:41], s[80:81], exec
	s_cselect_b32 s41, s12, s78
	s_cselect_b32 s40, s13, s77
	v_add_u32_e32 v138, s96, v212
	s_cselect_b32 s79, s17, s79
	s_cselect_b32 s78, s55, s83
	s_add_i32 s77, 0, 0x14000
	ds_read_b128 v[146:149], v138
	ds_read_b128 v[150:153], v138 offset:1024
	ds_read_b128 v[154:157], v138 offset:2048
	ds_read_b128 v[158:161], v138 offset:3072
	v_add_u32_e32 v138, s77, v212
	ds_read_b128 v[166:169], v138
	ds_read_b128 v[170:173], v138 offset:1024
	ds_read_b128 v[174:177], v138 offset:2048
	ds_read_b128 v[162:165], v138 offset:3072
	v_lshl_add_u64 v[202:203], v[200:201], 0, s[62:63]
	v_lshl_add_u64 v[208:209], v[202:203], 0, s[30:31]
	s_add_i32 m0, s85, 0xc000
	ds_read_b128 v[138:141], v215
	ds_read_b128 v[142:145], v215 offset:1024
	ds_read_b128 v[180:183], v215 offset:2048
	ds_read_b128 v[184:187], v215 offset:3072
	ds_read_b128 v[216:219], v215 offset:4096
	ds_read_b128 v[220:223], v215 offset:5120
	ds_read_b128 v[224:227], v215 offset:6144
	ds_read_b128 v[228:231], v215 offset:7168
	global_load_lds_dwordx4 v[208:209], off
	v_lshl_add_u64 v[202:203], v[202:203], 0, s[34:35]
	s_add_i32 m0, s85, 0xe000
	s_nop 0
	global_load_lds_dwordx4 v[202:203], off
	v_lshl_add_u64 v[202:203], v[198:199], 0, s[62:63]
	s_add_i32 m0, s45, 0x20800
	s_nop 0
	global_load_lds_dword v[202:203], off
	s_waitcnt vmcnt(9)
	s_waitcnt lgkmcnt(0)
	s_setprio 1
	s_barrier
	v_mfma_f32_16x16x32_bf16 v[134:137], v[146:149], v[138:141], v[134:137]
	v_mfma_f32_16x16x32_bf16 v[130:133], v[154:157], v[138:141], v[130:133]
	v_mfma_f32_16x16x32_bf16 v[118:121], v[146:149], v[180:183], v[118:121]
	v_mfma_f32_16x16x32_bf16 v[114:117], v[154:157], v[180:183], v[114:117]
	v_mfma_f32_16x16x32_bf16 v[102:105], v[146:149], v[216:219], v[102:105]
	v_mfma_f32_16x16x32_bf16 v[98:101], v[154:157], v[216:219], v[98:101]
	v_mfma_f32_16x16x32_bf16 v[86:89], v[146:149], v[224:227], v[86:89]
	v_mfma_f32_16x16x32_bf16 v[82:85], v[154:157], v[224:227], v[82:85]
	v_mfma_f32_16x16x32_bf16 v[134:137], v[150:153], v[142:145], v[134:137]
	v_mfma_f32_16x16x32_bf16 v[130:133], v[158:161], v[142:145], v[130:133]
	v_mfma_f32_16x16x32_bf16 v[118:121], v[150:153], v[184:187], v[118:121]
	v_mfma_f32_16x16x32_bf16 v[114:117], v[158:161], v[184:187], v[114:117]
	v_mfma_f32_16x16x32_bf16 v[102:105], v[150:153], v[220:223], v[102:105]
	v_mfma_f32_16x16x32_bf16 v[98:101], v[158:161], v[220:223], v[98:101]
	v_mfma_f32_16x16x32_bf16 v[86:89], v[150:153], v[228:231], v[86:89]
	v_mfma_f32_16x16x32_bf16 v[82:85], v[158:161], v[228:231], v[82:85]
	s_setprio 0
	s_setprio 1
	v_mfma_f32_16x16x32_bf16 v[126:129], v[166:169], v[138:141], v[126:129]
	v_mfma_f32_16x16x32_bf16 v[122:125], v[174:177], v[138:141], v[122:125]
	v_mfma_f32_16x16x32_bf16 v[110:113], v[166:169], v[180:183], v[110:113]
	v_mfma_f32_16x16x32_bf16 v[106:109], v[174:177], v[180:183], v[106:109]
	v_mfma_f32_16x16x32_bf16 v[94:97], v[166:169], v[216:219], v[94:97]
	v_mfma_f32_16x16x32_bf16 v[90:93], v[174:177], v[216:219], v[90:93]
	v_mfma_f32_16x16x32_bf16 v[78:81], v[166:169], v[224:227], v[78:81]
	v_mfma_f32_16x16x32_bf16 v[74:77], v[174:177], v[224:227], v[74:77]
	v_mfma_f32_16x16x32_bf16 v[126:129], v[170:173], v[142:145], v[126:129]
	v_mfma_f32_16x16x32_bf16 v[122:125], v[162:165], v[142:145], v[122:125]
	v_mfma_f32_16x16x32_bf16 v[110:113], v[170:173], v[184:187], v[110:113]
	v_mfma_f32_16x16x32_bf16 v[106:109], v[162:165], v[184:187], v[106:109]
	v_mfma_f32_16x16x32_bf16 v[94:97], v[170:173], v[220:223], v[94:97]
	v_mfma_f32_16x16x32_bf16 v[90:93], v[162:165], v[220:223], v[90:93]
	v_mfma_f32_16x16x32_bf16 v[78:81], v[170:173], v[228:231], v[78:81]
	v_mfma_f32_16x16x32_bf16 v[74:77], v[162:165], v[228:231], v[74:77]
	s_barrier
; #define PG8_SB(B) __builtin_amdgcn_rcpf(1.f + expneg(B))
; #define PG8_SB(B) __builtin_amdgcn_rcpf(1.f + expneg(B))
; #define PG8_STAGE(bufoff, gbase, voff) do { _Pragma("unroll") for (int _i = 0; _i < 2; ++_i) \
;         __builtin_amdgcn_global_load_lds((const unsigned*)((const char*)(gbase) + (size_t)_i * qstep + (voff)[0]), (PG8_LAS unsigned*)(lds + (bufoff) + ldsw + _i * 8192), 16, 0, 0); } while (0)
; #define PG8_LDA(dst, b, h) do { _Pragma("unroll") for (int m = 0; m < 4; ++m) _Pragma("unroll") for (int k = 0; k < 2; ++k) dst[m][k] = *(const PG8_LAS bf16x8*)(lds + PG8_SA(b, h) + aoff + m * 2048 + k * 1024); } while (0)
; #define PG8_MMA(ai, bj, At, Bt) do { __builtin_amdgcn_s_setprio(1); _Pragma("unroll") for (int m = 0; m < 4; ++m) _Pragma("unroll") for (int n = 0; n < 2; ++n) _Pragma("unroll") for (int k = 0; k < 2; ++k) \
;         acc[ai][bj][m][n] = __builtin_amdgcn_mfma_f32_16x16x32_bf16(Bt[n][k], At[m][k], acc[ai][bj][m][n], 0, 0, 0); __builtin_amdgcn_s_setprio(0); } while (0)
; #define PG8_WAIT_V89() do { if constexpr (SLIVER) PG8_WAIT_V(9); else PG8_WAIT_V(8); } while (0)
; #define PG8_LDS_S(b) do { if constexpr (SLIVER) { Sf[0] = *(const PG8_LAS bf16x8*)(lds + STAGE_BYTES + (b) * 2048 + soff0); Sf[1] = *(const PG8_LAS bf16x8*)(lds + STAGE_BYTES + (b) * 2048 + (soff0 ^ 64)); } } while (0)
; #define PG8_WAIT_L(n) asm volatile("s_waitcnt lgkmcnt(" #n ")" ::: "memory")
; #define PG8_BAR __builtin_amdgcn_s_barrier()
; #define PG8_SCHED __builtin_amdgcn_sched_barrier(0)
; template <class Epi, class Sched, bool ALIGN_EPI = false, bool SP2 = false, bool SLIVER = false>
; __device__ __forceinline__ void gemm_phase(PG8_LAS unsigned char* lds, const Gemm g, const Sched& S, const Epi& E) {
;     ...
;             PG8_WAIT_V89(); PG8_WAIT_L(0); PG8_BAR; PG8_MMA(0, 0, At, B0); PG8_MMA(0, 1, At, B1); PG8_BAR; PG8_SCHED;
;             PG8_LDA(At, 0, 1); PG8_LDS_S(0); PG8_STAGE(PG8_SB(0, 0), b2, voffB); PG8_STAGE(PG8_SB(0, 1), b2 + hstep, voffB); PG8_STAGE(PG8_SA(0, 0), a2, voffA);
;             PG8_WAIT_V89(); PG8_WAIT_L(0); PG8_BAR; PG8_MMA(1, 0, At, B0); PG8_MMA(1, 1, At, B1); PG8_MMA_S(); PG8_BAR; PG8_SCHED;
	s_setprio 0
	s_add_i32 s83, 0, 0x20000
	v_lshl_add_u64 v[202:203], s[78:79], 0, v[190:191]
	s_add_i32 s78, s96, s18
	v_add_u32_e32 v178, s83, v213
	v_add_u32_e32 v184, s83, v214
	s_mov_b32 m0, s78
	ds_read_b128 v[138:141], v215 offset:16384
	ds_read_b128 v[142:145], v215 offset:17408
	ds_read_b128 v[216:219], v215 offset:18432
	ds_read_b128 v[220:223], v215 offset:19456
	ds_read_b128 v[224:227], v215 offset:20480
	ds_read_b128 v[228:231], v215 offset:21504
	ds_read_b128 v[232:235], v215 offset:22528
	ds_read_b128 v[240:243], v215 offset:23552
	ds_read_b128 v[180:183], v178
	ds_read_b128 v[184:187], v184
	global_load_lds_dwordx4 v[202:203], off
	v_lshl_add_u64 v[208:209], v[202:203], 0, s[20:21]
	s_add_i32 m0, s78, 0x2000
	s_add_i32 s77, s77, s18
	global_load_lds_dwordx4 v[208:209], off
	v_lshl_add_u64 v[208:209], v[202:203], 0, s[22:23]
	s_mov_b32 m0, s77
	v_lshl_add_u64 v[210:211], s[40:41], 0, v[188:189]
	global_load_lds_dwordx4 v[208:209], off
	v_lshl_add_u64 v[208:209], v[202:203], 0, s[24:25]
	s_add_i32 m0, s77, 0x2000
	s_nop 0
	global_load_lds_dwordx4 v[208:209], off
	s_mov_b32 m0, s85
	v_lshl_add_u64 v[208:209], v[210:211], 0, s[20:21]
	global_load_lds_dwordx4 v[210:211], off
	s_mov_b32 m0, s19
	s_nop 0
	global_load_lds_dwordx4 v[208:209], off
	s_waitcnt vmcnt(9)
	s_waitcnt lgkmcnt(0)
	s_setprio 1
	s_barrier
	v_mfma_f32_16x16x32_bf16 v[70:73], v[146:149], v[138:141], v[70:73]
	v_mfma_f32_16x16x32_bf16 v[66:69], v[154:157], v[138:141], v[66:69]
	v_mfma_f32_16x16x32_bf16 v[54:57], v[146:149], v[216:219], v[54:57]
	v_mfma_f32_16x16x32_bf16 v[50:53], v[154:157], v[216:219], v[50:53]
	v_mfma_f32_16x16x32_bf16 v[38:41], v[146:149], v[224:227], v[38:41]
	v_mfma_f32_16x16x32_bf16 v[34:37], v[154:157], v[224:227], v[34:37]
	v_mfma_f32_16x16x32_bf16 v[22:25], v[146:149], v[232:235], v[22:25]
	v_mfma_f32_16x16x32_bf16 v[18:21], v[154:157], v[232:235], v[18:21]
	v_mfma_f32_16x16x32_bf16 v[70:73], v[150:153], v[142:145], v[70:73]
	v_mfma_f32_16x16x32_bf16 v[66:69], v[158:161], v[142:145], v[66:69]
	v_mfma_f32_16x16x32_bf16 v[54:57], v[150:153], v[220:223], v[54:57]
	v_mfma_f32_16x16x32_bf16 v[50:53], v[158:161], v[220:223], v[50:53]
	v_mfma_f32_16x16x32_bf16 v[38:41], v[150:153], v[228:231], v[38:41]
	v_mfma_f32_16x16x32_bf16 v[34:37], v[158:161], v[228:231], v[34:37]
	v_mfma_f32_16x16x32_bf16 v[22:25], v[150:153], v[240:243], v[22:25]
	v_mfma_f32_16x16x32_bf16 v[18:21], v[158:161], v[240:243], v[18:21]
	s_setprio 0
	s_setprio 1
	v_mfma_f32_16x16x32_bf16 v[62:65], v[166:169], v[138:141], v[62:65]
	v_mfma_f32_16x16x32_bf16 v[58:61], v[174:177], v[138:141], v[58:61]
	v_mfma_f32_16x16x32_bf16 v[46:49], v[166:169], v[216:219], v[46:49]
	v_mfma_f32_16x16x32_bf16 v[42:45], v[174:177], v[216:219], v[42:45]
	v_mfma_f32_16x16x32_bf16 v[30:33], v[166:169], v[224:227], v[30:33]
	v_mfma_f32_16x16x32_bf16 v[26:29], v[174:177], v[224:227], v[26:29]
	v_mfma_f32_16x16x32_bf16 v[14:17], v[166:169], v[232:235], v[14:17]
	v_mfma_f32_16x16x32_bf16 v[10:13], v[174:177], v[232:235], v[10:13]
	v_mfma_f32_16x16x32_bf16 v[62:65], v[170:173], v[142:145], v[62:65]
	v_mfma_f32_16x16x32_bf16 v[58:61], v[162:165], v[142:145], v[58:61]
	v_mfma_f32_16x16x32_bf16 v[46:49], v[170:173], v[220:223], v[46:49]
	v_mfma_f32_16x16x32_bf16 v[42:45], v[162:165], v[220:223], v[42:45]
	v_mfma_f32_16x16x32_bf16 v[30:33], v[170:173], v[228:231], v[30:33]
	v_mfma_f32_16x16x32_bf16 v[26:29], v[162:165], v[228:231], v[26:29]
	v_mfma_f32_16x16x32_bf16 v[14:17], v[170:173], v[240:243], v[14:17]
	v_mfma_f32_16x16x32_bf16 v[10:13], v[162:165], v[240:243], v[10:13]
	s_setprio 0
	s_setprio 1
	v_cndmask_b32_e64 v138, 0, 1, s[52:53]
	v_cmp_ne_u32_e64 s[40:41], 1, v138
	s_andn2_b64 vcc, exec, s[52:53]
	s_mov_b64 s[96:97], -1
	s_cbranch_vccnz .LBB0_600
	v_mfma_f32_16x16x32_bf16 v[138:141], v[166:169], v[180:183], v[6:9]
	s_mov_b64 s[96:97], 0
	v_mfma_f32_16x16x32_bf16 v[142:145], v[174:177], v[180:183], v[2:5]
	v_mfma_f32_16x16x32_bf16 v[138:141], v[170:173], v[184:187], v[138:141]
	v_mfma_f32_16x16x32_bf16 v[142:145], v[162:165], v[184:187], v[142:145]

; #define PG8_SB(B) __builtin_amdgcn_rcpf(1.f + expneg(B))
; #define PG8_SB(B) __builtin_amdgcn_rcpf(1.f + expneg(B))
; #define PG8_STAGE(bufoff, gbase, voff) do { _Pragma("unroll") for (int _i = 0; _i < 2; ++_i) \
;         __builtin_amdgcn_global_load_lds((const unsigned*)((const char*)(gbase) + (size_t)_i * qstep + (voff)[0]), (PG8_LAS unsigned*)(lds + (bufoff) + ldsw + _i * 8192), 16, 0, 0); } while (0)
; #define PG8_LDA(dst, b, h) do { _Pragma("unroll") for (int m = 0; m < 4; ++m) _Pragma("unroll") for (int k = 0; k < 2; ++k) dst[m][k] = *(const PG8_LAS bf16x8*)(lds + PG8_SA(b, h) + aoff + m * 2048 + k * 1024); } while (0)
; #define PG8_LDB(dst, b, h) do { _Pragma("unroll") for (int n = 0; n < 2; ++n) _Pragma("unroll") for (int k = 0; k < 2; ++k) dst[n][k] = *(const PG8_LAS bf16x8*)(lds + PG8_SB(b, h) + boff + n * 2048 + k * 1024); } while (0)
; #define PG8_WAIT_L(n) asm volatile("s_waitcnt lgkmcnt(" #n ")" ::: "memory")
; template <class Epi, class Sched, bool ALIGN_EPI = false, bool SP2 = false, bool SLIVER = false>
; __device__ __forceinline__ void gemm_phase(PG8_LAS unsigned char* lds, const Gemm g, const Sched& S, const Epi& E) {
;     ...
;             const char* a2 = last ? nA : cA + (size_t)(t + 2) * kstep; const char* b2 = last ? nB : cB + (size_t)(t + 2) * kstep;
;             const char* a3 = a2 + kstep; const char* b3 = b2 + kstep;
;             const char* s1 = cS + (size_t)(t + 1) * kstep; const char* s2 = last ? nS : cS + (size_t)(t + 2) * kstep;
;             if (last && has_next) S.a_ready(nxt);
;             if constexpr (SP2) {
;             PG8_LDB(B0, 0, 0); PG8_LDB(B1, 0, 1); PG8_SCHED; PG8_LDA(At, 0, 0); PG8_STAGE(PG8_SA(1, 1), a1 + hstep, voffA); PG8_STAGE_S(1, s1);
;             PG8_WAIT_V89(); PG8_WAIT_L(0); PG8_BAR; PG8_MMA(0, 0, At, B0); PG8_MMA(0, 1, At, B1); PG8_BAR; PG8_SCHED;
;             PG8_LDA(At, 0, 1); PG8_LDS_S(0); PG8_STAGE(PG8_SB(0, 0), b2, voffB); PG8_STAGE(PG8_SB(0, 1), b2 + hstep, voffB); PG8_STAGE(PG8_SA(0, 0), a2, voffA);
;             PG8_WAIT_V89(); PG8_WAIT_L(0); PG8_BAR; PG8_MMA(1, 0, At, B0); PG8_MMA(1, 1, At, B1); PG8_MMA_S(); PG8_BAR; PG8_SCHED;
;             PG8_LDB(B0, 1, 0); PG8_LDB(B1, 1, 1); PG8_SCHED; PG8_LDA(At, 1, 0); PG8_STAGE(PG8_SA(0, 1), a2 + hstep, voffA); PG8_STAGE_S(0, s2);
;             PG8_WAIT_V89(); PG8_WAIT_L(0); PG8_BAR; PG8_MMA(0, 0, At, B0); PG8_MMA(0, 1, At, B1); PG8_BAR; PG8_SCHED;
.LBB0_602:
	s_add_u32 s77, s94, s62
	s_addc_u32 s78, s95, s63
	s_add_u32 s77, s77, 0x100
	s_addc_u32 s83, s78, 0
	s_and_b64 s[78:79], s[80:81], exec
	s_cselect_b32 s79, s66, s83
	s_cselect_b32 s78, s67, s77
	s_barrier
	s_setprio 0
	s_add_i32 s77, 0, 0x18000
	v_add_u32_e32 v2, s77, v212
	s_add_i32 s80, 0, 0x1c000
	ds_read_b128 v[146:149], v2
	ds_read_b128 v[150:153], v2 offset:1024
	ds_read_b128 v[154:157], v2 offset:2048
	ds_read_b128 v[158:161], v2 offset:3072
	v_add_u32_e32 v2, s80, v212
	ds_read_b128 v[166:169], v2
	ds_read_b128 v[170:173], v2 offset:1024
	ds_read_b128 v[174:177], v2 offset:2048
	ds_read_b128 v[162:165], v2 offset:3072
	s_mov_b32 m0, s49
	v_lshl_add_u64 v[208:209], v[210:211], 0, s[22:23]
	ds_read_b128 v[2:5], v215 offset:32768
	ds_read_b128 v[6:9], v215 offset:33792
	ds_read_b128 v[180:183], v215 offset:34816
	ds_read_b128 v[184:187], v215 offset:35840
	ds_read_b128 v[216:219], v215 offset:36864
	ds_read_b128 v[220:223], v215 offset:37888
	ds_read_b128 v[224:227], v215 offset:38912
	ds_read_b128 v[228:231], v215 offset:39936
	global_load_lds_dwordx4 v[208:209], off
	v_lshl_add_u64 v[208:209], v[210:211], 0, s[24:25]
	s_mov_b32 m0, s50
	s_nop 0
	global_load_lds_dwordx4 v[208:209], off
	v_lshl_add_u64 v[208:209], s[78:79], 0, v[192:193]
	s_mov_b32 m0, s51
	s_nop 0
	global_load_lds_dword v[208:209], off
	s_waitcnt vmcnt(9)
	s_waitcnt lgkmcnt(0)
	s_setprio 1
	s_barrier
	v_mfma_f32_16x16x32_bf16 v[134:137], v[146:149], v[2:5], v[134:137]
	v_mfma_f32_16x16x32_bf16 v[130:133], v[154:157], v[2:5], v[130:133]
	v_mfma_f32_16x16x32_bf16 v[118:121], v[146:149], v[180:183], v[118:121]
	v_mfma_f32_16x16x32_bf16 v[114:117], v[154:157], v[180:183], v[114:117]
	v_mfma_f32_16x16x32_bf16 v[102:105], v[146:149], v[216:219], v[102:105]
	v_mfma_f32_16x16x32_bf16 v[98:101], v[154:157], v[216:219], v[98:101]
	v_mfma_f32_16x16x32_bf16 v[86:89], v[146:149], v[224:227], v[86:89]
	v_mfma_f32_16x16x32_bf16 v[82:85], v[154:157], v[224:227], v[82:85]
	v_mfma_f32_16x16x32_bf16 v[134:137], v[150:153], v[6:9], v[134:137]
	v_mfma_f32_16x16x32_bf16 v[130:133], v[158:161], v[6:9], v[130:133]
	v_mfma_f32_16x16x32_bf16 v[118:121], v[150:153], v[184:187], v[118:121]
	v_mfma_f32_16x16x32_bf16 v[114:117], v[158:161], v[184:187], v[114:117]
	v_mfma_f32_16x16x32_bf16 v[102:105], v[150:153], v[220:223], v[102:105]
	v_mfma_f32_16x16x32_bf16 v[98:101], v[158:161], v[220:223], v[98:101]
	v_mfma_f32_16x16x32_bf16 v[86:89], v[150:153], v[228:231], v[86:89]
	v_mfma_f32_16x16x32_bf16 v[82:85], v[158:161], v[228:231], v[82:85]
	s_setprio 0
	s_setprio 1
	v_mfma_f32_16x16x32_bf16 v[126:129], v[166:169], v[2:5], v[126:129]
	v_mfma_f32_16x16x32_bf16 v[2:5], v[174:177], v[2:5], v[122:125]
	v_mfma_f32_16x16x32_bf16 v[122:125], v[162:165], v[6:9], v[2:5]
	v_mfma_f32_16x16x32_bf16 v[2:5], v[166:169], v[180:183], v[110:113]
	v_mfma_f32_16x16x32_bf16 v[110:113], v[170:173], v[184:187], v[2:5]
	v_mfma_f32_16x16x32_bf16 v[2:5], v[174:177], v[180:183], v[106:109]
	v_mfma_f32_16x16x32_bf16 v[106:109], v[162:165], v[184:187], v[2:5]
	v_mfma_f32_16x16x32_bf16 v[2:5], v[166:169], v[216:219], v[94:97]
	v_mfma_f32_16x16x32_bf16 v[94:97], v[170:173], v[220:223], v[2:5]
	v_mfma_f32_16x16x32_bf16 v[2:5], v[174:177], v[216:219], v[90:93]
	v_mfma_f32_16x16x32_bf16 v[90:93], v[162:165], v[220:223], v[2:5]
	v_mfma_f32_16x16x32_bf16 v[2:5], v[166:169], v[224:227], v[78:81]
	v_mfma_f32_16x16x32_bf16 v[78:81], v[170:173], v[228:231], v[2:5]
	v_mfma_f32_16x16x32_bf16 v[2:5], v[174:177], v[224:227], v[74:77]
	v_mfma_f32_16x16x32_bf16 v[126:129], v[170:173], v[6:9], v[126:129]
	v_mfma_f32_16x16x32_bf16 v[74:77], v[162:165], v[228:231], v[2:5]
	s_barrier
; #define PG8_SB(B) __builtin_amdgcn_rcpf(1.f + expneg(B))
; #define PG8_SB(B) __builtin_amdgcn_rcpf(1.f + expneg(B))
; #define PG8_STAGE(bufoff, gbase, voff) do { _Pragma("unroll") for (int _i = 0; _i < 2; ++_i) \
;         __builtin_amdgcn_global_load_lds((const unsigned*)((const char*)(gbase) + (size_t)_i * qstep + (voff)[0]), (PG8_LAS unsigned*)(lds + (bufoff) + ldsw + _i * 8192), 16, 0, 0); } while (0)
; #define PG8_LDA(dst, b, h) do { _Pragma("unroll") for (int m = 0; m < 4; ++m) _Pragma("unroll") for (int k = 0; k < 2; ++k) dst[m][k] = *(const PG8_LAS bf16x8*)(lds + PG8_SA(b, h) + aoff + m * 2048 + k * 1024); } while (0)
; #define PG8_MMA(ai, bj, At, Bt) do { __builtin_amdgcn_s_setprio(1); _Pragma("unroll") for (int m = 0; m < 4; ++m) _Pragma("unroll") for (int n = 0; n < 2; ++n) _Pragma("unroll") for (int k = 0; k < 2; ++k) \
;         acc[ai][bj][m][n] = __builtin_amdgcn_mfma_f32_16x16x32_bf16(Bt[n][k], At[m][k], acc[ai][bj][m][n], 0, 0, 0); __builtin_amdgcn_s_setprio(0); } while (0)
; #define PG8_WAIT_V89() do { if constexpr (SLIVER) PG8_WAIT_V(9); else PG8_WAIT_V(8); } while (0)
; #define PG8_LDS_S(b) do { if constexpr (SLIVER) { Sf[0] = *(const PG8_LAS bf16x8*)(lds + STAGE_BYTES + (b) * 2048 + soff0); Sf[1] = *(const PG8_LAS bf16x8*)(lds + STAGE_BYTES + (b) * 2048 + (soff0 ^ 64)); } } while (0)
; #define PG8_WAIT_L(n) asm volatile("s_waitcnt lgkmcnt(" #n ")" ::: "memory")
; #define PG8_BAR __builtin_amdgcn_s_barrier()
; #define PG8_SCHED __builtin_amdgcn_sched_barrier(0)
; template <class Epi, class Sched, bool ALIGN_EPI = false, bool SP2 = false, bool SLIVER = false>
; __device__ __forceinline__ void gemm_phase(PG8_LAS unsigned char* lds, const Gemm g, const Sched& S, const Epi& E) {
;     ...
;             PG8_LDA(At, 1, 1); PG8_LDS_S(1); PG8_STAGE(PG8_SB(1, 0), b3, voffB); PG8_STAGE(PG8_SB(1, 1), b3 + hstep, voffB); PG8_STAGE(PG8_SA(1, 0), a3, voffA);
;             PG8_WAIT_V89(); PG8_WAIT_L(0); PG8_BAR; PG8_MMA(1, 0, At, B0); PG8_MMA(1, 1, At, B1); PG8_MMA_S(); PG8_BAR; PG8_SCHED;
	s_setprio 0
	s_add_i32 s78, 0, 0x20800
	s_add_i32 s77, s77, s18
	v_add_u32_e32 v178, s78, v213
	v_add_u32_e32 v184, s78, v214
	v_lshl_add_u64 v[208:209], v[202:203], 0, s[26:27]
	s_mov_b32 m0, s77
	ds_read_b128 v[2:5], v215 offset:49152
	ds_read_b128 v[6:9], v215 offset:50176
	ds_read_b128 v[216:219], v215 offset:51200
	ds_read_b128 v[220:223], v215 offset:52224
	ds_read_b128 v[224:227], v215 offset:53248
	ds_read_b128 v[228:231], v215 offset:54272
	ds_read_b128 v[232:235], v215 offset:55296
	ds_read_b128 v[240:243], v215 offset:56320
	ds_read_b128 v[180:183], v178
	ds_read_b128 v[184:187], v184
	global_load_lds_dwordx4 v[208:209], off
	v_lshl_add_u64 v[208:209], v[202:203], 0, s[28:29]
	s_add_i32 m0, s77, 0x2000
	s_add_i32 s77, s80, s18
	global_load_lds_dwordx4 v[208:209], off
	v_lshl_add_u64 v[208:209], v[202:203], 0, s[30:31]
	s_mov_b32 m0, s77
	v_lshl_add_u64 v[202:203], v[202:203], 0, s[34:35]
	global_load_lds_dwordx4 v[208:209], off
	s_add_i32 m0, s77, 0x2000
	s_nop 0
	global_load_lds_dwordx4 v[202:203], off
	v_lshl_add_u64 v[202:203], v[210:211], 0, s[26:27]
	s_mov_b32 m0, s10
	s_nop 0
	global_load_lds_dwordx4 v[202:203], off
	v_lshl_add_u64 v[202:203], v[210:211], 0, s[28:29]
	s_mov_b32 m0, s2
	s_nop 0
	global_load_lds_dwordx4 v[202:203], off
	s_waitcnt vmcnt(9)
	s_waitcnt lgkmcnt(0)
	s_setprio 1
	s_barrier
	v_mfma_f32_16x16x32_bf16 v[70:73], v[146:149], v[2:5], v[70:73]
	v_mfma_f32_16x16x32_bf16 v[66:69], v[154:157], v[2:5], v[66:69]
	v_mfma_f32_16x16x32_bf16 v[54:57], v[146:149], v[216:219], v[54:57]
	v_mfma_f32_16x16x32_bf16 v[50:53], v[154:157], v[216:219], v[50:53]
	v_mfma_f32_16x16x32_bf16 v[38:41], v[146:149], v[224:227], v[38:41]
	v_mfma_f32_16x16x32_bf16 v[34:37], v[154:157], v[224:227], v[34:37]
	v_mfma_f32_16x16x32_bf16 v[22:25], v[146:149], v[232:235], v[22:25]
	v_mfma_f32_16x16x32_bf16 v[18:21], v[154:157], v[232:235], v[18:21]
	v_mfma_f32_16x16x32_bf16 v[70:73], v[150:153], v[6:9], v[70:73]
	v_mfma_f32_16x16x32_bf16 v[66:69], v[158:161], v[6:9], v[66:69]
	v_mfma_f32_16x16x32_bf16 v[54:57], v[150:153], v[220:223], v[54:57]
	v_mfma_f32_16x16x32_bf16 v[50:53], v[158:161], v[220:223], v[50:53]
	v_mfma_f32_16x16x32_bf16 v[38:41], v[150:153], v[228:231], v[38:41]
	v_mfma_f32_16x16x32_bf16 v[34:37], v[158:161], v[228:231], v[34:37]
	v_mfma_f32_16x16x32_bf16 v[22:25], v[150:153], v[240:243], v[22:25]
	v_mfma_f32_16x16x32_bf16 v[18:21], v[158:161], v[240:243], v[18:21]
	s_setprio 0
	s_setprio 1
	v_mfma_f32_16x16x32_bf16 v[62:65], v[166:169], v[2:5], v[62:65]
	v_mfma_f32_16x16x32_bf16 v[2:5], v[174:177], v[2:5], v[58:61]
	v_mfma_f32_16x16x32_bf16 v[58:61], v[162:165], v[6:9], v[2:5]
	v_mfma_f32_16x16x32_bf16 v[2:5], v[166:169], v[216:219], v[46:49]
	v_mfma_f32_16x16x32_bf16 v[46:49], v[170:173], v[220:223], v[2:5]
	v_mfma_f32_16x16x32_bf16 v[2:5], v[174:177], v[216:219], v[42:45]
	v_mfma_f32_16x16x32_bf16 v[42:45], v[162:165], v[220:223], v[2:5]
	v_mfma_f32_16x16x32_bf16 v[2:5], v[166:169], v[224:227], v[30:33]
	v_mfma_f32_16x16x32_bf16 v[30:33], v[170:173], v[228:231], v[2:5]
	v_mfma_f32_16x16x32_bf16 v[2:5], v[174:177], v[224:227], v[26:29]
	v_mfma_f32_16x16x32_bf16 v[26:29], v[162:165], v[228:231], v[2:5]
	v_mfma_f32_16x16x32_bf16 v[2:5], v[166:169], v[232:235], v[14:17]
	v_mfma_f32_16x16x32_bf16 v[14:17], v[170:173], v[240:243], v[2:5]
	v_mfma_f32_16x16x32_bf16 v[2:5], v[174:177], v[232:235], v[10:13]
	v_mfma_f32_16x16x32_bf16 v[62:65], v[170:173], v[6:9], v[62:65]
	v_mfma_f32_16x16x32_bf16 v[10:13], v[162:165], v[240:243], v[2:5]
	s_setprio 0
	s_setprio 1
	s_and_b64 vcc, exec, s[40:41]
	s_mov_b64 s[40:41], -1
	s_cbranch_vccnz .LBB0_604
	v_mfma_f32_16x16x32_bf16 v[2:5], v[166:169], v[180:183], v[138:141]
	s_mov_b64 s[40:41], 0
	v_mfma_f32_16x16x32_bf16 v[6:9], v[170:173], v[184:187], v[2:5]
	v_mfma_f32_16x16x32_bf16 v[2:5], v[174:177], v[180:183], v[142:145]
	v_mfma_f32_16x16x32_bf16 v[2:5], v[162:165], v[184:187], v[2:5]

; #define PG8_SB(B) __builtin_amdgcn_rcpf(1.f + expneg(B))
; #define PG8_SB(B) __builtin_amdgcn_rcpf(1.f + expneg(B))
; #define PG8_STAGE(bufoff, gbase, voff) do { _Pragma("unroll") for (int _i = 0; _i < 2; ++_i) \
;         __builtin_amdgcn_global_load_lds((const unsigned*)((const char*)(gbase) + (size_t)_i * qstep + (voff)[0]), (PG8_LAS unsigned*)(lds + (bufoff) + ldsw + _i * 8192), 16, 0, 0); } while (0)
; #define PG8_LDA(dst, b, h) do { _Pragma("unroll") for (int m = 0; m < 4; ++m) _Pragma("unroll") for (int k = 0; k < 2; ++k) dst[m][k] = *(const PG8_LAS bf16x8*)(lds + PG8_SA(b, h) + aoff + m * 2048 + k * 1024); } while (0)
; #define PG8_MMA(ai, bj, At, Bt) do { __builtin_amdgcn_s_setprio(1); _Pragma("unroll") for (int m = 0; m < 4; ++m) _Pragma("unroll") for (int n = 0; n < 2; ++n) _Pragma("unroll") for (int k = 0; k < 2; ++k) \
;         acc[ai][bj][m][n] = __builtin_amdgcn_mfma_f32_16x16x32_bf16(Bt[n][k], At[m][k], acc[ai][bj][m][n], 0, 0, 0); __builtin_amdgcn_s_setprio(0); } while (0)
; #define PG8_WAIT_V89() do { if constexpr (SLIVER) PG8_WAIT_V(9); else PG8_WAIT_V(8); } while (0)
; #define PG8_LDS_S(b) do { if constexpr (SLIVER) { Sf[0] = *(const PG8_LAS bf16x8*)(lds + STAGE_BYTES + (b) * 2048 + soff0); Sf[1] = *(const PG8_LAS bf16x8*)(lds + STAGE_BYTES + (b) * 2048 + (soff0 ^ 64)); } } while (0)
; #define PG8_WAIT_L(n) asm volatile("s_waitcnt lgkmcnt(" #n ")" ::: "memory")
; #define PG8_BAR __builtin_amdgcn_s_barrier()
; #define PG8_SCHED __builtin_amdgcn_sched_barrier(0)
; template <class Epi, class Sched, bool ALIGN_EPI = false, bool SP2 = false, bool SLIVER = false>
; __device__ __forceinline__ void gemm_phase(PG8_LAS unsigned char* lds, const Gemm g, const Sched& S, const Epi& E) {
;     ...
;             PG8_WAIT_V89(); PG8_WAIT_L(0); PG8_BAR; PG8_MMA(0, 0, At, B0); PG8_MMA(0, 1, At, B1); PG8_BAR; PG8_SCHED;
;             PG8_LDA(At, 0, 1); PG8_LDS_S(0); PG8_STAGE(PG8_SB(0, 0), b2, voffB); PG8_STAGE(PG8_SB(0, 1), b2 + hstep, voffB); PG8_STAGE(PG8_SA(0, 0), a2, voffA);
;             PG8_WAIT_V89(); PG8_WAIT_L(0); PG8_BAR; PG8_MMA(1, 0, At, B0); PG8_MMA(1, 1, At, B1); PG8_MMA_S(); PG8_BAR; PG8_SCHED;
.Lgup_skipw0:
	s_waitcnt lgkmcnt(0)
	s_setprio 1
	s_barrier
	v_mfma_f32_16x16x32_bf16 v[126:129], v[130:133], v[172:175], v[126:129]
	v_mfma_f32_16x16x32_bf16 v[118:121], v[148:151], v[172:175], v[118:121]
	v_mfma_f32_16x16x32_bf16 v[110:113], v[130:133], v[184:187], v[110:113]
	v_mfma_f32_16x16x32_bf16 v[102:105], v[148:151], v[184:187], v[102:105]
	v_mfma_f32_16x16x32_bf16 v[94:97], v[130:133], v[192:195], v[94:97]
	v_mfma_f32_16x16x32_bf16 v[86:89], v[148:151], v[192:195], v[86:89]
	v_mfma_f32_16x16x32_bf16 v[78:81], v[130:133], v[200:203], v[78:81]
	v_mfma_f32_16x16x32_bf16 v[70:73], v[148:151], v[200:203], v[70:73]
	v_mfma_f32_16x16x32_bf16 v[126:129], v[138:141], v[180:183], v[126:129]
	v_mfma_f32_16x16x32_bf16 v[118:121], v[152:155], v[180:183], v[118:121]
	v_mfma_f32_16x16x32_bf16 v[110:113], v[138:141], v[188:191], v[110:113]
	v_mfma_f32_16x16x32_bf16 v[102:105], v[152:155], v[188:191], v[102:105]
	v_mfma_f32_16x16x32_bf16 v[94:97], v[138:141], v[196:199], v[94:97]
	v_mfma_f32_16x16x32_bf16 v[86:89], v[152:155], v[196:199], v[86:89]
	v_mfma_f32_16x16x32_bf16 v[78:81], v[138:141], v[210:213], v[78:81]
	v_mfma_f32_16x16x32_bf16 v[70:73], v[152:155], v[210:213], v[70:73]
	s_setprio 0
	s_setprio 1
	v_mfma_f32_16x16x32_bf16 v[122:125], v[156:159], v[172:175], v[122:125]
	v_mfma_f32_16x16x32_bf16 v[114:117], v[164:167], v[172:175], v[114:117]
	v_mfma_f32_16x16x32_bf16 v[106:109], v[156:159], v[184:187], v[106:109]
	v_mfma_f32_16x16x32_bf16 v[98:101], v[164:167], v[184:187], v[98:101]
	v_mfma_f32_16x16x32_bf16 v[90:93], v[156:159], v[192:195], v[90:93]
	v_mfma_f32_16x16x32_bf16 v[82:85], v[164:167], v[192:195], v[82:85]
	v_mfma_f32_16x16x32_bf16 v[74:77], v[156:159], v[200:203], v[74:77]
	v_mfma_f32_16x16x32_bf16 v[66:69], v[164:167], v[200:203], v[66:69]
	v_mfma_f32_16x16x32_bf16 v[122:125], v[160:163], v[180:183], v[122:125]
	v_mfma_f32_16x16x32_bf16 v[114:117], v[168:171], v[180:183], v[114:117]
	v_mfma_f32_16x16x32_bf16 v[106:109], v[160:163], v[188:191], v[106:109]
	v_mfma_f32_16x16x32_bf16 v[98:101], v[168:171], v[188:191], v[98:101]
	v_mfma_f32_16x16x32_bf16 v[90:93], v[160:163], v[196:199], v[90:93]
	v_mfma_f32_16x16x32_bf16 v[82:85], v[168:171], v[196:199], v[82:85]
	v_mfma_f32_16x16x32_bf16 v[74:77], v[160:163], v[210:213], v[74:77]
	v_mfma_f32_16x16x32_bf16 v[66:69], v[168:171], v[210:213], v[66:69]
	s_barrier
	s_setprio 0
	v_lshl_add_u64 v[144:145], s[76:77], 0, v[178:179]
	s_add_i32 s76, s78, s88
	s_mov_b32 m0, s76
	ds_read_b128 v[172:175], v147 offset:16384
	ds_read_b128 v[180:183], v147 offset:17408
	ds_read_b128 v[184:187], v147 offset:18432
	ds_read_b128 v[188:191], v147 offset:19456
	ds_read_b128 v[192:195], v147 offset:20480
	ds_read_b128 v[196:199], v147 offset:21504
	ds_read_b128 v[200:203], v147 offset:22528
	ds_read_b128 v[210:213], v147 offset:23552
	global_load_lds_dwordx4 v[144:145], off
	v_lshl_add_u64 v[176:177], v[144:145], 0, s[20:21]
	s_add_i32 m0, s76, 0x2000
	s_add_i32 s76, s79, s88
	global_load_lds_dwordx4 v[176:177], off
	v_lshl_add_u64 v[176:177], v[144:145], 0, s[22:23]
	s_mov_b32 m0, s76
	s_nop 0
	global_load_lds_dwordx4 v[176:177], off
	v_lshl_add_u64 v[176:177], v[144:145], 0, s[24:25]
	s_add_i32 m0, s76, 0x2000
	s_nop 0
	global_load_lds_dwordx4 v[176:177], off
	v_lshl_add_u64 v[176:177], s[80:81], 0, v[134:135]
	s_mov_b32 m0, s45
	v_lshl_add_u64 v[208:209], v[176:177], 0, s[20:21]
	global_load_lds_dwordx4 v[176:177], off
	s_mov_b32 m0, s83
	s_nop 0
	global_load_lds_dwordx4 v[208:209], off
	s_cmp_eq_u32 s69, s101
	s_cbranch_scc1 .Lgup_skipw1
	s_waitcnt vmcnt(8)
.Lgup_skipw1:
	s_waitcnt lgkmcnt(0)
	s_setprio 1
	s_barrier
	v_mfma_f32_16x16x32_bf16 v[62:65], v[130:133], v[172:175], v[62:65]
	v_mfma_f32_16x16x32_bf16 v[54:57], v[148:151], v[172:175], v[54:57]
	v_mfma_f32_16x16x32_bf16 v[46:49], v[130:133], v[184:187], v[46:49]
	v_mfma_f32_16x16x32_bf16 v[38:41], v[148:151], v[184:187], v[38:41]
	v_mfma_f32_16x16x32_bf16 v[30:33], v[130:133], v[192:195], v[30:33]
	v_mfma_f32_16x16x32_bf16 v[22:25], v[148:151], v[192:195], v[22:25]
	v_mfma_f32_16x16x32_bf16 v[14:17], v[130:133], v[200:203], v[14:17]
	v_mfma_f32_16x16x32_bf16 v[6:9], v[148:151], v[200:203], v[6:9]
	v_mfma_f32_16x16x32_bf16 v[62:65], v[138:141], v[180:183], v[62:65]
	v_mfma_f32_16x16x32_bf16 v[54:57], v[152:155], v[180:183], v[54:57]
	v_mfma_f32_16x16x32_bf16 v[46:49], v[138:141], v[188:191], v[46:49]
	v_mfma_f32_16x16x32_bf16 v[38:41], v[152:155], v[188:191], v[38:41]
	v_mfma_f32_16x16x32_bf16 v[30:33], v[138:141], v[196:199], v[30:33]
	v_mfma_f32_16x16x32_bf16 v[22:25], v[152:155], v[196:199], v[22:25]
	v_mfma_f32_16x16x32_bf16 v[14:17], v[138:141], v[210:213], v[14:17]
	v_mfma_f32_16x16x32_bf16 v[6:9], v[152:155], v[210:213], v[6:9]
	s_setprio 0
	s_setprio 1
	v_mfma_f32_16x16x32_bf16 v[58:61], v[156:159], v[172:175], v[58:61]
	v_mfma_f32_16x16x32_bf16 v[50:53], v[164:167], v[172:175], v[50:53]
	v_mfma_f32_16x16x32_bf16 v[42:45], v[156:159], v[184:187], v[42:45]
	v_mfma_f32_16x16x32_bf16 v[34:37], v[164:167], v[184:187], v[34:37]
	v_mfma_f32_16x16x32_bf16 v[26:29], v[156:159], v[192:195], v[26:29]
	v_mfma_f32_16x16x32_bf16 v[18:21], v[164:167], v[192:195], v[18:21]
	v_mfma_f32_16x16x32_bf16 v[10:13], v[156:159], v[200:203], v[10:13]
	v_mfma_f32_16x16x32_bf16 v[2:5], v[164:167], v[200:203], v[2:5]
	v_mfma_f32_16x16x32_bf16 v[58:61], v[160:163], v[180:183], v[58:61]
	v_mfma_f32_16x16x32_bf16 v[50:53], v[168:171], v[180:183], v[50:53]
	v_mfma_f32_16x16x32_bf16 v[42:45], v[160:163], v[188:191], v[42:45]
	v_mfma_f32_16x16x32_bf16 v[34:37], v[168:171], v[188:191], v[34:37]
	v_mfma_f32_16x16x32_bf16 v[26:29], v[160:163], v[196:199], v[26:29]
	v_mfma_f32_16x16x32_bf16 v[18:21], v[168:171], v[196:199], v[18:21]
	v_mfma_f32_16x16x32_bf16 v[10:13], v[160:163], v[210:213], v[10:13]
	v_mfma_f32_16x16x32_bf16 v[2:5], v[168:171], v[210:213], v[2:5]
	s_barrier
; #define PG8_STAGE(bufoff, gbase, voff) do { _Pragma("unroll") for (int _i = 0; _i < 2; ++_i) \
;         __builtin_amdgcn_global_load_lds((const unsigned*)((const char*)(gbase) + (size_t)_i * qstep + (voff)[0]), (PG8_LAS unsigned*)(lds + (bufoff) + ldsw + _i * 8192), 16, 0, 0); } while (0)
; #define PG8_LDA(dst, b, h) do { _Pragma("unroll") for (int m = 0; m < 4; ++m) _Pragma("unroll") for (int k = 0; k < 2; ++k) dst[m][k] = *(const PG8_LAS bf16x8*)(lds + PG8_SA(b, h) + aoff + m * 2048 + k * 1024); } while (0)
; #define PG8_LDB(dst, b, h) do { _Pragma("unroll") for (int n = 0; n < 2; ++n) _Pragma("unroll") for (int k = 0; k < 2; ++k) dst[n][k] = *(const PG8_LAS bf16x8*)(lds + PG8_SB(b, h) + boff + n * 2048 + k * 1024); } while (0)
; #define PG8_MMA(ai, bj, At, Bt) do { __builtin_amdgcn_s_setprio(1); _Pragma("unroll") for (int m = 0; m < 4; ++m) _Pragma("unroll") for (int n = 0; n < 2; ++n) _Pragma("unroll") for (int k = 0; k < 2; ++k) \
;         acc[ai][bj][m][n] = __builtin_amdgcn_mfma_f32_16x16x32_bf16(Bt[n][k], At[m][k], acc[ai][bj][m][n], 0, 0, 0); __builtin_amdgcn_s_setprio(0); } while (0)
; #define PG8_WAIT_V89() do { if constexpr (SLIVER) PG8_WAIT_V(9); else PG8_WAIT_V(8); } while (0)
; #define PG8_STAGE_S(b, gbase) do { if constexpr (SLIVER) __builtin_amdgcn_global_load_lds((const unsigned*)((const char*)(gbase) + voffS), (PG8_LAS unsigned*)(lds + STAGE_BYTES + (b) * 2048 + wid * 256), 4, 0, 0); } while (0)
; #define PG8_WAIT_L(n) asm volatile("s_waitcnt lgkmcnt(" #n ")" ::: "memory")
; #define PG8_BAR __builtin_amdgcn_s_barrier()
; #define PG8_SCHED __builtin_amdgcn_sched_barrier(0)
; template <class Epi, class Sched, bool ALIGN_EPI = false, bool SP2 = false, bool SLIVER = false>
; __device__ __forceinline__ void gemm_phase(PG8_LAS unsigned char* lds, const Gemm g, const Sched& S, const Epi& E) {
;     ...
;             PG8_LDB(B0, 1, 0); PG8_LDB(B1, 1, 1); PG8_SCHED; PG8_LDA(At, 1, 0); PG8_STAGE(PG8_SA(0, 1), a2 + hstep, voffA); PG8_STAGE_S(0, s2);
;             PG8_WAIT_V89(); PG8_WAIT_L(0); PG8_BAR; PG8_MMA(0, 0, At, B0); PG8_MMA(0, 1, At, B1); PG8_BAR; PG8_SCHED;
	s_setprio 0
	s_add_i32 s76, 0, 0x18000
	v_add_u32_e32 v142, s76, v143
	s_add_i32 s77, 0, 0x1c000
	ds_read_b128 v[130:133], v142
	ds_read_b128 v[138:141], v142 offset:1024
	ds_read_b128 v[148:151], v142 offset:2048
	ds_read_b128 v[152:155], v142 offset:3072
	v_add_u32_e32 v142, s77, v143
	ds_read_b128 v[156:159], v142
	ds_read_b128 v[160:163], v142 offset:1024
	ds_read_b128 v[164:167], v142 offset:2048
	ds_read_b128 v[168:171], v142 offset:3072
	s_mov_b32 m0, s90
	v_lshl_add_u64 v[208:209], v[176:177], 0, s[22:23]
	ds_read_b128 v[172:175], v147 offset:32768
	ds_read_b128 v[180:183], v147 offset:33792
	ds_read_b128 v[184:187], v147 offset:34816
	ds_read_b128 v[188:191], v147 offset:35840
	ds_read_b128 v[192:195], v147 offset:36864
	ds_read_b128 v[196:199], v147 offset:37888
	ds_read_b128 v[200:203], v147 offset:38912
	ds_read_b128 v[210:213], v147 offset:39936
	global_load_lds_dwordx4 v[208:209], off
	v_lshl_add_u64 v[208:209], v[176:177], 0, s[24:25]
	s_mov_b32 m0, s91
	s_nop 0
	global_load_lds_dwordx4 v[208:209], off
	s_waitcnt vmcnt(8)
	s_waitcnt lgkmcnt(0)
	s_setprio 1
	s_barrier
	v_mfma_f32_16x16x32_bf16 v[126:129], v[130:133], v[172:175], v[126:129]
	v_mfma_f32_16x16x32_bf16 v[118:121], v[148:151], v[172:175], v[118:121]
	v_mfma_f32_16x16x32_bf16 v[110:113], v[130:133], v[184:187], v[110:113]
	v_mfma_f32_16x16x32_bf16 v[102:105], v[148:151], v[184:187], v[102:105]
	v_mfma_f32_16x16x32_bf16 v[94:97], v[130:133], v[192:195], v[94:97]
	v_mfma_f32_16x16x32_bf16 v[86:89], v[148:151], v[192:195], v[86:89]
	v_mfma_f32_16x16x32_bf16 v[78:81], v[130:133], v[200:203], v[78:81]
	v_mfma_f32_16x16x32_bf16 v[70:73], v[148:151], v[200:203], v[70:73]
	v_mfma_f32_16x16x32_bf16 v[126:129], v[138:141], v[180:183], v[126:129]
	v_mfma_f32_16x16x32_bf16 v[118:121], v[152:155], v[180:183], v[118:121]
	v_mfma_f32_16x16x32_bf16 v[110:113], v[138:141], v[188:191], v[110:113]
	v_mfma_f32_16x16x32_bf16 v[102:105], v[152:155], v[188:191], v[102:105]
	v_mfma_f32_16x16x32_bf16 v[94:97], v[138:141], v[196:199], v[94:97]
	v_mfma_f32_16x16x32_bf16 v[86:89], v[152:155], v[196:199], v[86:89]
	v_mfma_f32_16x16x32_bf16 v[78:81], v[138:141], v[210:213], v[78:81]
	v_mfma_f32_16x16x32_bf16 v[70:73], v[152:155], v[210:213], v[70:73]
	s_setprio 0
	s_setprio 1
	v_mfma_f32_16x16x32_bf16 v[122:125], v[156:159], v[172:175], v[122:125]
	v_mfma_f32_16x16x32_bf16 v[114:117], v[164:167], v[172:175], v[114:117]
	v_mfma_f32_16x16x32_bf16 v[106:109], v[156:159], v[184:187], v[106:109]
	v_mfma_f32_16x16x32_bf16 v[98:101], v[164:167], v[184:187], v[98:101]
	v_mfma_f32_16x16x32_bf16 v[90:93], v[156:159], v[192:195], v[90:93]
	v_mfma_f32_16x16x32_bf16 v[82:85], v[164:167], v[192:195], v[82:85]
	v_mfma_f32_16x16x32_bf16 v[74:77], v[156:159], v[200:203], v[74:77]
	v_mfma_f32_16x16x32_bf16 v[66:69], v[164:167], v[200:203], v[66:69]
	v_mfma_f32_16x16x32_bf16 v[122:125], v[160:163], v[180:183], v[122:125]
	v_mfma_f32_16x16x32_bf16 v[114:117], v[168:171], v[180:183], v[114:117]
	v_mfma_f32_16x16x32_bf16 v[106:109], v[160:163], v[188:191], v[106:109]
	v_mfma_f32_16x16x32_bf16 v[98:101], v[168:171], v[188:191], v[98:101]
	v_mfma_f32_16x16x32_bf16 v[90:93], v[160:163], v[196:199], v[90:93]
	v_mfma_f32_16x16x32_bf16 v[82:85], v[168:171], v[196:199], v[82:85]
	v_mfma_f32_16x16x32_bf16 v[74:77], v[160:163], v[210:213], v[74:77]
	v_mfma_f32_16x16x32_bf16 v[66:69], v[168:171], v[210:213], v[66:69]
	s_barrier
; #define PG8_SB(B) __builtin_amdgcn_rcpf(1.f + expneg(B))
; #define PG8_SB(B) __builtin_amdgcn_rcpf(1.f + expneg(B))
; #define PG8_STAGE(bufoff, gbase, voff) do { _Pragma("unroll") for (int _i = 0; _i < 2; ++_i) \
;         __builtin_amdgcn_global_load_lds((const unsigned*)((const char*)(gbase) + (size_t)_i * qstep + (voff)[0]), (PG8_LAS unsigned*)(lds + (bufoff) + ldsw + _i * 8192), 16, 0, 0); } while (0)
; #define PG8_LDA(dst, b, h) do { _Pragma("unroll") for (int m = 0; m < 4; ++m) _Pragma("unroll") for (int k = 0; k < 2; ++k) dst[m][k] = *(const PG8_LAS bf16x8*)(lds + PG8_SA(b, h) + aoff + m * 2048 + k * 1024); } while (0)
; #define PG8_MMA(ai, bj, At, Bt) do { __builtin_amdgcn_s_setprio(1); _Pragma("unroll") for (int m = 0; m < 4; ++m) _Pragma("unroll") for (int n = 0; n < 2; ++n) _Pragma("unroll") for (int k = 0; k < 2; ++k) \
;         acc[ai][bj][m][n] = __builtin_amdgcn_mfma_f32_16x16x32_bf16(Bt[n][k], At[m][k], acc[ai][bj][m][n], 0, 0, 0); __builtin_amdgcn_s_setprio(0); } while (0)
; #define PG8_WAIT_V89() do { if constexpr (SLIVER) PG8_WAIT_V(9); else PG8_WAIT_V(8); } while (0)
; #define PG8_LDS_S(b) do { if constexpr (SLIVER) { Sf[0] = *(const PG8_LAS bf16x8*)(lds + STAGE_BYTES + (b) * 2048 + soff0); Sf[1] = *(const PG8_LAS bf16x8*)(lds + STAGE_BYTES + (b) * 2048 + (soff0 ^ 64)); } } while (0)
; #define PG8_WAIT_L(n) asm volatile("s_waitcnt lgkmcnt(" #n ")" ::: "memory")
; #define PG8_BAR __builtin_amdgcn_s_barrier()
; #define PG8_SCHED __builtin_amdgcn_sched_barrier(0)
; template <class Epi, class Sched, bool ALIGN_EPI = false, bool SP2 = false, bool SLIVER = false>
; __device__ __forceinline__ void gemm_phase(PG8_LAS unsigned char* lds, const Gemm g, const Sched& S, const Epi& E) {
;     ...
;             PG8_LDA(At, 1, 1); PG8_LDS_S(1); PG8_STAGE(PG8_SB(1, 0), b3, voffB); PG8_STAGE(PG8_SB(1, 1), b3 + hstep, voffB); PG8_STAGE(PG8_SA(1, 0), a3, voffA);
;             PG8_WAIT_V89(); PG8_WAIT_L(0); PG8_BAR; PG8_MMA(1, 0, At, B0); PG8_MMA(1, 1, At, B1); PG8_MMA_S(); PG8_BAR; PG8_SCHED;
;     ...
;         if constexpr (ALIGN_EPI) { if (wr == 0) PG8_BAR; }
	s_setprio 0
	s_add_i32 s76, s76, s88
	v_lshl_add_u64 v[208:209], v[144:145], 0, s[26:27]
	s_mov_b32 m0, s76
	ds_read_b128 v[172:175], v147 offset:49152
	ds_read_b128 v[180:183], v147 offset:50176
	ds_read_b128 v[184:187], v147 offset:51200
	ds_read_b128 v[188:191], v147 offset:52224
	ds_read_b128 v[192:195], v147 offset:53248
	ds_read_b128 v[196:199], v147 offset:54272
	ds_read_b128 v[200:203], v147 offset:55296
	ds_read_b128 v[210:213], v147 offset:56320
	global_load_lds_dwordx4 v[208:209], off
	v_lshl_add_u64 v[208:209], v[144:145], 0, s[28:29]
	s_add_i32 m0, s76, 0x2000
	s_add_i32 s76, s77, s88
	global_load_lds_dwordx4 v[208:209], off
	v_lshl_add_u64 v[208:209], v[144:145], 0, s[30:31]
	s_mov_b32 m0, s76
	v_lshl_add_u64 v[144:145], v[144:145], 0, s[34:35]
	global_load_lds_dwordx4 v[208:209], off
	s_add_i32 m0, s76, 0x2000
	s_nop 0
	global_load_lds_dwordx4 v[144:145], off
	v_lshl_add_u64 v[144:145], v[176:177], 0, s[26:27]
	s_mov_b32 m0, s93
	s_nop 0
	global_load_lds_dwordx4 v[144:145], off
	v_lshl_add_u64 v[144:145], v[176:177], 0, s[28:29]
	s_mov_b32 m0, s94
	s_nop 0
	global_load_lds_dwordx4 v[144:145], off
	s_waitcnt vmcnt(8)
	s_waitcnt lgkmcnt(0)
	s_setprio 1
	s_barrier
	v_mfma_f32_16x16x32_bf16 v[62:65], v[130:133], v[172:175], v[62:65]
	v_mfma_f32_16x16x32_bf16 v[54:57], v[148:151], v[172:175], v[54:57]
	v_mfma_f32_16x16x32_bf16 v[46:49], v[130:133], v[184:187], v[46:49]
	v_mfma_f32_16x16x32_bf16 v[38:41], v[148:151], v[184:187], v[38:41]
	v_mfma_f32_16x16x32_bf16 v[30:33], v[130:133], v[192:195], v[30:33]
	v_mfma_f32_16x16x32_bf16 v[22:25], v[148:151], v[192:195], v[22:25]
	v_mfma_f32_16x16x32_bf16 v[14:17], v[130:133], v[200:203], v[14:17]
	v_mfma_f32_16x16x32_bf16 v[6:9], v[148:151], v[200:203], v[6:9]
	v_mfma_f32_16x16x32_bf16 v[62:65], v[138:141], v[180:183], v[62:65]
	v_mfma_f32_16x16x32_bf16 v[54:57], v[152:155], v[180:183], v[54:57]
	v_mfma_f32_16x16x32_bf16 v[46:49], v[138:141], v[188:191], v[46:49]
	v_mfma_f32_16x16x32_bf16 v[38:41], v[152:155], v[188:191], v[38:41]
	v_mfma_f32_16x16x32_bf16 v[30:33], v[138:141], v[196:199], v[30:33]
	v_mfma_f32_16x16x32_bf16 v[22:25], v[152:155], v[196:199], v[22:25]
	v_mfma_f32_16x16x32_bf16 v[14:17], v[138:141], v[210:213], v[14:17]
	v_mfma_f32_16x16x32_bf16 v[6:9], v[152:155], v[210:213], v[6:9]
	s_setprio 0
	s_setprio 1
	v_mfma_f32_16x16x32_bf16 v[58:61], v[156:159], v[172:175], v[58:61]
	v_mfma_f32_16x16x32_bf16 v[50:53], v[164:167], v[172:175], v[50:53]
	v_mfma_f32_16x16x32_bf16 v[42:45], v[156:159], v[184:187], v[42:45]
	v_mfma_f32_16x16x32_bf16 v[34:37], v[164:167], v[184:187], v[34:37]
	v_mfma_f32_16x16x32_bf16 v[26:29], v[156:159], v[192:195], v[26:29]
	v_mfma_f32_16x16x32_bf16 v[18:21], v[164:167], v[192:195], v[18:21]
	v_mfma_f32_16x16x32_bf16 v[10:13], v[156:159], v[200:203], v[10:13]
	v_mfma_f32_16x16x32_bf16 v[2:5], v[164:167], v[200:203], v[2:5]
	v_mfma_f32_16x16x32_bf16 v[58:61], v[160:163], v[180:183], v[58:61]
	v_mfma_f32_16x16x32_bf16 v[50:53], v[168:171], v[180:183], v[50:53]
	v_mfma_f32_16x16x32_bf16 v[42:45], v[160:163], v[188:191], v[42:45]
	v_mfma_f32_16x16x32_bf16 v[34:37], v[168:171], v[188:191], v[34:37]
	v_mfma_f32_16x16x32_bf16 v[26:29], v[160:163], v[196:199], v[26:29]
	v_mfma_f32_16x16x32_bf16 v[18:21], v[168:171], v[196:199], v[18:21]
	v_mfma_f32_16x16x32_bf16 v[10:13], v[160:163], v[210:213], v[10:13]
	v_mfma_f32_16x16x32_bf16 v[2:5], v[168:171], v[210:213], v[2:5]
	s_barrier
	s_setprio 0
	s_add_i32 s69, s69, 2
	s_add_u32 s62, s62, 0x100
	s_addc_u32 s63, s63, 0
	s_add_u32 s67, s67, 0x100
	s_addc_u32 s68, s68, 0
	s_cmp_gt_u32 s69, 29
	s_cbranch_scc0 .LBB0_705
	s_and_b64 vcc, exec, s[42:43]
	s_cbranch_vccz .LBB0_708
	s_barrier

; #define PG8_STAGE(bufoff, gbase, voff) do { _Pragma("unroll") for (int _i = 0; _i < 2; ++_i) \
;         __builtin_amdgcn_global_load_lds((const unsigned*)((const char*)(gbase) + (size_t)_i * qstep + (voff)[0]), (PG8_LAS unsigned*)(lds + (bufoff) + ldsw + _i * 8192), 16, 0, 0); } while (0)
; #define PG8_LDA(dst, b, h) do { _Pragma("unroll") for (int m = 0; m < 4; ++m) _Pragma("unroll") for (int k = 0; k < 2; ++k) dst[m][k] = *(const PG8_LAS bf16x8*)(lds + PG8_SA(b, h) + aoff + m * 2048 + k * 1024); } while (0)
; #define PG8_LDB(dst, b, h) do { _Pragma("unroll") for (int n = 0; n < 2; ++n) _Pragma("unroll") for (int k = 0; k < 2; ++k) dst[n][k] = *(const PG8_LAS bf16x8*)(lds + PG8_SB(b, h) + boff + n * 2048 + k * 1024); } while (0)
; #define PG8_MMA(ai, bj, At, Bt) do { __builtin_amdgcn_s_setprio(1); _Pragma("unroll") for (int m = 0; m < 4; ++m) _Pragma("unroll") for (int n = 0; n < 2; ++n) _Pragma("unroll") for (int k = 0; k < 2; ++k) \
;         acc[ai][bj][m][n] = __builtin_amdgcn_mfma_f32_16x16x32_bf16(Bt[n][k], At[m][k], acc[ai][bj][m][n], 0, 0, 0); __builtin_amdgcn_s_setprio(0); } while (0)
; #define PG8_WAIT_V89() do { if constexpr (SLIVER) PG8_WAIT_V(9); else PG8_WAIT_V(8); } while (0)
; #define PG8_WAIT_L(n) asm volatile("s_waitcnt lgkmcnt(" #n ")" ::: "memory")
; #define PG8_BAR __builtin_amdgcn_s_barrier()
; template <class Epi, class Sched, bool ALIGN_EPI = false, bool SP2 = false, bool SLIVER = false>
; __device__ __forceinline__ void gemm_phase(PG8_LAS unsigned char* lds, const Gemm g, const Sched& S, const Epi& E) {
;     ...
;         for (int t = 0; t < nt; t += 2) {
;             const bool last = (t == nt - 2);
;             const char* a1 = cA + (size_t)(t + 1) * kstep;
;             const char* a2 = last ? nA : cA + (size_t)(t + 2) * kstep; const char* b2 = last ? nB : cB + (size_t)(t + 2) * kstep;
;             const char* a3 = a2 + kstep; const char* b3 = b2 + kstep;
;             const char* s1 = cS + (size_t)(t + 1) * kstep; const char* s2 = last ? nS : cS + (size_t)(t + 2) * kstep;
;             if (last && has_next) S.a_ready(nxt);
;             if constexpr (SP2) {
;             PG8_LDB(B0, 0, 0); PG8_LDB(B1, 0, 1); PG8_SCHED; PG8_LDA(At, 0, 0); PG8_STAGE(PG8_SA(1, 1), a1 + hstep, voffA); PG8_STAGE_S(1, s1);
;             PG8_WAIT_V89(); PG8_WAIT_L(0); PG8_BAR; PG8_MMA(0, 0, At, B0); PG8_MMA(0, 1, At, B1); PG8_BAR; PG8_SCHED;
.LBB0_810:
	s_barrier
	s_setprio 0
	s_add_i32 s12, s12, 2
	s_add_u32 s62, s62, 0x100
	s_addc_u32 s63, s63, 0
	s_cmpk_gt_u32 s12, 0x55
	s_cbranch_scc1 .LBB0_821
.LBB0_811:
	s_add_u32 s13, s90, s62
	s_addc_u32 s40, s91, s63
	s_add_u32 s13, s13, 0x100
	s_addc_u32 s66, s40, 0
	s_add_u32 s68, s2, s62
	s_addc_u32 s67, s3, s63
	s_add_i32 s69, 0, 0x10000
	s_cmpk_eq_i32 s62, 0x2b00
	s_cselect_b64 s[80:81], -1, 0
	s_and_b64 s[40:41], s[80:81], exec
	s_cselect_b32 s41, s85, s66
	s_cselect_b32 s40, s84, s13
	v_add_u32_e32 v66, s69, v220
	s_cselect_b32 s67, s87, s67
	s_cselect_b32 s66, s86, s68
	s_add_i32 s13, 0, 0x14000
	ds_read_b128 v[154:157], v66
	ds_read_b128 v[158:161], v66 offset:1024
	ds_read_b128 v[162:165], v66 offset:2048
	ds_read_b128 v[174:177], v66 offset:3072
	v_add_u32_e32 v66, s13, v220
	ds_read_b128 v[184:187], v66
	ds_read_b128 v[188:191], v66 offset:1024
	ds_read_b128 v[192:195], v66 offset:2048
	ds_read_b128 v[180:183], v66 offset:3072
	v_lshl_add_u64 v[146:147], v[214:215], 0, s[62:63]
	v_lshl_add_u64 v[148:149], v[146:147], 0, s[8:9]
	s_add_i32 m0, s19, 0xc000
	s_mov_b64 s[94:95], 0x210080
	ds_read_b128 v[66:69], v223
	ds_read_b128 v[70:73], v223 offset:1024
	ds_read_b128 v[74:77], v223 offset:2048
	ds_read_b128 v[78:81], v223 offset:3072
	ds_read_b128 v[216:219], v223 offset:4096
	ds_read_b128 v[224:227], v223 offset:5120
	ds_read_b128 v[228:231], v223 offset:6144
	ds_read_b128 v[232:235], v223 offset:7168
	global_load_lds_dwordx4 v[148:149], off
	v_lshl_add_u64 v[146:147], v[146:147], 0, s[94:95]
	s_add_i32 m0, s19, 0xe000
	s_nop 0
	global_load_lds_dwordx4 v[146:147], off
	v_lshl_add_u64 v[146:147], v[212:213], 0, s[62:63]
	s_add_i32 m0, s96, 0x20800
	s_nop 0
	global_load_lds_dword v[146:147], off
	s_waitcnt vmcnt(9)
	s_waitcnt lgkmcnt(0)
	s_setprio 1
	s_barrier
	v_mfma_f32_16x16x32_bf16 v[146:149], v[154:157], v[66:69], v[170:173]
	v_mfma_f32_16x16x32_bf16 v[150:153], v[162:165], v[66:69], v[166:169]
	v_mfma_f32_16x16x32_bf16 v[134:137], v[154:157], v[74:77], v[134:137]
	v_mfma_f32_16x16x32_bf16 v[130:133], v[162:165], v[74:77], v[130:133]
	v_mfma_f32_16x16x32_bf16 v[118:121], v[154:157], v[216:219], v[118:121]
	v_mfma_f32_16x16x32_bf16 v[114:117], v[162:165], v[216:219], v[114:117]
	v_mfma_f32_16x16x32_bf16 v[102:105], v[154:157], v[228:231], v[102:105]
	v_mfma_f32_16x16x32_bf16 v[98:101], v[162:165], v[228:231], v[98:101]
	v_mfma_f32_16x16x32_bf16 v[146:149], v[158:161], v[70:73], v[146:149]
	v_mfma_f32_16x16x32_bf16 v[150:153], v[174:177], v[70:73], v[150:153]
	v_mfma_f32_16x16x32_bf16 v[134:137], v[158:161], v[78:81], v[134:137]
	v_mfma_f32_16x16x32_bf16 v[130:133], v[174:177], v[78:81], v[130:133]
	v_mfma_f32_16x16x32_bf16 v[118:121], v[158:161], v[224:227], v[118:121]
	v_mfma_f32_16x16x32_bf16 v[114:117], v[174:177], v[224:227], v[114:117]
	v_mfma_f32_16x16x32_bf16 v[102:105], v[158:161], v[232:235], v[102:105]
	v_mfma_f32_16x16x32_bf16 v[98:101], v[174:177], v[232:235], v[98:101]
	s_setprio 0
	s_setprio 1
	v_mfma_f32_16x16x32_bf16 v[142:145], v[184:187], v[66:69], v[142:145]
	v_mfma_f32_16x16x32_bf16 v[66:69], v[192:195], v[66:69], v[138:141]
	v_mfma_f32_16x16x32_bf16 v[138:141], v[180:183], v[70:73], v[66:69]
	v_mfma_f32_16x16x32_bf16 v[66:69], v[184:187], v[74:77], v[126:129]
	v_mfma_f32_16x16x32_bf16 v[126:129], v[188:191], v[78:81], v[66:69]
	v_mfma_f32_16x16x32_bf16 v[66:69], v[192:195], v[74:77], v[122:125]
	v_mfma_f32_16x16x32_bf16 v[122:125], v[180:183], v[78:81], v[66:69]
	v_mfma_f32_16x16x32_bf16 v[66:69], v[184:187], v[216:219], v[110:113]
	v_mfma_f32_16x16x32_bf16 v[110:113], v[188:191], v[224:227], v[66:69]
	v_mfma_f32_16x16x32_bf16 v[66:69], v[192:195], v[216:219], v[106:109]
	v_mfma_f32_16x16x32_bf16 v[106:109], v[180:183], v[224:227], v[66:69]
	v_mfma_f32_16x16x32_bf16 v[66:69], v[184:187], v[228:231], v[94:97]
	v_mfma_f32_16x16x32_bf16 v[94:97], v[188:191], v[232:235], v[66:69]
	v_mfma_f32_16x16x32_bf16 v[66:69], v[192:195], v[228:231], v[90:93]
	v_mfma_f32_16x16x32_bf16 v[142:145], v[188:191], v[70:73], v[142:145]
	v_mfma_f32_16x16x32_bf16 v[90:93], v[180:183], v[232:235], v[66:69]
	s_barrier
; #define PG8_SB(B) __builtin_amdgcn_rcpf(1.f + expneg(B))
; #define PG8_SB(B) __builtin_amdgcn_rcpf(1.f + expneg(B))
; #define PG8_STAGE(bufoff, gbase, voff) do { _Pragma("unroll") for (int _i = 0; _i < 2; ++_i) \
;         __builtin_amdgcn_global_load_lds((const unsigned*)((const char*)(gbase) + (size_t)_i * qstep + (voff)[0]), (PG8_LAS unsigned*)(lds + (bufoff) + ldsw + _i * 8192), 16, 0, 0); } while (0)
; #define PG8_LDA(dst, b, h) do { _Pragma("unroll") for (int m = 0; m < 4; ++m) _Pragma("unroll") for (int k = 0; k < 2; ++k) dst[m][k] = *(const PG8_LAS bf16x8*)(lds + PG8_SA(b, h) + aoff + m * 2048 + k * 1024); } while (0)
; #define PG8_MMA(ai, bj, At, Bt) do { __builtin_amdgcn_s_setprio(1); _Pragma("unroll") for (int m = 0; m < 4; ++m) _Pragma("unroll") for (int n = 0; n < 2; ++n) _Pragma("unroll") for (int k = 0; k < 2; ++k) \
;         acc[ai][bj][m][n] = __builtin_amdgcn_mfma_f32_16x16x32_bf16(Bt[n][k], At[m][k], acc[ai][bj][m][n], 0, 0, 0); __builtin_amdgcn_s_setprio(0); } while (0)
; #define PG8_WAIT_V89() do { if constexpr (SLIVER) PG8_WAIT_V(9); else PG8_WAIT_V(8); } while (0)
; #define PG8_LDS_S(b) do { if constexpr (SLIVER) { Sf[0] = *(const PG8_LAS bf16x8*)(lds + STAGE_BYTES + (b) * 2048 + soff0); Sf[1] = *(const PG8_LAS bf16x8*)(lds + STAGE_BYTES + (b) * 2048 + (soff0 ^ 64)); } } while (0)
; #define PG8_WAIT_L(n) asm volatile("s_waitcnt lgkmcnt(" #n ")" ::: "memory")
; #define PG8_BAR __builtin_amdgcn_s_barrier()
; #define PG8_SCHED __builtin_amdgcn_sched_barrier(0)
; template <class Epi, class Sched, bool ALIGN_EPI = false, bool SP2 = false, bool SLIVER = false>
; __device__ __forceinline__ void gemm_phase(PG8_LAS unsigned char* lds, const Gemm g, const Sched& S, const Epi& E) {
;     ...
;             PG8_WAIT_V89(); PG8_WAIT_L(0); PG8_BAR; PG8_MMA(0, 0, At, B0); PG8_MMA(0, 1, At, B1); PG8_BAR; PG8_SCHED;
;             PG8_LDA(At, 0, 1); PG8_LDS_S(0); PG8_STAGE(PG8_SB(0, 0), b2, voffB); PG8_STAGE(PG8_SB(0, 1), b2 + hstep, voffB); PG8_STAGE(PG8_SA(0, 0), a2, voffA);
;             PG8_WAIT_V89(); PG8_WAIT_L(0); PG8_BAR; PG8_MMA(1, 0, At, B0); PG8_MMA(1, 1, At, B1); PG8_MMA_S(); PG8_BAR; PG8_SCHED;
	s_setprio 0
	s_add_i32 s68, 0, 0x20000
	v_lshl_add_u64 v[216:217], s[66:67], 0, v[198:199]
	s_add_i32 s66, s69, s18
	v_add_u32_e32 v74, s68, v221
	v_add_u32_e32 v75, s68, v222
	s_mov_b32 m0, s66
	ds_read_b128 v[66:69], v223 offset:16384
	ds_read_b128 v[70:73], v223 offset:17408
	ds_read_b128 v[224:227], v223 offset:18432
	ds_read_b128 v[228:231], v223 offset:19456
	ds_read_b128 v[232:235], v223 offset:20480
	ds_read_b128 v[240:243], v223 offset:21504
	ds_read_b128 v[244:247], v223 offset:22528
	ds_read_b128 v[248:251], v223 offset:23552
	ds_read_b128 v[166:169], v74
	ds_read_b128 v[170:173], v75
	global_load_lds_dwordx4 v[216:217], off
	v_lshl_add_u64 v[74:75], v[216:217], 0, s[64:65]
	s_add_i32 m0, s66, 0x2000
	s_add_i32 s13, s13, s18
	global_load_lds_dwordx4 v[74:75], off
	v_lshl_add_u64 v[74:75], v[216:217], 0, s[0:1]
	s_mov_b32 m0, s13
	v_lshl_add_u64 v[218:219], s[40:41], 0, v[196:197]
	global_load_lds_dwordx4 v[74:75], off
	v_lshl_add_u64 v[74:75], v[216:217], 0, s[74:75]
	s_add_i32 m0, s13, 0x2000
	s_nop 0
	global_load_lds_dwordx4 v[74:75], off
	s_mov_b32 m0, s19
	v_lshl_add_u64 v[74:75], v[218:219], 0, s[64:65]
	global_load_lds_dwordx4 v[218:219], off
	s_mov_b32 m0, s52
	s_nop 0
	global_load_lds_dwordx4 v[74:75], off
	s_waitcnt vmcnt(9)
	s_waitcnt lgkmcnt(0)
	s_setprio 1
	s_barrier
	v_mfma_f32_16x16x32_bf16 v[74:77], v[154:157], v[66:69], v[86:89]
	v_mfma_f32_16x16x32_bf16 v[78:81], v[162:165], v[66:69], v[82:85]
	v_mfma_f32_16x16x32_bf16 v[54:57], v[154:157], v[224:227], v[54:57]
	v_mfma_f32_16x16x32_bf16 v[50:53], v[162:165], v[224:227], v[50:53]
	v_mfma_f32_16x16x32_bf16 v[38:41], v[154:157], v[232:235], v[38:41]
	v_mfma_f32_16x16x32_bf16 v[34:37], v[162:165], v[232:235], v[34:37]
	v_mfma_f32_16x16x32_bf16 v[22:25], v[154:157], v[244:247], v[22:25]
	v_mfma_f32_16x16x32_bf16 v[18:21], v[162:165], v[244:247], v[18:21]
	v_mfma_f32_16x16x32_bf16 v[74:77], v[158:161], v[70:73], v[74:77]
	v_mfma_f32_16x16x32_bf16 v[78:81], v[174:177], v[70:73], v[78:81]
	v_mfma_f32_16x16x32_bf16 v[54:57], v[158:161], v[228:231], v[54:57]
	v_mfma_f32_16x16x32_bf16 v[50:53], v[174:177], v[228:231], v[50:53]
	v_mfma_f32_16x16x32_bf16 v[38:41], v[158:161], v[240:243], v[38:41]
	v_mfma_f32_16x16x32_bf16 v[34:37], v[174:177], v[240:243], v[34:37]
	v_mfma_f32_16x16x32_bf16 v[22:25], v[158:161], v[248:251], v[22:25]
	v_mfma_f32_16x16x32_bf16 v[18:21], v[174:177], v[248:251], v[18:21]
	s_setprio 0
	s_setprio 1
	v_mfma_f32_16x16x32_bf16 v[62:65], v[184:187], v[66:69], v[62:65]
	v_mfma_f32_16x16x32_bf16 v[58:61], v[192:195], v[66:69], v[58:61]
	v_mfma_f32_16x16x32_bf16 v[46:49], v[184:187], v[224:227], v[46:49]
	v_mfma_f32_16x16x32_bf16 v[42:45], v[192:195], v[224:227], v[42:45]
	v_mfma_f32_16x16x32_bf16 v[30:33], v[184:187], v[232:235], v[30:33]
	v_mfma_f32_16x16x32_bf16 v[26:29], v[192:195], v[232:235], v[26:29]
	v_mfma_f32_16x16x32_bf16 v[14:17], v[184:187], v[244:247], v[14:17]
	v_mfma_f32_16x16x32_bf16 v[10:13], v[192:195], v[244:247], v[10:13]
	v_mfma_f32_16x16x32_bf16 v[62:65], v[188:191], v[70:73], v[62:65]
	v_mfma_f32_16x16x32_bf16 v[58:61], v[180:183], v[70:73], v[58:61]
	v_mfma_f32_16x16x32_bf16 v[46:49], v[188:191], v[228:231], v[46:49]
	v_mfma_f32_16x16x32_bf16 v[42:45], v[180:183], v[228:231], v[42:45]
	v_mfma_f32_16x16x32_bf16 v[30:33], v[188:191], v[240:243], v[30:33]
	v_mfma_f32_16x16x32_bf16 v[26:29], v[180:183], v[240:243], v[26:29]
	v_mfma_f32_16x16x32_bf16 v[14:17], v[188:191], v[248:251], v[14:17]
	v_mfma_f32_16x16x32_bf16 v[10:13], v[180:183], v[248:251], v[10:13]
	s_setprio 0
	s_setprio 1
	v_cndmask_b32_e64 v66, 0, 1, s[82:83]
	v_cmp_ne_u32_e64 s[40:41], 1, v66
	s_andn2_b64 vcc, exec, s[82:83]
	s_mov_b64 s[94:95], -1
	s_cbranch_vccnz .LBB0_813
	v_mfma_f32_16x16x32_bf16 v[66:69], v[184:187], v[166:169], v[6:9]
	s_mov_b64 s[94:95], 0
	v_mfma_f32_16x16x32_bf16 v[70:73], v[192:195], v[166:169], v[2:5]
	v_mfma_f32_16x16x32_bf16 v[66:69], v[188:191], v[170:173], v[66:69]
	v_mfma_f32_16x16x32_bf16 v[70:73], v[180:183], v[170:173], v[70:73]

; #define PG8_SB(B) __builtin_amdgcn_rcpf(1.f + expneg(B))
; #define PG8_SB(B) __builtin_amdgcn_rcpf(1.f + expneg(B))
; #define PG8_STAGE(bufoff, gbase, voff) do { _Pragma("unroll") for (int _i = 0; _i < 2; ++_i) \
;         __builtin_amdgcn_global_load_lds((const unsigned*)((const char*)(gbase) + (size_t)_i * qstep + (voff)[0]), (PG8_LAS unsigned*)(lds + (bufoff) + ldsw + _i * 8192), 16, 0, 0); } while (0)
; #define PG8_LDA(dst, b, h) do { _Pragma("unroll") for (int m = 0; m < 4; ++m) _Pragma("unroll") for (int k = 0; k < 2; ++k) dst[m][k] = *(const PG8_LAS bf16x8*)(lds + PG8_SA(b, h) + aoff + m * 2048 + k * 1024); } while (0)
; #define PG8_LDB(dst, b, h) do { _Pragma("unroll") for (int n = 0; n < 2; ++n) _Pragma("unroll") for (int k = 0; k < 2; ++k) dst[n][k] = *(const PG8_LAS bf16x8*)(lds + PG8_SB(b, h) + boff + n * 2048 + k * 1024); } while (0)
; #define PG8_WAIT_L(n) asm volatile("s_waitcnt lgkmcnt(" #n ")" ::: "memory")
; template <class Epi, class Sched, bool ALIGN_EPI = false, bool SP2 = false, bool SLIVER = false>
; __device__ __forceinline__ void gemm_phase(PG8_LAS unsigned char* lds, const Gemm g, const Sched& S, const Epi& E) {
;     ...
;             const char* a2 = last ? nA : cA + (size_t)(t + 2) * kstep; const char* b2 = last ? nB : cB + (size_t)(t + 2) * kstep;
;             const char* a3 = a2 + kstep; const char* b3 = b2 + kstep;
;             const char* s1 = cS + (size_t)(t + 1) * kstep; const char* s2 = last ? nS : cS + (size_t)(t + 2) * kstep;
;             if (last && has_next) S.a_ready(nxt);
;             if constexpr (SP2) {
;             PG8_LDB(B0, 0, 0); PG8_LDB(B1, 0, 1); PG8_SCHED; PG8_LDA(At, 0, 0); PG8_STAGE(PG8_SA(1, 1), a1 + hstep, voffA); PG8_STAGE_S(1, s1);
;             PG8_WAIT_V89(); PG8_WAIT_L(0); PG8_BAR; PG8_MMA(0, 0, At, B0); PG8_MMA(0, 1, At, B1); PG8_BAR; PG8_SCHED;
;             PG8_LDA(At, 0, 1); PG8_LDS_S(0); PG8_STAGE(PG8_SB(0, 0), b2, voffB); PG8_STAGE(PG8_SB(0, 1), b2 + hstep, voffB); PG8_STAGE(PG8_SA(0, 0), a2, voffA);
;             PG8_WAIT_V89(); PG8_WAIT_L(0); PG8_BAR; PG8_MMA(1, 0, At, B0); PG8_MMA(1, 1, At, B1); PG8_MMA_S(); PG8_BAR; PG8_SCHED;
;             PG8_LDB(B0, 1, 0); PG8_LDB(B1, 1, 1); PG8_SCHED; PG8_LDA(At, 1, 0); PG8_STAGE(PG8_SA(0, 1), a2 + hstep, voffA); PG8_STAGE_S(0, s2);
;             PG8_WAIT_V89(); PG8_WAIT_L(0); PG8_BAR; PG8_MMA(0, 0, At, B0); PG8_MMA(0, 1, At, B1); PG8_BAR; PG8_SCHED;
.LBB0_815:
	s_add_u32 s13, s92, s62
	s_addc_u32 s66, s93, s63
	s_add_u32 s13, s13, 0x100
	s_addc_u32 s68, s66, 0
	s_and_b64 s[66:67], s[80:81], exec
	s_cselect_b32 s67, s89, s68
	s_cselect_b32 s66, s88, s13
	s_barrier
	s_setprio 0
	s_add_i32 s13, 0, 0x18000
	v_add_u32_e32 v2, s13, v220
	s_add_i32 s68, 0, 0x1c000
	ds_read_b128 v[154:157], v2
	ds_read_b128 v[158:161], v2 offset:1024
	ds_read_b128 v[162:165], v2 offset:2048
	ds_read_b128 v[174:177], v2 offset:3072
	v_add_u32_e32 v2, s68, v220
	ds_read_b128 v[184:187], v2
	ds_read_b128 v[188:191], v2 offset:1024
	ds_read_b128 v[192:195], v2 offset:2048
	ds_read_b128 v[180:183], v2 offset:3072
	s_mov_b32 m0, s53
	v_lshl_add_u64 v[166:167], v[218:219], 0, s[0:1]
	ds_read_b128 v[2:5], v223 offset:32768
	ds_read_b128 v[6:9], v223 offset:33792
	ds_read_b128 v[82:85], v223 offset:34816
	ds_read_b128 v[86:89], v223 offset:35840
	ds_read_b128 v[224:227], v223 offset:36864
	ds_read_b128 v[228:231], v223 offset:37888
	ds_read_b128 v[232:235], v223 offset:38912
	ds_read_b128 v[240:243], v223 offset:39936
	global_load_lds_dwordx4 v[166:167], off
	v_lshl_add_u64 v[166:167], v[218:219], 0, s[74:75]
	s_mov_b32 m0, s54
	s_nop 0
	global_load_lds_dwordx4 v[166:167], off
	v_lshl_add_u64 v[166:167], s[66:67], 0, v[200:201]
	s_mov_b32 m0, s55
	s_nop 0
	global_load_lds_dword v[166:167], off
	s_waitcnt vmcnt(9)
	s_waitcnt lgkmcnt(0)
	s_setprio 1
	s_barrier
	v_mfma_f32_16x16x32_bf16 v[146:149], v[154:157], v[2:5], v[146:149]
	v_mfma_f32_16x16x32_bf16 v[170:173], v[158:161], v[6:9], v[146:149]
	v_mfma_f32_16x16x32_bf16 v[146:149], v[162:165], v[2:5], v[150:153]
	v_mfma_f32_16x16x32_bf16 v[134:137], v[154:157], v[82:85], v[134:137]
	v_mfma_f32_16x16x32_bf16 v[130:133], v[162:165], v[82:85], v[130:133]
	v_mfma_f32_16x16x32_bf16 v[118:121], v[154:157], v[224:227], v[118:121]
	v_mfma_f32_16x16x32_bf16 v[114:117], v[162:165], v[224:227], v[114:117]
	v_mfma_f32_16x16x32_bf16 v[102:105], v[154:157], v[232:235], v[102:105]
	v_mfma_f32_16x16x32_bf16 v[98:101], v[162:165], v[232:235], v[98:101]
	v_mfma_f32_16x16x32_bf16 v[166:169], v[174:177], v[6:9], v[146:149]
	v_mfma_f32_16x16x32_bf16 v[134:137], v[158:161], v[86:89], v[134:137]
	v_mfma_f32_16x16x32_bf16 v[130:133], v[174:177], v[86:89], v[130:133]
	v_mfma_f32_16x16x32_bf16 v[118:121], v[158:161], v[228:231], v[118:121]
	v_mfma_f32_16x16x32_bf16 v[114:117], v[174:177], v[228:231], v[114:117]
	v_mfma_f32_16x16x32_bf16 v[102:105], v[158:161], v[240:243], v[102:105]
	v_mfma_f32_16x16x32_bf16 v[98:101], v[174:177], v[240:243], v[98:101]
	s_setprio 0
	s_setprio 1
	v_mfma_f32_16x16x32_bf16 v[142:145], v[184:187], v[2:5], v[142:145]
	v_mfma_f32_16x16x32_bf16 v[2:5], v[192:195], v[2:5], v[138:141]
	v_mfma_f32_16x16x32_bf16 v[138:141], v[180:183], v[6:9], v[2:5]
	v_mfma_f32_16x16x32_bf16 v[2:5], v[184:187], v[82:85], v[126:129]
	v_mfma_f32_16x16x32_bf16 v[126:129], v[188:191], v[86:89], v[2:5]
	v_mfma_f32_16x16x32_bf16 v[2:5], v[192:195], v[82:85], v[122:125]
	v_mfma_f32_16x16x32_bf16 v[122:125], v[180:183], v[86:89], v[2:5]
	v_mfma_f32_16x16x32_bf16 v[2:5], v[184:187], v[224:227], v[110:113]
	v_mfma_f32_16x16x32_bf16 v[110:113], v[188:191], v[228:231], v[2:5]
	v_mfma_f32_16x16x32_bf16 v[2:5], v[192:195], v[224:227], v[106:109]
	v_mfma_f32_16x16x32_bf16 v[106:109], v[180:183], v[228:231], v[2:5]
	v_mfma_f32_16x16x32_bf16 v[2:5], v[184:187], v[232:235], v[94:97]
	v_mfma_f32_16x16x32_bf16 v[94:97], v[188:191], v[240:243], v[2:5]
	v_mfma_f32_16x16x32_bf16 v[2:5], v[192:195], v[232:235], v[90:93]
	v_mfma_f32_16x16x32_bf16 v[142:145], v[188:191], v[6:9], v[142:145]
	v_mfma_f32_16x16x32_bf16 v[90:93], v[180:183], v[240:243], v[2:5]
	s_barrier
; #define PG8_SB(B) __builtin_amdgcn_rcpf(1.f + expneg(B))
; #define PG8_SB(B) __builtin_amdgcn_rcpf(1.f + expneg(B))
; #define PG8_STAGE(bufoff, gbase, voff) do { _Pragma("unroll") for (int _i = 0; _i < 2; ++_i) \
;         __builtin_amdgcn_global_load_lds((const unsigned*)((const char*)(gbase) + (size_t)_i * qstep + (voff)[0]), (PG8_LAS unsigned*)(lds + (bufoff) + ldsw + _i * 8192), 16, 0, 0); } while (0)
; #define PG8_LDA(dst, b, h) do { _Pragma("unroll") for (int m = 0; m < 4; ++m) _Pragma("unroll") for (int k = 0; k < 2; ++k) dst[m][k] = *(const PG8_LAS bf16x8*)(lds + PG8_SA(b, h) + aoff + m * 2048 + k * 1024); } while (0)
; #define PG8_MMA(ai, bj, At, Bt) do { __builtin_amdgcn_s_setprio(1); _Pragma("unroll") for (int m = 0; m < 4; ++m) _Pragma("unroll") for (int n = 0; n < 2; ++n) _Pragma("unroll") for (int k = 0; k < 2; ++k) \
;         acc[ai][bj][m][n] = __builtin_amdgcn_mfma_f32_16x16x32_bf16(Bt[n][k], At[m][k], acc[ai][bj][m][n], 0, 0, 0); __builtin_amdgcn_s_setprio(0); } while (0)
; #define PG8_WAIT_V89() do { if constexpr (SLIVER) PG8_WAIT_V(9); else PG8_WAIT_V(8); } while (0)
; #define PG8_LDS_S(b) do { if constexpr (SLIVER) { Sf[0] = *(const PG8_LAS bf16x8*)(lds + STAGE_BYTES + (b) * 2048 + soff0); Sf[1] = *(const PG8_LAS bf16x8*)(lds + STAGE_BYTES + (b) * 2048 + (soff0 ^ 64)); } } while (0)
; #define PG8_WAIT_L(n) asm volatile("s_waitcnt lgkmcnt(" #n ")" ::: "memory")
; #define PG8_BAR __builtin_amdgcn_s_barrier()
; #define PG8_SCHED __builtin_amdgcn_sched_barrier(0)
; template <class Epi, class Sched, bool ALIGN_EPI = false, bool SP2 = false, bool SLIVER = false>
; __device__ __forceinline__ void gemm_phase(PG8_LAS unsigned char* lds, const Gemm g, const Sched& S, const Epi& E) {
;     ...
;             PG8_LDA(At, 1, 1); PG8_LDS_S(1); PG8_STAGE(PG8_SB(1, 0), b3, voffB); PG8_STAGE(PG8_SB(1, 1), b3 + hstep, voffB); PG8_STAGE(PG8_SA(1, 0), a3, voffA);
;             PG8_WAIT_V89(); PG8_WAIT_L(0); PG8_BAR; PG8_MMA(1, 0, At, B0); PG8_MMA(1, 1, At, B1); PG8_MMA_S(); PG8_BAR; PG8_SCHED;
	s_setprio 0
	s_add_i32 s66, 0, 0x20800
	v_add_u32_e32 v82, s66, v221
	v_add_u32_e32 v83, s66, v222
	s_add_i32 s13, s13, s18
	ds_read_b128 v[2:5], v223 offset:49152
	ds_read_b128 v[6:9], v223 offset:50176
	ds_read_b128 v[224:227], v223 offset:51200
	ds_read_b128 v[228:231], v223 offset:52224
	ds_read_b128 v[232:235], v223 offset:53248
	ds_read_b128 v[240:243], v223 offset:54272
	ds_read_b128 v[244:247], v223 offset:55296
	ds_read_b128 v[248:251], v223 offset:56320
	ds_read_b128 v[146:149], v82
	ds_read_b128 v[150:153], v83
	v_lshl_add_u64 v[82:83], v[216:217], 0, s[26:27]
	s_mov_b32 m0, s13
	s_mov_b64 s[66:67], 0x210080
	global_load_lds_dwordx4 v[82:83], off
	v_lshl_add_u64 v[82:83], v[216:217], 0, s[60:61]
	s_add_i32 m0, s13, 0x2000
	s_add_i32 s13, s68, s18
	global_load_lds_dwordx4 v[82:83], off
	v_lshl_add_u64 v[82:83], v[216:217], 0, s[8:9]
	s_mov_b32 m0, s13
	s_nop 0
	global_load_lds_dwordx4 v[82:83], off
	v_lshl_add_u64 v[82:83], v[216:217], 0, s[66:67]
	s_add_i32 m0, s13, 0x2000
	s_nop 0
	global_load_lds_dwordx4 v[82:83], off
	v_lshl_add_u64 v[82:83], v[218:219], 0, s[26:27]
	s_mov_b32 m0, s10
	s_nop 0
	global_load_lds_dwordx4 v[82:83], off
	v_lshl_add_u64 v[82:83], v[218:219], 0, s[60:61]
	s_mov_b32 m0, s48
	s_nop 0
	global_load_lds_dwordx4 v[82:83], off
	s_waitcnt vmcnt(9)
	s_waitcnt lgkmcnt(0)
	s_setprio 1
	s_barrier
	v_mfma_f32_16x16x32_bf16 v[74:77], v[154:157], v[2:5], v[74:77]
	v_mfma_f32_16x16x32_bf16 v[86:89], v[158:161], v[6:9], v[74:77]
	v_mfma_f32_16x16x32_bf16 v[74:77], v[162:165], v[2:5], v[78:81]
	v_mfma_f32_16x16x32_bf16 v[54:57], v[154:157], v[224:227], v[54:57]
	v_mfma_f32_16x16x32_bf16 v[50:53], v[162:165], v[224:227], v[50:53]
	v_mfma_f32_16x16x32_bf16 v[38:41], v[154:157], v[232:235], v[38:41]
	v_mfma_f32_16x16x32_bf16 v[34:37], v[162:165], v[232:235], v[34:37]
	v_mfma_f32_16x16x32_bf16 v[22:25], v[154:157], v[244:247], v[22:25]
	v_mfma_f32_16x16x32_bf16 v[18:21], v[162:165], v[244:247], v[18:21]
	v_mfma_f32_16x16x32_bf16 v[82:85], v[174:177], v[6:9], v[74:77]
	v_mfma_f32_16x16x32_bf16 v[54:57], v[158:161], v[228:231], v[54:57]
	v_mfma_f32_16x16x32_bf16 v[50:53], v[174:177], v[228:231], v[50:53]
	v_mfma_f32_16x16x32_bf16 v[38:41], v[158:161], v[240:243], v[38:41]
	v_mfma_f32_16x16x32_bf16 v[34:37], v[174:177], v[240:243], v[34:37]
	v_mfma_f32_16x16x32_bf16 v[22:25], v[158:161], v[248:251], v[22:25]
	v_mfma_f32_16x16x32_bf16 v[18:21], v[174:177], v[248:251], v[18:21]
	s_setprio 0
	s_setprio 1
	v_mfma_f32_16x16x32_bf16 v[62:65], v[184:187], v[2:5], v[62:65]
	v_mfma_f32_16x16x32_bf16 v[2:5], v[192:195], v[2:5], v[58:61]
	v_mfma_f32_16x16x32_bf16 v[58:61], v[180:183], v[6:9], v[2:5]
	v_mfma_f32_16x16x32_bf16 v[2:5], v[184:187], v[224:227], v[46:49]
	v_mfma_f32_16x16x32_bf16 v[46:49], v[188:191], v[228:231], v[2:5]
	v_mfma_f32_16x16x32_bf16 v[2:5], v[192:195], v[224:227], v[42:45]
	v_mfma_f32_16x16x32_bf16 v[42:45], v[180:183], v[228:231], v[2:5]
	v_mfma_f32_16x16x32_bf16 v[2:5], v[184:187], v[232:235], v[30:33]
	v_mfma_f32_16x16x32_bf16 v[30:33], v[188:191], v[240:243], v[2:5]
	v_mfma_f32_16x16x32_bf16 v[2:5], v[192:195], v[232:235], v[26:29]
	v_mfma_f32_16x16x32_bf16 v[26:29], v[180:183], v[240:243], v[2:5]
	v_mfma_f32_16x16x32_bf16 v[2:5], v[184:187], v[244:247], v[14:17]
	v_mfma_f32_16x16x32_bf16 v[14:17], v[188:191], v[248:251], v[2:5]
	v_mfma_f32_16x16x32_bf16 v[2:5], v[192:195], v[244:247], v[10:13]
	v_mfma_f32_16x16x32_bf16 v[62:65], v[188:191], v[6:9], v[62:65]
	v_mfma_f32_16x16x32_bf16 v[10:13], v[180:183], v[248:251], v[2:5]
	s_setprio 0
	s_setprio 1
	s_and_b64 vcc, exec, s[40:41]
	s_mov_b64 s[40:41], -1
	s_cbranch_vccnz .LBB0_817
	v_mfma_f32_16x16x32_bf16 v[2:5], v[184:187], v[146:149], v[66:69]
	s_mov_b64 s[40:41], 0
	v_mfma_f32_16x16x32_bf16 v[6:9], v[188:191], v[150:153], v[2:5]
	v_mfma_f32_16x16x32_bf16 v[2:5], v[192:195], v[146:149], v[70:73]
	v_mfma_f32_16x16x32_bf16 v[2:5], v[180:183], v[150:153], v[2:5]

; #define PG8_STAGE(bufoff, gbase, voff) do { _Pragma("unroll") for (int _i = 0; _i < 2; ++_i) \
;         __builtin_amdgcn_global_load_lds((const unsigned*)((const char*)(gbase) + (size_t)_i * qstep + (voff)[0]), (PG8_LAS unsigned*)(lds + (bufoff) + ldsw + _i * 8192), 16, 0, 0); } while (0)
; #define PG8_LDA(dst, b, h) do { _Pragma("unroll") for (int m = 0; m < 4; ++m) _Pragma("unroll") for (int k = 0; k < 2; ++k) dst[m][k] = *(const PG8_LAS bf16x8*)(lds + PG8_SA(b, h) + aoff + m * 2048 + k * 1024); } while (0)
; #define PG8_LDB(dst, b, h) do { _Pragma("unroll") for (int n = 0; n < 2; ++n) _Pragma("unroll") for (int k = 0; k < 2; ++k) dst[n][k] = *(const PG8_LAS bf16x8*)(lds + PG8_SB(b, h) + boff + n * 2048 + k * 1024); } while (0)
; #define PG8_MMA(ai, bj, At, Bt) do { __builtin_amdgcn_s_setprio(1); _Pragma("unroll") for (int m = 0; m < 4; ++m) _Pragma("unroll") for (int n = 0; n < 2; ++n) _Pragma("unroll") for (int k = 0; k < 2; ++k) \
;         acc[ai][bj][m][n] = __builtin_amdgcn_mfma_f32_16x16x32_bf16(Bt[n][k], At[m][k], acc[ai][bj][m][n], 0, 0, 0); __builtin_amdgcn_s_setprio(0); } while (0)
; #define PG8_WAIT_V89() do { if constexpr (SLIVER) PG8_WAIT_V(9); else PG8_WAIT_V(8); } while (0)
; #define PG8_WAIT_L(n) asm volatile("s_waitcnt lgkmcnt(" #n ")" ::: "memory")
; #define PG8_BAR __builtin_amdgcn_s_barrier()
; template <class Epi, class Sched, bool ALIGN_EPI = false, bool SP2 = false, bool SLIVER = false>
; __device__ __forceinline__ void gemm_phase(PG8_LAS unsigned char* lds, const Gemm g, const Sched& S, const Epi& E) {
;     ...
;         for (int t = 0; t < nt; t += 2) {
;             const bool last = (t == nt - 2);
;             const char* a1 = cA + (size_t)(t + 1) * kstep;
;             const char* a2 = last ? nA : cA + (size_t)(t + 2) * kstep; const char* b2 = last ? nB : cB + (size_t)(t + 2) * kstep;
;             const char* a3 = a2 + kstep; const char* b3 = b2 + kstep;
;             const char* s1 = cS + (size_t)(t + 1) * kstep; const char* s2 = last ? nS : cS + (size_t)(t + 2) * kstep;
;             if (last && has_next) S.a_ready(nxt);
;             if constexpr (SP2) {
;             PG8_LDB(B0, 0, 0); PG8_LDB(B1, 0, 1); PG8_SCHED; PG8_LDA(At, 0, 0); PG8_STAGE(PG8_SA(1, 1), a1 + hstep, voffA); PG8_STAGE_S(1, s1);
;             PG8_WAIT_V89(); PG8_WAIT_L(0); PG8_BAR; PG8_MMA(0, 0, At, B0); PG8_MMA(0, 1, At, B1); PG8_BAR; PG8_SCHED;
.LBB0_933:
	s_add_i32 s67, s67, 2
	s_barrier
	s_setprio 0
	s_add_u32 s62, s62, 0x100
	s_addc_u32 s63, s63, 0
	s_cmp_ge_u32 s67, s2
	s_cbranch_scc1 .LBB0_944
.LBB0_934:
	s_cmp_eq_u32 s66, s62
	s_cselect_b64 s[80:81], -1, 0
	s_add_u32 s12, s42, s62
	s_addc_u32 s13, s43, s63
	s_add_u32 s40, s12, 0x100
	s_addc_u32 s41, s13, 0
	s_and_b64 s[12:13], s[80:81], exec
	s_cselect_b32 s41, s95, s41
	s_cselect_b32 s40, s94, s40
	s_add_u32 s68, s17, s62
	s_addc_u32 s69, s45, s63
	s_add_i32 s76, 0, 0x10000
	s_and_b64 s[12:13], s[80:81], exec
	v_add_u32_e32 v138, s76, v212
	s_cselect_b32 s13, s97, s69
	s_cselect_b32 s12, s96, s68
	s_add_i32 s68, 0, 0x14000
	ds_read_b128 v[146:149], v138
	ds_read_b128 v[150:153], v138 offset:1024
	ds_read_b128 v[154:157], v138 offset:2048
	ds_read_b128 v[158:161], v138 offset:3072
	v_add_u32_e32 v138, s68, v212
	ds_read_b128 v[166:169], v138
	ds_read_b128 v[170:173], v138 offset:1024
	ds_read_b128 v[174:177], v138 offset:2048
	ds_read_b128 v[162:165], v138 offset:3072
	v_lshl_add_u64 v[202:203], v[198:199], 0, s[62:63]
	s_mov_b64 vcc, 0x90080
	v_lshl_add_u64 v[208:209], v[202:203], 0, vcc
	s_add_i32 m0, s93, 0xc000
	s_mov_b64 vcc, 0xd8080
	ds_read_b128 v[138:141], v215
	ds_read_b128 v[142:145], v215 offset:1024
	ds_read_b128 v[180:183], v215 offset:2048
	ds_read_b128 v[184:187], v215 offset:3072
	ds_read_b128 v[216:219], v215 offset:4096
	ds_read_b128 v[220:223], v215 offset:5120
	ds_read_b128 v[224:227], v215 offset:6144
	ds_read_b128 v[228:231], v215 offset:7168
	global_load_lds_dwordx4 v[208:209], off
	v_lshl_add_u64 v[202:203], v[202:203], 0, vcc
	s_add_i32 m0, s93, 0xe000
	s_nop 0
	global_load_lds_dwordx4 v[202:203], off
	v_lshl_add_u64 v[202:203], v[200:201], 0, s[62:63]
	s_add_i32 m0, s50, 0x20800
	s_nop 0
	global_load_lds_dword v[202:203], off
	s_waitcnt vmcnt(9)
	s_waitcnt lgkmcnt(0)
	s_setprio 1
	s_barrier
	v_mfma_f32_16x16x32_bf16 v[134:137], v[146:149], v[138:141], v[134:137]
	v_mfma_f32_16x16x32_bf16 v[130:133], v[154:157], v[138:141], v[130:133]
	v_mfma_f32_16x16x32_bf16 v[126:129], v[146:149], v[180:183], v[126:129]
	v_mfma_f32_16x16x32_bf16 v[122:125], v[154:157], v[180:183], v[122:125]
	v_mfma_f32_16x16x32_bf16 v[114:117], v[146:149], v[216:219], v[114:117]
	v_mfma_f32_16x16x32_bf16 v[106:109], v[154:157], v[216:219], v[106:109]
	v_mfma_f32_16x16x32_bf16 v[98:101], v[146:149], v[224:227], v[98:101]
	v_mfma_f32_16x16x32_bf16 v[90:93], v[154:157], v[224:227], v[90:93]
	v_mfma_f32_16x16x32_bf16 v[134:137], v[150:153], v[142:145], v[134:137]
	v_mfma_f32_16x16x32_bf16 v[130:133], v[158:161], v[142:145], v[130:133]
	v_mfma_f32_16x16x32_bf16 v[126:129], v[150:153], v[184:187], v[126:129]
	v_mfma_f32_16x16x32_bf16 v[122:125], v[158:161], v[184:187], v[122:125]
	v_mfma_f32_16x16x32_bf16 v[114:117], v[150:153], v[220:223], v[114:117]
	v_mfma_f32_16x16x32_bf16 v[106:109], v[158:161], v[220:223], v[106:109]
	v_mfma_f32_16x16x32_bf16 v[98:101], v[150:153], v[228:231], v[98:101]
	v_mfma_f32_16x16x32_bf16 v[90:93], v[158:161], v[228:231], v[90:93]
	s_setprio 0
	s_setprio 1
	v_mfma_f32_16x16x32_bf16 v[118:121], v[166:169], v[138:141], v[118:121]
	v_mfma_f32_16x16x32_bf16 v[110:113], v[174:177], v[138:141], v[110:113]
	v_mfma_f32_16x16x32_bf16 v[102:105], v[166:169], v[180:183], v[102:105]
	v_mfma_f32_16x16x32_bf16 v[94:97], v[174:177], v[180:183], v[94:97]
	v_mfma_f32_16x16x32_bf16 v[86:89], v[166:169], v[216:219], v[86:89]
	v_mfma_f32_16x16x32_bf16 v[82:85], v[174:177], v[216:219], v[82:85]
	v_mfma_f32_16x16x32_bf16 v[78:81], v[166:169], v[224:227], v[78:81]
	v_mfma_f32_16x16x32_bf16 v[74:77], v[174:177], v[224:227], v[74:77]
	v_mfma_f32_16x16x32_bf16 v[118:121], v[170:173], v[142:145], v[118:121]
	v_mfma_f32_16x16x32_bf16 v[110:113], v[162:165], v[142:145], v[110:113]
	v_mfma_f32_16x16x32_bf16 v[102:105], v[170:173], v[184:187], v[102:105]
	v_mfma_f32_16x16x32_bf16 v[94:97], v[162:165], v[184:187], v[94:97]
	v_mfma_f32_16x16x32_bf16 v[86:89], v[170:173], v[220:223], v[86:89]
	v_mfma_f32_16x16x32_bf16 v[82:85], v[162:165], v[220:223], v[82:85]
	v_mfma_f32_16x16x32_bf16 v[78:81], v[170:173], v[228:231], v[78:81]
	v_mfma_f32_16x16x32_bf16 v[74:77], v[162:165], v[228:231], v[74:77]
	s_barrier
; #define PG8_SB(B) __builtin_amdgcn_rcpf(1.f + expneg(B))
; #define PG8_SB(B) __builtin_amdgcn_rcpf(1.f + expneg(B))
; #define PG8_STAGE(bufoff, gbase, voff) do { _Pragma("unroll") for (int _i = 0; _i < 2; ++_i) \
;         __builtin_amdgcn_global_load_lds((const unsigned*)((const char*)(gbase) + (size_t)_i * qstep + (voff)[0]), (PG8_LAS unsigned*)(lds + (bufoff) + ldsw + _i * 8192), 16, 0, 0); } while (0)
; #define PG8_LDA(dst, b, h) do { _Pragma("unroll") for (int m = 0; m < 4; ++m) _Pragma("unroll") for (int k = 0; k < 2; ++k) dst[m][k] = *(const PG8_LAS bf16x8*)(lds + PG8_SA(b, h) + aoff + m * 2048 + k * 1024); } while (0)
; #define PG8_MMA(ai, bj, At, Bt) do { __builtin_amdgcn_s_setprio(1); _Pragma("unroll") for (int m = 0; m < 4; ++m) _Pragma("unroll") for (int n = 0; n < 2; ++n) _Pragma("unroll") for (int k = 0; k < 2; ++k) \
;         acc[ai][bj][m][n] = __builtin_amdgcn_mfma_f32_16x16x32_bf16(Bt[n][k], At[m][k], acc[ai][bj][m][n], 0, 0, 0); __builtin_amdgcn_s_setprio(0); } while (0)
; #define PG8_WAIT_V89() do { if constexpr (SLIVER) PG8_WAIT_V(9); else PG8_WAIT_V(8); } while (0)
; #define PG8_LDS_S(b) do { if constexpr (SLIVER) { Sf[0] = *(const PG8_LAS bf16x8*)(lds + STAGE_BYTES + (b) * 2048 + soff0); Sf[1] = *(const PG8_LAS bf16x8*)(lds + STAGE_BYTES + (b) * 2048 + (soff0 ^ 64)); } } while (0)
; #define PG8_WAIT_L(n) asm volatile("s_waitcnt lgkmcnt(" #n ")" ::: "memory")
; #define PG8_BAR __builtin_amdgcn_s_barrier()
; #define PG8_SCHED __builtin_amdgcn_sched_barrier(0)
; template <class Epi, class Sched, bool ALIGN_EPI = false, bool SP2 = false, bool SLIVER = false>
; __device__ __forceinline__ void gemm_phase(PG8_LAS unsigned char* lds, const Gemm g, const Sched& S, const Epi& E) {
;     ...
;             PG8_WAIT_V89(); PG8_WAIT_L(0); PG8_BAR; PG8_MMA(0, 0, At, B0); PG8_MMA(0, 1, At, B1); PG8_BAR; PG8_SCHED;
;             PG8_LDA(At, 0, 1); PG8_LDS_S(0); PG8_STAGE(PG8_SB(0, 0), b2, voffB); PG8_STAGE(PG8_SB(0, 1), b2 + hstep, voffB); PG8_STAGE(PG8_SA(0, 0), a2, voffA);
;             PG8_WAIT_V89(); PG8_WAIT_L(0); PG8_BAR; PG8_MMA(1, 0, At, B0); PG8_MMA(1, 1, At, B1); PG8_MMA_S(); PG8_BAR; PG8_SCHED;
	s_setprio 0
	s_add_i32 s69, 0, 0x20000
	v_lshl_add_u64 v[202:203], s[12:13], 0, v[190:191]
	s_add_i32 s12, s76, s92
	v_add_u32_e32 v178, s69, v213
	v_add_u32_e32 v184, s69, v214
	s_mov_b32 m0, s12
	ds_read_b128 v[138:141], v215 offset:16384
	ds_read_b128 v[142:145], v215 offset:17408
	ds_read_b128 v[216:219], v215 offset:18432
	ds_read_b128 v[220:223], v215 offset:19456
	ds_read_b128 v[224:227], v215 offset:20480
	ds_read_b128 v[228:231], v215 offset:21504
	ds_read_b128 v[232:235], v215 offset:22528
	ds_read_b128 v[240:243], v215 offset:23552
	ds_read_b128 v[180:183], v178
	ds_read_b128 v[184:187], v184
	global_load_lds_dwordx4 v[202:203], off
	v_lshl_add_u64 v[208:209], v[202:203], 0, s[70:71]
	s_add_i32 m0, s12, 0x2000
	s_add_i32 s12, s68, s92
	global_load_lds_dwordx4 v[208:209], off
	v_lshl_add_u64 v[208:209], v[202:203], 0, s[46:47]
	s_mov_b32 m0, s12
	v_lshl_add_u64 v[210:211], s[40:41], 0, v[188:189]
	global_load_lds_dwordx4 v[208:209], off
	v_lshl_add_u64 v[208:209], v[202:203], 0, s[6:7]
	s_add_i32 m0, s12, 0x2000
	s_nop 0
	global_load_lds_dwordx4 v[208:209], off
	s_mov_b32 m0, s93
	v_lshl_add_u64 v[208:209], v[210:211], 0, s[70:71]
	global_load_lds_dwordx4 v[210:211], off
	s_mov_b32 m0, s48
	s_nop 0
	global_load_lds_dwordx4 v[208:209], off
	s_waitcnt vmcnt(9)
	s_waitcnt lgkmcnt(0)
	s_setprio 1
	s_barrier
	v_mfma_f32_16x16x32_bf16 v[70:73], v[146:149], v[138:141], v[70:73]
	v_mfma_f32_16x16x32_bf16 v[66:69], v[154:157], v[138:141], v[66:69]
	v_mfma_f32_16x16x32_bf16 v[62:65], v[146:149], v[216:219], v[62:65]
	v_mfma_f32_16x16x32_bf16 v[58:61], v[154:157], v[216:219], v[58:61]
	v_mfma_f32_16x16x32_bf16 v[50:53], v[146:149], v[224:227], v[50:53]
	v_mfma_f32_16x16x32_bf16 v[42:45], v[154:157], v[224:227], v[42:45]
	v_mfma_f32_16x16x32_bf16 v[34:37], v[146:149], v[232:235], v[34:37]
	v_mfma_f32_16x16x32_bf16 v[26:29], v[154:157], v[232:235], v[26:29]
	v_mfma_f32_16x16x32_bf16 v[70:73], v[150:153], v[142:145], v[70:73]
	v_mfma_f32_16x16x32_bf16 v[66:69], v[158:161], v[142:145], v[66:69]
	v_mfma_f32_16x16x32_bf16 v[62:65], v[150:153], v[220:223], v[62:65]
	v_mfma_f32_16x16x32_bf16 v[58:61], v[158:161], v[220:223], v[58:61]
	v_mfma_f32_16x16x32_bf16 v[50:53], v[150:153], v[228:231], v[50:53]
	v_mfma_f32_16x16x32_bf16 v[42:45], v[158:161], v[228:231], v[42:45]
	v_mfma_f32_16x16x32_bf16 v[34:37], v[150:153], v[240:243], v[34:37]
	v_mfma_f32_16x16x32_bf16 v[26:29], v[158:161], v[240:243], v[26:29]
	s_setprio 0
	s_setprio 1
	v_mfma_f32_16x16x32_bf16 v[54:57], v[166:169], v[138:141], v[54:57]
	v_mfma_f32_16x16x32_bf16 v[46:49], v[174:177], v[138:141], v[46:49]
	v_mfma_f32_16x16x32_bf16 v[38:41], v[166:169], v[216:219], v[38:41]
	v_mfma_f32_16x16x32_bf16 v[30:33], v[174:177], v[216:219], v[30:33]
	v_mfma_f32_16x16x32_bf16 v[22:25], v[166:169], v[224:227], v[22:25]
	v_mfma_f32_16x16x32_bf16 v[18:21], v[174:177], v[224:227], v[18:21]
	v_mfma_f32_16x16x32_bf16 v[14:17], v[166:169], v[232:235], v[14:17]
	v_mfma_f32_16x16x32_bf16 v[10:13], v[174:177], v[232:235], v[10:13]
	v_mfma_f32_16x16x32_bf16 v[54:57], v[170:173], v[142:145], v[54:57]
	v_mfma_f32_16x16x32_bf16 v[46:49], v[162:165], v[142:145], v[46:49]
	v_mfma_f32_16x16x32_bf16 v[38:41], v[170:173], v[220:223], v[38:41]
	v_mfma_f32_16x16x32_bf16 v[30:33], v[162:165], v[220:223], v[30:33]
	v_mfma_f32_16x16x32_bf16 v[22:25], v[170:173], v[228:231], v[22:25]
	v_mfma_f32_16x16x32_bf16 v[18:21], v[162:165], v[228:231], v[18:21]
	v_mfma_f32_16x16x32_bf16 v[14:17], v[170:173], v[240:243], v[14:17]
	v_mfma_f32_16x16x32_bf16 v[10:13], v[162:165], v[240:243], v[10:13]
	s_setprio 0
	s_setprio 1
	v_cndmask_b32_e64 v138, 0, 1, s[90:91]
	v_cmp_ne_u32_e64 s[40:41], 1, v138
	s_andn2_b64 vcc, exec, s[90:91]
	s_mov_b64 s[12:13], -1
	s_cbranch_vccnz .LBB0_936
	v_mfma_f32_16x16x32_bf16 v[138:141], v[166:169], v[180:183], v[6:9]
	s_mov_b64 s[12:13], 0
	v_mfma_f32_16x16x32_bf16 v[142:145], v[174:177], v[180:183], v[2:5]
	v_mfma_f32_16x16x32_bf16 v[138:141], v[170:173], v[184:187], v[138:141]
	v_mfma_f32_16x16x32_bf16 v[142:145], v[162:165], v[184:187], v[142:145]

; #define PG8_SB(B) __builtin_amdgcn_rcpf(1.f + expneg(B))
; #define PG8_SB(B) __builtin_amdgcn_rcpf(1.f + expneg(B))
; #define PG8_STAGE(bufoff, gbase, voff) do { _Pragma("unroll") for (int _i = 0; _i < 2; ++_i) \
;         __builtin_amdgcn_global_load_lds((const unsigned*)((const char*)(gbase) + (size_t)_i * qstep + (voff)[0]), (PG8_LAS unsigned*)(lds + (bufoff) + ldsw + _i * 8192), 16, 0, 0); } while (0)
; #define PG8_LDA(dst, b, h) do { _Pragma("unroll") for (int m = 0; m < 4; ++m) _Pragma("unroll") for (int k = 0; k < 2; ++k) dst[m][k] = *(const PG8_LAS bf16x8*)(lds + PG8_SA(b, h) + aoff + m * 2048 + k * 1024); } while (0)
; #define PG8_LDB(dst, b, h) do { _Pragma("unroll") for (int n = 0; n < 2; ++n) _Pragma("unroll") for (int k = 0; k < 2; ++k) dst[n][k] = *(const PG8_LAS bf16x8*)(lds + PG8_SB(b, h) + boff + n * 2048 + k * 1024); } while (0)
; #define PG8_WAIT_L(n) asm volatile("s_waitcnt lgkmcnt(" #n ")" ::: "memory")
; template <class Epi, class Sched, bool ALIGN_EPI = false, bool SP2 = false, bool SLIVER = false>
; __device__ __forceinline__ void gemm_phase(PG8_LAS unsigned char* lds, const Gemm g, const Sched& S, const Epi& E) {
;     ...
;             const char* a2 = last ? nA : cA + (size_t)(t + 2) * kstep; const char* b2 = last ? nB : cB + (size_t)(t + 2) * kstep;
;             const char* a3 = a2 + kstep; const char* b3 = b2 + kstep;
;             const char* s1 = cS + (size_t)(t + 1) * kstep; const char* s2 = last ? nS : cS + (size_t)(t + 2) * kstep;
;             if (last && has_next) S.a_ready(nxt);
;             if constexpr (SP2) {
;             PG8_LDB(B0, 0, 0); PG8_LDB(B1, 0, 1); PG8_SCHED; PG8_LDA(At, 0, 0); PG8_STAGE(PG8_SA(1, 1), a1 + hstep, voffA); PG8_STAGE_S(1, s1);
;             PG8_WAIT_V89(); PG8_WAIT_L(0); PG8_BAR; PG8_MMA(0, 0, At, B0); PG8_MMA(0, 1, At, B1); PG8_BAR; PG8_SCHED;
;             PG8_LDA(At, 0, 1); PG8_LDS_S(0); PG8_STAGE(PG8_SB(0, 0), b2, voffB); PG8_STAGE(PG8_SB(0, 1), b2 + hstep, voffB); PG8_STAGE(PG8_SA(0, 0), a2, voffA);
;             PG8_WAIT_V89(); PG8_WAIT_L(0); PG8_BAR; PG8_MMA(1, 0, At, B0); PG8_MMA(1, 1, At, B1); PG8_MMA_S(); PG8_BAR; PG8_SCHED;
;             PG8_LDB(B0, 1, 0); PG8_LDB(B1, 1, 1); PG8_SCHED; PG8_LDA(At, 1, 0); PG8_STAGE(PG8_SA(0, 1), a2 + hstep, voffA); PG8_STAGE_S(0, s2);
;             PG8_WAIT_V89(); PG8_WAIT_L(0); PG8_BAR; PG8_MMA(0, 0, At, B0); PG8_MMA(0, 1, At, B1); PG8_BAR; PG8_SCHED;
.LBB0_938:
	s_add_u32 s12, s54, s62
	s_addc_u32 s13, s55, s63
	s_add_u32 s68, s12, 0x100
	s_addc_u32 s69, s13, 0
	s_and_b64 s[12:13], s[80:81], exec
	s_cselect_b32 s13, s19, s69
	s_cselect_b32 s12, s18, s68
	s_barrier
	s_setprio 0
	s_add_i32 s68, 0, 0x18000
	v_add_u32_e32 v2, s68, v212
	s_add_i32 s69, 0, 0x1c000
	ds_read_b128 v[146:149], v2
	ds_read_b128 v[150:153], v2 offset:1024
	ds_read_b128 v[154:157], v2 offset:2048
	ds_read_b128 v[158:161], v2 offset:3072
	v_add_u32_e32 v2, s69, v212
	ds_read_b128 v[166:169], v2
	ds_read_b128 v[170:173], v2 offset:1024
	ds_read_b128 v[174:177], v2 offset:2048
	ds_read_b128 v[162:165], v2 offset:3072
	s_mov_b32 m0, s49
	v_lshl_add_u64 v[208:209], v[210:211], 0, s[46:47]
	ds_read_b128 v[2:5], v215 offset:32768
	ds_read_b128 v[6:9], v215 offset:33792
	ds_read_b128 v[180:183], v215 offset:34816
	ds_read_b128 v[184:187], v215 offset:35840
	ds_read_b128 v[216:219], v215 offset:36864
	ds_read_b128 v[220:223], v215 offset:37888
	ds_read_b128 v[224:227], v215 offset:38912
	ds_read_b128 v[228:231], v215 offset:39936
	global_load_lds_dwordx4 v[208:209], off
	v_lshl_add_u64 v[208:209], v[210:211], 0, s[6:7]
	s_mov_b32 m0, s88
	s_nop 0
	global_load_lds_dwordx4 v[208:209], off
	v_lshl_add_u64 v[208:209], s[12:13], 0, v[192:193]
	s_mov_b32 m0, s89
	s_nop 0
	global_load_lds_dword v[208:209], off
	s_waitcnt vmcnt(9)
	s_waitcnt lgkmcnt(0)
	s_setprio 1
	s_barrier
	v_mfma_f32_16x16x32_bf16 v[134:137], v[146:149], v[2:5], v[134:137]
	v_mfma_f32_16x16x32_bf16 v[130:133], v[154:157], v[2:5], v[130:133]
	v_mfma_f32_16x16x32_bf16 v[126:129], v[146:149], v[180:183], v[126:129]
	v_mfma_f32_16x16x32_bf16 v[122:125], v[154:157], v[180:183], v[122:125]
	v_mfma_f32_16x16x32_bf16 v[114:117], v[146:149], v[216:219], v[114:117]
	v_mfma_f32_16x16x32_bf16 v[106:109], v[154:157], v[216:219], v[106:109]
	v_mfma_f32_16x16x32_bf16 v[98:101], v[146:149], v[224:227], v[98:101]
	v_mfma_f32_16x16x32_bf16 v[90:93], v[154:157], v[224:227], v[90:93]
	v_mfma_f32_16x16x32_bf16 v[134:137], v[150:153], v[6:9], v[134:137]
	v_mfma_f32_16x16x32_bf16 v[130:133], v[158:161], v[6:9], v[130:133]
	v_mfma_f32_16x16x32_bf16 v[126:129], v[150:153], v[184:187], v[126:129]
	v_mfma_f32_16x16x32_bf16 v[122:125], v[158:161], v[184:187], v[122:125]
	v_mfma_f32_16x16x32_bf16 v[114:117], v[150:153], v[220:223], v[114:117]
	v_mfma_f32_16x16x32_bf16 v[106:109], v[158:161], v[220:223], v[106:109]
	v_mfma_f32_16x16x32_bf16 v[98:101], v[150:153], v[228:231], v[98:101]
	v_mfma_f32_16x16x32_bf16 v[90:93], v[158:161], v[228:231], v[90:93]
	s_setprio 0
	s_setprio 1
	v_mfma_f32_16x16x32_bf16 v[118:121], v[166:169], v[2:5], v[118:121]
	v_mfma_f32_16x16x32_bf16 v[2:5], v[174:177], v[2:5], v[110:113]
	v_mfma_f32_16x16x32_bf16 v[110:113], v[162:165], v[6:9], v[2:5]
	v_mfma_f32_16x16x32_bf16 v[2:5], v[166:169], v[180:183], v[102:105]
	v_mfma_f32_16x16x32_bf16 v[102:105], v[170:173], v[184:187], v[2:5]
	v_mfma_f32_16x16x32_bf16 v[2:5], v[174:177], v[180:183], v[94:97]
	v_mfma_f32_16x16x32_bf16 v[94:97], v[162:165], v[184:187], v[2:5]
	v_mfma_f32_16x16x32_bf16 v[2:5], v[166:169], v[216:219], v[86:89]
	v_mfma_f32_16x16x32_bf16 v[86:89], v[170:173], v[220:223], v[2:5]
	v_mfma_f32_16x16x32_bf16 v[2:5], v[174:177], v[216:219], v[82:85]
	v_mfma_f32_16x16x32_bf16 v[82:85], v[162:165], v[220:223], v[2:5]
	v_mfma_f32_16x16x32_bf16 v[2:5], v[166:169], v[224:227], v[78:81]
	v_mfma_f32_16x16x32_bf16 v[78:81], v[170:173], v[228:231], v[2:5]
	v_mfma_f32_16x16x32_bf16 v[2:5], v[174:177], v[224:227], v[74:77]
	v_mfma_f32_16x16x32_bf16 v[118:121], v[170:173], v[6:9], v[118:121]
	v_mfma_f32_16x16x32_bf16 v[74:77], v[162:165], v[228:231], v[2:5]
	s_barrier
; #define PG8_SB(B) __builtin_amdgcn_rcpf(1.f + expneg(B))
; #define PG8_SB(B) __builtin_amdgcn_rcpf(1.f + expneg(B))
; #define PG8_STAGE(bufoff, gbase, voff) do { _Pragma("unroll") for (int _i = 0; _i < 2; ++_i) \
;         __builtin_amdgcn_global_load_lds((const unsigned*)((const char*)(gbase) + (size_t)_i * qstep + (voff)[0]), (PG8_LAS unsigned*)(lds + (bufoff) + ldsw + _i * 8192), 16, 0, 0); } while (0)
; #define PG8_LDA(dst, b, h) do { _Pragma("unroll") for (int m = 0; m < 4; ++m) _Pragma("unroll") for (int k = 0; k < 2; ++k) dst[m][k] = *(const PG8_LAS bf16x8*)(lds + PG8_SA(b, h) + aoff + m * 2048 + k * 1024); } while (0)
; #define PG8_MMA(ai, bj, At, Bt) do { __builtin_amdgcn_s_setprio(1); _Pragma("unroll") for (int m = 0; m < 4; ++m) _Pragma("unroll") for (int n = 0; n < 2; ++n) _Pragma("unroll") for (int k = 0; k < 2; ++k) \
;         acc[ai][bj][m][n] = __builtin_amdgcn_mfma_f32_16x16x32_bf16(Bt[n][k], At[m][k], acc[ai][bj][m][n], 0, 0, 0); __builtin_amdgcn_s_setprio(0); } while (0)
; #define PG8_WAIT_V89() do { if constexpr (SLIVER) PG8_WAIT_V(9); else PG8_WAIT_V(8); } while (0)
; #define PG8_LDS_S(b) do { if constexpr (SLIVER) { Sf[0] = *(const PG8_LAS bf16x8*)(lds + STAGE_BYTES + (b) * 2048 + soff0); Sf[1] = *(const PG8_LAS bf16x8*)(lds + STAGE_BYTES + (b) * 2048 + (soff0 ^ 64)); } } while (0)
; #define PG8_WAIT_L(n) asm volatile("s_waitcnt lgkmcnt(" #n ")" ::: "memory")
; #define PG8_BAR __builtin_amdgcn_s_barrier()
; #define PG8_SCHED __builtin_amdgcn_sched_barrier(0)
; template <class Epi, class Sched, bool ALIGN_EPI = false, bool SP2 = false, bool SLIVER = false>
; __device__ __forceinline__ void gemm_phase(PG8_LAS unsigned char* lds, const Gemm g, const Sched& S, const Epi& E) {
;     ...
;             PG8_LDA(At, 1, 1); PG8_LDS_S(1); PG8_STAGE(PG8_SB(1, 0), b3, voffB); PG8_STAGE(PG8_SB(1, 1), b3 + hstep, voffB); PG8_STAGE(PG8_SA(1, 0), a3, voffA);
;             PG8_WAIT_V89(); PG8_WAIT_L(0); PG8_BAR; PG8_MMA(1, 0, At, B0); PG8_MMA(1, 1, At, B1); PG8_MMA_S(); PG8_BAR; PG8_SCHED;
	s_setprio 0
	s_add_i32 s12, 0, 0x20800
	v_add_u32_e32 v178, s12, v213
	v_add_u32_e32 v184, s12, v214
	s_add_i32 s12, s68, s92
	v_lshl_add_u64 v[208:209], v[202:203], 0, s[26:27]
	s_mov_b32 m0, s12
	ds_read_b128 v[2:5], v215 offset:49152
	ds_read_b128 v[6:9], v215 offset:50176
	ds_read_b128 v[216:219], v215 offset:51200
	ds_read_b128 v[220:223], v215 offset:52224
	ds_read_b128 v[224:227], v215 offset:53248
	ds_read_b128 v[228:231], v215 offset:54272
	ds_read_b128 v[232:235], v215 offset:55296
	ds_read_b128 v[240:243], v215 offset:56320
	ds_read_b128 v[180:183], v178
	ds_read_b128 v[184:187], v184
	global_load_lds_dwordx4 v[208:209], off
	v_lshl_add_u64 v[208:209], v[202:203], 0, s[58:59]
	s_add_i32 m0, s12, 0x2000
	s_mov_b64 s[12:13], 0x90080
	global_load_lds_dwordx4 v[208:209], off
	v_lshl_add_u64 v[208:209], v[202:203], 0, s[12:13]
	s_add_i32 s12, s69, s92
	s_mov_b32 m0, s12
	s_mov_b64 s[68:69], 0xd8080
	global_load_lds_dwordx4 v[208:209], off
	v_lshl_add_u64 v[202:203], v[202:203], 0, s[68:69]
	s_add_i32 m0, s12, 0x2000
	s_nop 0
	global_load_lds_dwordx4 v[202:203], off
	v_lshl_add_u64 v[202:203], v[210:211], 0, s[26:27]
	s_mov_b32 m0, s51
	s_nop 0
	global_load_lds_dwordx4 v[202:203], off
	v_lshl_add_u64 v[202:203], v[210:211], 0, s[58:59]
	s_mov_b32 m0, s53
	s_nop 0
	global_load_lds_dwordx4 v[202:203], off
	s_waitcnt vmcnt(9)
	s_waitcnt lgkmcnt(0)
	s_setprio 1
	s_barrier
	v_mfma_f32_16x16x32_bf16 v[70:73], v[146:149], v[2:5], v[70:73]
	v_mfma_f32_16x16x32_bf16 v[66:69], v[154:157], v[2:5], v[66:69]
	v_mfma_f32_16x16x32_bf16 v[62:65], v[146:149], v[216:219], v[62:65]
	v_mfma_f32_16x16x32_bf16 v[58:61], v[154:157], v[216:219], v[58:61]
	v_mfma_f32_16x16x32_bf16 v[50:53], v[146:149], v[224:227], v[50:53]
	v_mfma_f32_16x16x32_bf16 v[42:45], v[154:157], v[224:227], v[42:45]
	v_mfma_f32_16x16x32_bf16 v[34:37], v[146:149], v[232:235], v[34:37]
	v_mfma_f32_16x16x32_bf16 v[26:29], v[154:157], v[232:235], v[26:29]
	v_mfma_f32_16x16x32_bf16 v[70:73], v[150:153], v[6:9], v[70:73]
	v_mfma_f32_16x16x32_bf16 v[66:69], v[158:161], v[6:9], v[66:69]
	v_mfma_f32_16x16x32_bf16 v[62:65], v[150:153], v[220:223], v[62:65]
	v_mfma_f32_16x16x32_bf16 v[58:61], v[158:161], v[220:223], v[58:61]
	v_mfma_f32_16x16x32_bf16 v[50:53], v[150:153], v[228:231], v[50:53]
	v_mfma_f32_16x16x32_bf16 v[42:45], v[158:161], v[228:231], v[42:45]
	v_mfma_f32_16x16x32_bf16 v[34:37], v[150:153], v[240:243], v[34:37]
	v_mfma_f32_16x16x32_bf16 v[26:29], v[158:161], v[240:243], v[26:29]
	s_setprio 0
	s_setprio 1
	v_mfma_f32_16x16x32_bf16 v[54:57], v[166:169], v[2:5], v[54:57]
	v_mfma_f32_16x16x32_bf16 v[2:5], v[174:177], v[2:5], v[46:49]
	v_mfma_f32_16x16x32_bf16 v[46:49], v[162:165], v[6:9], v[2:5]
	v_mfma_f32_16x16x32_bf16 v[2:5], v[166:169], v[216:219], v[38:41]
	v_mfma_f32_16x16x32_bf16 v[38:41], v[170:173], v[220:223], v[2:5]
	v_mfma_f32_16x16x32_bf16 v[2:5], v[174:177], v[216:219], v[30:33]
	v_mfma_f32_16x16x32_bf16 v[30:33], v[162:165], v[220:223], v[2:5]
	v_mfma_f32_16x16x32_bf16 v[2:5], v[166:169], v[224:227], v[22:25]
	v_mfma_f32_16x16x32_bf16 v[22:25], v[170:173], v[228:231], v[2:5]
	v_mfma_f32_16x16x32_bf16 v[2:5], v[174:177], v[224:227], v[18:21]
	v_mfma_f32_16x16x32_bf16 v[18:21], v[162:165], v[228:231], v[2:5]
	v_mfma_f32_16x16x32_bf16 v[2:5], v[166:169], v[232:235], v[14:17]
	v_mfma_f32_16x16x32_bf16 v[14:17], v[170:173], v[240:243], v[2:5]
	v_mfma_f32_16x16x32_bf16 v[2:5], v[174:177], v[232:235], v[10:13]
	v_mfma_f32_16x16x32_bf16 v[54:57], v[170:173], v[6:9], v[54:57]
	v_mfma_f32_16x16x32_bf16 v[10:13], v[162:165], v[240:243], v[2:5]
	s_setprio 0
	s_setprio 1
	s_and_b64 vcc, exec, s[40:41]
	s_mov_b64 s[12:13], -1
	s_cbranch_vccnz .LBB0_940
	v_mfma_f32_16x16x32_bf16 v[2:5], v[166:169], v[180:183], v[138:141]
	s_mov_b64 s[12:13], 0
	v_mfma_f32_16x16x32_bf16 v[6:9], v[170:173], v[184:187], v[2:5]
	v_mfma_f32_16x16x32_bf16 v[2:5], v[174:177], v[180:183], v[142:145]
	v_mfma_f32_16x16x32_bf16 v[2:5], v[162:165], v[184:187], v[2:5]
